# EpiConv LDS strip re-laid out so ds_read_b64 groups are bank-conflict-free (planes of 64 rows x 16 B)
# speedup vs baseline: 1.0156x; 1.0156x over previous
; #define PG8_LAS __attribute__((address_space(3)))
;     __device__ __forceinline__ void operator()(const f32x4 (&acc)[2][2][4][2], const Unit& u, int wr, int wc, int fr, int fq) const {
;     ...
;         const int ch0 = 128 * u.pn + 32 * wc + 8 * fq;
;         f32x4 w0[2], w1[2], w2[2], bb[2];
; #pragma unroll
;         for (int bj = 0; bj < 2; ++bj) { const int col = bj * 2816 + ch0;
;             w0[bj] = *(const f32x4*)(cw + col); w1[bj] = *(const f32x4*)(cw + 5632 + col); w2[bj] = *(const f32x4*)(cw + 11264 + col); bb[bj] = *(const f32x4*)(cb + col); }
; #pragma unroll
;         for (int ai = 0; ai < 2; ++ai) { const int blk = ai * 2 + wr;
;             if (fr == 0) {
; #pragma unroll
;                 for (int bj = 0; bj < 2; ++bj)
; #pragma unroll
;                     for (int n = 0; n < 2; ++n) *(PG8_LAS f32x4*)(xb + ((((blk * 2 + 0) * 4 + wc) * 4 + fq) * 16 + (bj * 2 + n) * 4)) = acc[ai][bj][0][n]; }
;             if (fr == 15) {
; #pragma unroll
;                 for (int bj = 0; bj < 2; ++bj)
; #pragma unroll
;                     for (int n = 0; n < 2; ++n) *(PG8_LAS f32x4*)(xb + ((((blk * 2 + 1) * 4 + wc) * 4 + fq) * 16 + (bj * 2 + n) * 4)) = acc[ai][bj][3][n]; } }
;         asm volatile("s_waitcnt lgkmcnt(0)" ::: "memory"); __builtin_amdgcn_s_barrier(); asm volatile("" ::: "memory");
;         const f32x4 zero4 = {0.f, 0.f, 0.f, 0.f};
; #pragma unroll
;         for (int n = 0; n < 2; ++n) {
;             if (n == 1) {
; #pragma unroll
;                 for (int bj = 0; bj < 2; ++bj) { const int col = bj * 2816 + ch0 + 4;
;                     w0[bj] = *(const f32x4*)(cw + col); w1[bj] = *(const f32x4*)(cw + 5632 + col); w2[bj] = *(const f32x4*)(cw + 11264 + col); bb[bj] = *(const f32x4*)(cb + col); } }
; #pragma unroll
;             for (int ai = 0; ai < 2; ++ai) { const int blk = ai * 2 + wr;
; #pragma unroll
;                 for (int m = 0; m < 4; ++m) { const int r = 128 * ai + 64 * wr + 16 * m + fr, t = tstart + r;
;                     const bool upok = t >= 1, dnok = (t + 1) < T, store_ok = (r >= vlo) && (r < vhi) && (t < T);
;                     f32x4 res[2];
; #pragma unroll
;                     for (int bj = 0; bj < 2; ++bj) { const f32x4 cur = acc[ai][bj][m][n];
;                         f32x4 su = cur, sd = cur;
;                         if (m > 0) { if (fr == 15) su = acc[ai][bj][m > 0 ? m - 1 : 0][n]; }
.LBB0_705:
	v_lshl_or_b32 v248, s2, 7, v229
	v_lshlrev_b32_e32 v247, 1, v248
	v_lshlrev_b32_e32 v248, 2, v248
	v_add_u32_e32 v249, 0x2c00, v248
	global_load_dwordx4 v[106:109], v248, s[62:63]
	global_load_dwordx4 v[110:113], v248, s[66:67]
	global_load_dwordx4 v[114:117], v248, s[68:69]
	global_load_dwordx4 v[118:121], v248, s[64:65]
	global_load_dwordx4 v[122:125], v249, s[62:63]
	global_load_dwordx4 v[126:129], v249, s[66:67]
	global_load_dwordx4 v[130:133], v249, s[68:69]
	global_load_dwordx4 v[134:137], v249, s[64:65]
	v_readlane_b32 s10, v254, 4
	v_readlane_b32 s11, v254, 5
	s_add_i32 s0, s78, s48
	s_mulk_i32 s0, 0x1600
	s_movk_i32 s29, 0x1600
	s_add_i32 s28, s93, -1
	v_add_u32_e32 v247, s0, v247
	v_mov_b32_e32 v202, 0
	v_mov_b32_e32 v203, 0
	v_and_b32_e32 v250, 7, v226
	v_lshlrev_b32_e32 v250, 3, v250
	v_add_u32_e32 v250, 0x27000, v250
	ds_write_b64 v250, v[202:203]
	s_mov_b64 exec, s[6:7]
	ds_write_b128 v238, v[166:169]
	ds_write_b128 v238, v[70:73] offset:16
	ds_write_b128 v238, v[162:165] offset:32
	ds_write_b128 v238, v[66:69] offset:48
	ds_write_b128 v239, v[102:105]
	ds_write_b128 v239, v[30:33] offset:16
	ds_write_b128 v239, v[98:101] offset:32
	ds_write_b128 v239, v[26:29] offset:48
	s_mov_b64 exec, s[4:5]
	ds_write_b128 v238, v[142:145] offset:1024
	ds_write_b128 v238, v[46:49] offset:1040
	ds_write_b128 v238, v[138:141] offset:1056
	ds_write_b128 v238, v[42:45] offset:1072
	ds_write_b128 v239, v[78:81] offset:1024
	ds_write_b128 v239, v[6:9] offset:1040
	ds_write_b128 v239, v[74:77] offset:1056
	ds_write_b128 v239, v[2:5] offset:1072
	s_mov_b64 exec, -1
	v_and_b32_e32 v250, 0xb80, v238
	v_lshlrev_b32_e32 v250, 3, v250
	v_bfe_u32 v251, v238, 6, 1
	v_lshl_add_u32 v250, v251, 3, v250
	v_lshl_add_u32 v250, v226, 4, v250
	v_add_u32_e32 v243, 0x20000, v250
	v_add_u32_e32 v244, 0xfffffff0, v243
	v_add_u32_e32 v250, 0xfffffc00, v238
	v_mov_b32_e32 v251, 0x27000
	v_cndmask_b32_e64 v245, v251, v250, s[74:75]
	v_add_u32_e32 v250, 0x800, v239
	v_cndmask_b32_e64 v246, v250, v251, s[74:75]
	s_waitcnt lgkmcnt(0)
	s_barrier
	s_cmp_lt_i32 s48, 1
	s_cbranch_scc1 .Lec_edge
	s_add_i32 s0, s48, 0x100
	s_cmp_ge_i32 s0, s93
	s_cbranch_scc1 .Lec_edge
	v_cmp_le_i32_e64 s[12:13], s54, v227
	v_cmp_gt_i32_e32 vcc, s55, v227
	s_and_b64 s[12:13], s[12:13], vcc
	v_cmp_le_i32_e64 s[14:15], s54, v231
	v_cmp_gt_i32_e32 vcc, s55, v231
	s_and_b64 s[14:15], s[14:15], vcc
	v_cmp_le_i32_e64 s[16:17], s54, v232
	v_cmp_gt_i32_e32 vcc, s55, v232
	s_and_b64 s[16:17], s[16:17], vcc
	v_cmp_le_i32_e64 s[18:19], s54, v233
	v_cmp_gt_i32_e32 vcc, s55, v233
	s_and_b64 s[18:19], s[18:19], vcc
	v_cmp_le_i32_e64 s[20:21], s54, v234
	v_cmp_gt_i32_e32 vcc, s55, v234
	s_and_b64 s[20:21], s[20:21], vcc
	v_cmp_le_i32_e64 s[22:23], s54, v235
	v_cmp_gt_i32_e32 vcc, s55, v235
	s_and_b64 s[22:23], s[22:23], vcc
	v_cmp_le_i32_e64 s[24:25], s54, v236
	v_cmp_gt_i32_e32 vcc, s55, v236
	s_and_b64 s[24:25], s[24:25], vcc
	v_cmp_le_i32_e64 s[26:27], s54, v237
	v_cmp_gt_i32_e32 vcc, s55, v237
	s_and_b64 s[26:27], s[26:27], vcc
	ds_write_b64 v243, v[166:167]
	ds_write_b64 v243, v[158:159] offset:256
	ds_write_b64 v243, v[150:151] offset:512
	ds_write_b64 v243, v[142:143] offset:768
	ds_read_b64 v[170:171], v244
	ds_read_b64 v[178:179], v243 offset:16
	ds_read_b64 v[198:199], v245
	ds_read_b64 v[172:173], v244 offset:256
	ds_read_b64 v[180:181], v243 offset:272
	ds_read_b64 v[174:175], v244 offset:512
	ds_read_b64 v[194:195], v243 offset:528
	ds_read_b64 v[176:177], v244 offset:768
	ds_read_b64 v[196:197], v243 offset:784
	ds_read_b64 v[200:201], v238 offset:2048
	s_waitcnt vmcnt(0)
	ds_write_b64 v243, v[168:169]
	ds_write_b64 v243, v[160:161] offset:256
	ds_write_b64 v243, v[152:153] offset:512
	ds_write_b64 v243, v[144:145] offset:768
	s_waitcnt lgkmcnt(11)
	v_cndmask_b32_e64 v170, v170, v198, s[6:7]
	v_cndmask_b32_e64 v171, v171, v199, s[6:7]
	v_pk_fma_f32 v[202:203], v[106:107], v[170:171], v[118:119]
	v_pk_fma_f32 v[166:167], v[166:167], v[110:111], v[202:203]
	v_pk_fma_f32 v[166:167], v[114:115], v[178:179], v[166:167]
	ds_read_b64 v[170:171], v244
	ds_read_b64 v[178:179], v243 offset:16
	ds_read_b64 v[198:199], v245 offset:8
	s_waitcnt lgkmcnt(12)
	v_pk_fma_f32 v[202:203], v[106:107], v[172:173], v[118:119]
	v_pk_fma_f32 v[158:159], v[158:159], v[110:111], v[202:203]
	v_pk_fma_f32 v[158:159], v[114:115], v[180:181], v[158:159]
	ds_read_b64 v[172:173], v244 offset:256
	ds_read_b64 v[180:181], v243 offset:272
	s_waitcnt lgkmcnt(12)
	v_pk_fma_f32 v[202:203], v[106:107], v[174:175], v[118:119]
	v_pk_fma_f32 v[150:151], v[150:151], v[110:111], v[202:203]
	v_pk_fma_f32 v[150:151], v[114:115], v[194:195], v[150:151]
	ds_read_b64 v[174:175], v244 offset:512
	ds_read_b64 v[194:195], v243 offset:528
	s_waitcnt lgkmcnt(11)
	v_cndmask_b32_e64 v196, v196, v200, s[4:5]
	v_cndmask_b32_e64 v197, v197, v201, s[4:5]
	v_pk_fma_f32 v[202:203], v[106:107], v[176:177], v[118:119]
	v_pk_fma_f32 v[142:143], v[142:143], v[110:111], v[202:203]
	v_pk_fma_f32 v[142:143], v[114:115], v[196:197], v[142:143]
	ds_read_b64 v[176:177], v244 offset:768
	ds_read_b64 v[196:197], v243 offset:784
	ds_read_b64 v[200:201], v238 offset:2056
	ds_write_b64 v243, v[162:163]
	ds_write_b64 v243, v[154:155] offset:256
	ds_write_b64 v243, v[146:147] offset:512
	ds_write_b64 v243, v[138:139] offset:768
	s_waitcnt lgkmcnt(11)
	v_cndmask_b32_e64 v170, v170, v198, s[6:7]
	v_cndmask_b32_e64 v171, v171, v199, s[6:7]
	v_pk_fma_f32 v[202:203], v[108:109], v[170:171], v[120:121]
	v_pk_fma_f32 v[168:169], v[168:169], v[112:113], v[202:203]
	v_pk_fma_f32 v[168:169], v[116:117], v[178:179], v[168:169]
	ds_read_b64 v[170:171], v244
	ds_read_b64 v[178:179], v243 offset:16
	ds_read_b64 v[198:199], v245 offset:32
	s_waitcnt lgkmcnt(12)
; #define PG8_LAS __attribute__((address_space(3)))
; __device__ __forceinline__ unsigned cvt_pk_bf16(float lo, float hi) { unsigned r; asm volatile("v_cvt_pk_bf16_f32 %0, %1, %2" : "=v"(r) : "v"(lo), "v"(hi)); return r; }
; __device__ __forceinline__ float dpp_ror1(float v) { return __builtin_bit_cast(float, __builtin_amdgcn_update_dpp(0, __builtin_bit_cast(int, v), 0x121, 0xf, 0xf, false)); }
; __device__ __forceinline__ float dpp_ror15(float v) { return __builtin_bit_cast(float, __builtin_amdgcn_update_dpp(0, __builtin_bit_cast(int, v), 0x12F, 0xf, 0xf, false)); }
;     __device__ __forceinline__ void operator()(const f32x4 (&acc)[2][2][4][2], const Unit& u, int wr, int wc, int fr, int fq) const {
;     ...
;                     for (int bj = 0; bj < 2; ++bj) { const f32x4 cur = acc[ai][bj][m][n];
;                         f32x4 su = cur, sd = cur;
;                         if (m > 0) { if (fr == 15) su = acc[ai][bj][m > 0 ? m - 1 : 0][n]; }
;                         if (m < 3) { if (fr == 0) sd = acc[ai][bj][m < 3 ? m + 1 : 3][n]; }
;                         f32x4 up, dn;
;                         up[0] = dpp_ror1(su[0]); up[1] = dpp_ror1(su[1]); up[2] = dpp_ror1(su[2]); up[3] = dpp_ror1(su[3]);
;                         dn[0] = dpp_ror15(sd[0]); dn[1] = dpp_ror15(sd[1]); dn[2] = dpp_ror15(sd[2]); dn[3] = dpp_ror15(sd[3]);
;                         if (m == 0) { f32x4 halo = zero4; if (blk > 0) halo = *(const PG8_LAS f32x4*)(xb + (((((blk - 1) * 2 + 1) * 4 + wc) * 4 + fq) * 16 + (bj * 2 + n) * 4)); if (fr == 0) up = halo; }
;                         if (m == 3) { f32x4 halo = zero4; if (blk < 3) halo = *(const PG8_LAS f32x4*)(xb + (((((blk + 1) * 2 + 0) * 4 + wc) * 4 + fq) * 16 + (bj * 2 + n) * 4)); if (fr == 15) dn = halo; }
;                         if (edge) { if (!upok) up = zero4; if (!dnok) dn = zero4; }
;                         res[bj] = bb[bj] + w0[bj] * up + w1[bj] * cur + w2[bj] * dn; }
;                     if (store_ok) {
;                         float o[4];
; #pragma unroll
;                         for (int j = 0; j < 4; ++j) { const float gg = res[1][j]; o[j] = gg * __builtin_amdgcn_rcpf(1.f + __expf(-gg)) * res[0][j]; }
;                         u32x2 w; w.x = cvt_pk_bf16(o[0], o[1]); w.y = cvt_pk_bf16(o[2], o[3]);
;                         *(u32x2*)(ACT + (size_t)(seqrow + t) * 2816 + ch0 + 4 * n) = w; } } }
	v_pk_fma_f32 v[202:203], v[108:109], v[172:173], v[120:121]
	v_pk_fma_f32 v[160:161], v[160:161], v[112:113], v[202:203]
	v_pk_fma_f32 v[160:161], v[116:117], v[180:181], v[160:161]
	ds_read_b64 v[172:173], v244 offset:256
	ds_read_b64 v[180:181], v243 offset:272
	s_waitcnt lgkmcnt(12)
	v_pk_fma_f32 v[202:203], v[108:109], v[174:175], v[120:121]
	v_pk_fma_f32 v[152:153], v[152:153], v[112:113], v[202:203]
	v_pk_fma_f32 v[152:153], v[116:117], v[194:195], v[152:153]
	ds_read_b64 v[174:175], v244 offset:512
	ds_read_b64 v[194:195], v243 offset:528
	s_waitcnt lgkmcnt(11)
	v_cndmask_b32_e64 v196, v196, v200, s[4:5]
	v_cndmask_b32_e64 v197, v197, v201, s[4:5]
	v_pk_fma_f32 v[202:203], v[108:109], v[176:177], v[120:121]
	v_pk_fma_f32 v[144:145], v[144:145], v[112:113], v[202:203]
	v_pk_fma_f32 v[144:145], v[116:117], v[196:197], v[144:145]
	ds_read_b64 v[176:177], v244 offset:768
	ds_read_b64 v[196:197], v243 offset:784
	ds_read_b64 v[200:201], v238 offset:2080
	ds_write_b64 v243, v[164:165]
	ds_write_b64 v243, v[156:157] offset:256
	ds_write_b64 v243, v[148:149] offset:512
	ds_write_b64 v243, v[140:141] offset:768
	s_waitcnt lgkmcnt(11)
	v_cndmask_b32_e64 v170, v170, v198, s[6:7]
	v_cndmask_b32_e64 v171, v171, v199, s[6:7]
	v_pk_fma_f32 v[202:203], v[122:123], v[170:171], v[134:135]
	v_pk_fma_f32 v[162:163], v[162:163], v[126:127], v[202:203]
	v_pk_fma_f32 v[162:163], v[130:131], v[178:179], v[162:163]
	ds_read_b64 v[170:171], v244
	ds_read_b64 v[178:179], v243 offset:16
	ds_read_b64 v[198:199], v245 offset:40
	s_waitcnt lgkmcnt(12)
	v_pk_fma_f32 v[202:203], v[122:123], v[172:173], v[134:135]
	v_pk_fma_f32 v[154:155], v[154:155], v[126:127], v[202:203]
	v_pk_fma_f32 v[154:155], v[130:131], v[180:181], v[154:155]
	ds_read_b64 v[172:173], v244 offset:256
	ds_read_b64 v[180:181], v243 offset:272
	s_waitcnt lgkmcnt(12)
	v_pk_fma_f32 v[202:203], v[122:123], v[174:175], v[134:135]
	v_pk_fma_f32 v[146:147], v[146:147], v[126:127], v[202:203]
	v_pk_fma_f32 v[146:147], v[130:131], v[194:195], v[146:147]
	ds_read_b64 v[174:175], v244 offset:512
	ds_read_b64 v[194:195], v243 offset:528
	s_waitcnt lgkmcnt(11)
	v_cndmask_b32_e64 v196, v196, v200, s[4:5]
	v_cndmask_b32_e64 v197, v197, v201, s[4:5]
	v_pk_fma_f32 v[202:203], v[122:123], v[176:177], v[134:135]
	v_pk_fma_f32 v[138:139], v[138:139], v[126:127], v[202:203]
	v_pk_fma_f32 v[138:139], v[130:131], v[196:197], v[138:139]
	ds_read_b64 v[176:177], v244 offset:768
	ds_read_b64 v[196:197], v243 offset:784
	ds_read_b64 v[200:201], v238 offset:2088
	ds_write_b64 v243, v[102:103]
	ds_write_b64 v243, v[94:95] offset:256
	ds_write_b64 v243, v[86:87] offset:512
	ds_write_b64 v243, v[78:79] offset:768
	s_waitcnt lgkmcnt(11)
	v_cndmask_b32_e64 v170, v170, v198, s[6:7]
	v_cndmask_b32_e64 v171, v171, v199, s[6:7]
	v_pk_fma_f32 v[202:203], v[124:125], v[170:171], v[136:137]
	v_pk_fma_f32 v[164:165], v[164:165], v[128:129], v[202:203]
	v_pk_fma_f32 v[164:165], v[132:133], v[178:179], v[164:165]
	ds_read_b64 v[170:171], v244
	ds_read_b64 v[178:179], v243 offset:16
	ds_read_b64 v[198:199], v238 offset:3072
	s_waitcnt lgkmcnt(12)
	v_pk_fma_f32 v[202:203], v[124:125], v[172:173], v[136:137]
	v_pk_fma_f32 v[156:157], v[156:157], v[128:129], v[202:203]
	v_pk_fma_f32 v[156:157], v[132:133], v[180:181], v[156:157]
	ds_read_b64 v[172:173], v244 offset:256
	ds_read_b64 v[180:181], v243 offset:272
	s_waitcnt lgkmcnt(12)
	v_pk_fma_f32 v[202:203], v[124:125], v[174:175], v[136:137]
	v_pk_fma_f32 v[148:149], v[148:149], v[128:129], v[202:203]
	v_pk_fma_f32 v[148:149], v[132:133], v[194:195], v[148:149]
	ds_read_b64 v[174:175], v244 offset:512
	ds_read_b64 v[194:195], v243 offset:528
	s_waitcnt lgkmcnt(11)
	v_cndmask_b32_e64 v196, v196, v200, s[4:5]
	v_cndmask_b32_e64 v197, v197, v201, s[4:5]
	v_pk_fma_f32 v[202:203], v[124:125], v[176:177], v[136:137]
	v_pk_fma_f32 v[140:141], v[140:141], v[128:129], v[202:203]
	v_pk_fma_f32 v[140:141], v[132:133], v[196:197], v[140:141]
	ds_read_b64 v[176:177], v244 offset:768
	ds_read_b64 v[196:197], v243 offset:784
	ds_read_b64 v[200:201], v246
	v_mul_f32_e32 v208, 0xbfb8aa3b, v162
	v_mul_f32_e32 v209, 0xbfb8aa3b, v163
	v_mul_f32_e32 v210, 0xbfb8aa3b, v164
	v_mul_f32_e32 v211, 0xbfb8aa3b, v165
	v_exp_f32_e32 v208, v208
	v_exp_f32_e32 v209, v209
	v_exp_f32_e32 v210, v210
	v_exp_f32_e32 v211, v211
	v_add_f32_e32 v208, 1.0, v208
	v_add_f32_e32 v209, 1.0, v209
	v_add_f32_e32 v210, 1.0, v210
	v_add_f32_e32 v211, 1.0, v211
	v_rcp_f32_e32 v208, v208
	v_rcp_f32_e32 v209, v209
	v_rcp_f32_e32 v210, v210
	v_rcp_f32_e32 v211, v211
	v_mul_f32_e32 v162, v162, v208
	v_mul_f32_e32 v163, v163, v209
	v_mul_f32_e32 v164, v164, v210
	v_mul_f32_e32 v165, v165, v211
	v_mul_f32_e32 v162, v166, v162
	v_mul_f32_e32 v163, v167, v163
	v_mul_f32_e32 v164, v168, v164
	v_mul_f32_e32 v165, v169, v165
	v_cvt_pk_bf16_f32 v212, v162, v163
	v_cvt_pk_bf16_f32 v213, v164, v165
	v_mad_u32_u24 v221, v227, s29, v247
	s_and_saveexec_b64 s[30:31], s[12:13]
	global_store_dwordx2 v221, v[212:213], s[10:11]
	s_mov_b64 exec, s[30:31]
	v_mul_f32_e32 v208, 0xbfb8aa3b, v154
	v_mul_f32_e32 v209, 0xbfb8aa3b, v155
	v_mul_f32_e32 v210, 0xbfb8aa3b, v156
	v_mul_f32_e32 v211, 0xbfb8aa3b, v157
	v_exp_f32_e32 v208, v208
	v_exp_f32_e32 v209, v209
	v_exp_f32_e32 v210, v210
	v_exp_f32_e32 v211, v211
	v_add_f32_e32 v208, 1.0, v208
	v_add_f32_e32 v209, 1.0, v209
	v_add_f32_e32 v210, 1.0, v210
	v_add_f32_e32 v211, 1.0, v211
	v_rcp_f32_e32 v208, v208
	v_rcp_f32_e32 v209, v209
	v_rcp_f32_e32 v210, v210
	v_rcp_f32_e32 v211, v211
	v_mul_f32_e32 v154, v154, v208
	v_mul_f32_e32 v155, v155, v209
	v_mul_f32_e32 v156, v156, v210
	v_mul_f32_e32 v157, v157, v211
; #define PG8_LAS __attribute__((address_space(3)))
;     __device__ __forceinline__ void operator()(const f32x4 (&acc)[2][2][4][2], const Unit& u, int wr, int wc, int fr, int fq) const {
;     ...
;         for (int n = 0; n < 2; ++n) {
;             if (n == 1) {
; #pragma unroll
;                 for (int bj = 0; bj < 2; ++bj) { const int col = bj * 2816 + ch0 + 4;
;                     w0[bj] = *(const f32x4*)(cw + col); w1[bj] = *(const f32x4*)(cw + 5632 + col); w2[bj] = *(const f32x4*)(cw + 11264 + col); bb[bj] = *(const f32x4*)(cb + col); } }
; #pragma unroll
;             for (int ai = 0; ai < 2; ++ai) { const int blk = ai * 2 + wr;
; #pragma unroll
;                 for (int m = 0; m < 4; ++m) { const int r = 128 * ai + 64 * wr + 16 * m + fr, t = tstart + r;
;                     const bool upok = t >= 1, dnok = (t + 1) < T, store_ok = (r >= vlo) && (r < vhi) && (t < T);
;                     f32x4 res[2];
; #pragma unroll
;                     for (int bj = 0; bj < 2; ++bj) { const f32x4 cur = acc[ai][bj][m][n];
;                         f32x4 su = cur, sd = cur;
;                         if (m > 0) { if (fr == 15) su = acc[ai][bj][m > 0 ? m - 1 : 0][n]; }
;                         if (m < 3) { if (fr == 0) sd = acc[ai][bj][m < 3 ? m + 1 : 3][n]; }
;                         f32x4 up, dn;
;                         up[0] = dpp_ror1(su[0]); up[1] = dpp_ror1(su[1]); up[2] = dpp_ror1(su[2]); up[3] = dpp_ror1(su[3]);
;                         dn[0] = dpp_ror15(sd[0]); dn[1] = dpp_ror15(sd[1]); dn[2] = dpp_ror15(sd[2]); dn[3] = dpp_ror15(sd[3]);
;                         if (m == 0) { f32x4 halo = zero4; if (blk > 0) halo = *(const PG8_LAS f32x4*)(xb + (((((blk - 1) * 2 + 1) * 4 + wc) * 4 + fq) * 16 + (bj * 2 + n) * 4)); if (fr == 0) up = halo; }
;                         if (m == 3) { f32x4 halo = zero4; if (blk < 3) halo = *(const PG8_LAS f32x4*)(xb + (((((blk + 1) * 2 + 0) * 4 + wc) * 4 + fq) * 16 + (bj * 2 + n) * 4)); if (fr == 15) dn = halo; }
;                         if (edge) { if (!upok) up = zero4; if (!dnok) dn = zero4; }
;                         res[bj] = bb[bj] + w0[bj] * up + w1[bj] * cur + w2[bj] * dn; }
;                     if (store_ok) {
;                         float o[4];
; #pragma unroll
;                         for (int j = 0; j < 4; ++j) { const float gg = res[1][j]; o[j] = gg * __builtin_amdgcn_rcpf(1.f + __expf(-gg)) * res[0][j]; }
	v_mul_f32_e32 v154, v158, v154
	v_mul_f32_e32 v155, v159, v155
	v_mul_f32_e32 v156, v160, v156
	v_mul_f32_e32 v157, v161, v157
	v_cvt_pk_bf16_f32 v218, v154, v155
	v_cvt_pk_bf16_f32 v219, v156, v157
	v_mad_u32_u24 v40, v231, s29, v247
	s_and_saveexec_b64 s[30:31], s[14:15]
	global_store_dwordx2 v40, v[218:219], s[10:11]
	s_mov_b64 exec, s[30:31]
	v_mul_f32_e32 v208, 0xbfb8aa3b, v146
	v_mul_f32_e32 v209, 0xbfb8aa3b, v147
	v_mul_f32_e32 v210, 0xbfb8aa3b, v148
	v_mul_f32_e32 v211, 0xbfb8aa3b, v149
	v_exp_f32_e32 v208, v208
	v_exp_f32_e32 v209, v209
	v_exp_f32_e32 v210, v210
	v_exp_f32_e32 v211, v211
	v_add_f32_e32 v208, 1.0, v208
	v_add_f32_e32 v209, 1.0, v209
	v_add_f32_e32 v210, 1.0, v210
	v_add_f32_e32 v211, 1.0, v211
	v_rcp_f32_e32 v208, v208
	v_rcp_f32_e32 v209, v209
	v_rcp_f32_e32 v210, v210
	v_rcp_f32_e32 v211, v211
	v_mul_f32_e32 v146, v146, v208
	v_mul_f32_e32 v147, v147, v209
	v_mul_f32_e32 v148, v148, v210
	v_mul_f32_e32 v149, v149, v211
	v_mul_f32_e32 v146, v150, v146
	v_mul_f32_e32 v147, v151, v147
	v_mul_f32_e32 v148, v152, v148
	v_mul_f32_e32 v149, v153, v149
	v_cvt_pk_bf16_f32 v212, v146, v147
	v_cvt_pk_bf16_f32 v213, v148, v149
	v_mad_u32_u24 v221, v232, s29, v247
	s_and_saveexec_b64 s[30:31], s[16:17]
	global_store_dwordx2 v221, v[212:213], s[10:11]
	s_mov_b64 exec, s[30:31]
	v_mul_f32_e32 v208, 0xbfb8aa3b, v138
	v_mul_f32_e32 v209, 0xbfb8aa3b, v139
	v_mul_f32_e32 v210, 0xbfb8aa3b, v140
	v_mul_f32_e32 v211, 0xbfb8aa3b, v141
	v_exp_f32_e32 v208, v208
	v_exp_f32_e32 v209, v209
	v_exp_f32_e32 v210, v210
	v_exp_f32_e32 v211, v211
	v_add_f32_e32 v208, 1.0, v208
	v_add_f32_e32 v209, 1.0, v209
	v_add_f32_e32 v210, 1.0, v210
	v_add_f32_e32 v211, 1.0, v211
	v_rcp_f32_e32 v208, v208
	v_rcp_f32_e32 v209, v209
	v_rcp_f32_e32 v210, v210
	v_rcp_f32_e32 v211, v211
	v_mul_f32_e32 v138, v138, v208
	v_mul_f32_e32 v139, v139, v209
	v_mul_f32_e32 v140, v140, v210
	v_mul_f32_e32 v141, v141, v211
	v_mul_f32_e32 v138, v142, v138
	v_mul_f32_e32 v139, v143, v139
	v_mul_f32_e32 v140, v144, v140
	v_mul_f32_e32 v141, v145, v141
	v_cvt_pk_bf16_f32 v218, v138, v139
	v_cvt_pk_bf16_f32 v219, v140, v141
	v_mad_u32_u24 v40, v233, s29, v247
	s_and_saveexec_b64 s[30:31], s[18:19]
	global_store_dwordx2 v40, v[218:219], s[10:11]
	s_mov_b64 exec, s[30:31]
	global_load_dwordx4 v[138:141], v248, s[62:63] offset:16
	global_load_dwordx4 v[142:145], v248, s[66:67] offset:16
	global_load_dwordx4 v[146:149], v248, s[68:69] offset:16
	global_load_dwordx4 v[150:153], v248, s[64:65] offset:16
	global_load_dwordx4 v[154:157], v249, s[62:63] offset:16
	global_load_dwordx4 v[158:161], v249, s[66:67] offset:16
	global_load_dwordx4 v[162:165], v249, s[68:69] offset:16
	global_load_dwordx4 v[166:169], v249, s[64:65] offset:16
	ds_write_b64 v243, v[104:105]
	ds_write_b64 v243, v[96:97] offset:256
	ds_write_b64 v243, v[88:89] offset:512
	ds_write_b64 v243, v[80:81] offset:768
	s_waitcnt lgkmcnt(11)
	v_cndmask_b32_e64 v170, v170, v198, s[6:7]
	v_cndmask_b32_e64 v171, v171, v199, s[6:7]
	v_pk_fma_f32 v[202:203], v[106:107], v[170:171], v[118:119]
	v_pk_fma_f32 v[102:103], v[102:103], v[110:111], v[202:203]
	v_pk_fma_f32 v[102:103], v[114:115], v[178:179], v[102:103]
	ds_read_b64 v[170:171], v244
	ds_read_b64 v[178:179], v243 offset:16
	ds_read_b64 v[198:199], v238 offset:3080
	s_waitcnt lgkmcnt(12)
	v_pk_fma_f32 v[202:203], v[106:107], v[172:173], v[118:119]
	v_pk_fma_f32 v[94:95], v[94:95], v[110:111], v[202:203]
	v_pk_fma_f32 v[94:95], v[114:115], v[180:181], v[94:95]
	ds_read_b64 v[172:173], v244 offset:256
	ds_read_b64 v[180:181], v243 offset:272
	s_waitcnt lgkmcnt(12)
	v_pk_fma_f32 v[202:203], v[106:107], v[174:175], v[118:119]
	v_pk_fma_f32 v[86:87], v[86:87], v[110:111], v[202:203]
	v_pk_fma_f32 v[86:87], v[114:115], v[194:195], v[86:87]
	ds_read_b64 v[174:175], v244 offset:512
	ds_read_b64 v[194:195], v243 offset:528
	s_waitcnt lgkmcnt(11)
	v_cndmask_b32_e64 v196, v196, v200, s[4:5]
	v_cndmask_b32_e64 v197, v197, v201, s[4:5]
	v_pk_fma_f32 v[202:203], v[106:107], v[176:177], v[118:119]
	v_pk_fma_f32 v[78:79], v[78:79], v[110:111], v[202:203]
	v_pk_fma_f32 v[78:79], v[114:115], v[196:197], v[78:79]
	ds_read_b64 v[176:177], v244 offset:768
	ds_read_b64 v[196:197], v243 offset:784
	ds_read_b64 v[200:201], v246 offset:8
	ds_write_b64 v243, v[98:99]
	ds_write_b64 v243, v[90:91] offset:256
	ds_write_b64 v243, v[82:83] offset:512
	ds_write_b64 v243, v[74:75] offset:768
	s_waitcnt lgkmcnt(11)
	v_cndmask_b32_e64 v170, v170, v198, s[6:7]
	v_cndmask_b32_e64 v171, v171, v199, s[6:7]
	v_pk_fma_f32 v[202:203], v[108:109], v[170:171], v[120:121]
	v_pk_fma_f32 v[104:105], v[104:105], v[112:113], v[202:203]
	v_pk_fma_f32 v[104:105], v[116:117], v[178:179], v[104:105]
	ds_read_b64 v[170:171], v244
	ds_read_b64 v[178:179], v243 offset:16
	ds_read_b64 v[198:199], v238 offset:3104
	s_waitcnt lgkmcnt(12)
	v_pk_fma_f32 v[202:203], v[108:109], v[172:173], v[120:121]
	v_pk_fma_f32 v[96:97], v[96:97], v[112:113], v[202:203]
	v_pk_fma_f32 v[96:97], v[116:117], v[180:181], v[96:97]
	ds_read_b64 v[172:173], v244 offset:256
	ds_read_b64 v[180:181], v243 offset:272
	s_waitcnt lgkmcnt(12)
	v_pk_fma_f32 v[202:203], v[108:109], v[174:175], v[120:121]
	v_pk_fma_f32 v[88:89], v[88:89], v[112:113], v[202:203]
	v_pk_fma_f32 v[88:89], v[116:117], v[194:195], v[88:89]
	ds_read_b64 v[174:175], v244 offset:512
	ds_read_b64 v[194:195], v243 offset:528
	s_waitcnt lgkmcnt(11)
; #define PG8_LAS __attribute__((address_space(3)))
; __device__ __forceinline__ unsigned cvt_pk_bf16(float lo, float hi) { unsigned r; asm volatile("v_cvt_pk_bf16_f32 %0, %1, %2" : "=v"(r) : "v"(lo), "v"(hi)); return r; }
;     __device__ __forceinline__ void operator()(const f32x4 (&acc)[2][2][4][2], const Unit& u, int wr, int wc, int fr, int fq) const {
;     ...
;                 for (int m = 0; m < 4; ++m) { const int r = 128 * ai + 64 * wr + 16 * m + fr, t = tstart + r;
;                     const bool upok = t >= 1, dnok = (t + 1) < T, store_ok = (r >= vlo) && (r < vhi) && (t < T);
;                     f32x4 res[2];
; #pragma unroll
;                     for (int bj = 0; bj < 2; ++bj) { const f32x4 cur = acc[ai][bj][m][n];
;                         f32x4 su = cur, sd = cur;
;                         if (m > 0) { if (fr == 15) su = acc[ai][bj][m > 0 ? m - 1 : 0][n]; }
;                         if (m < 3) { if (fr == 0) sd = acc[ai][bj][m < 3 ? m + 1 : 3][n]; }
;                         f32x4 up, dn;
;                         up[0] = dpp_ror1(su[0]); up[1] = dpp_ror1(su[1]); up[2] = dpp_ror1(su[2]); up[3] = dpp_ror1(su[3]);
;                         dn[0] = dpp_ror15(sd[0]); dn[1] = dpp_ror15(sd[1]); dn[2] = dpp_ror15(sd[2]); dn[3] = dpp_ror15(sd[3]);
;                         if (m == 0) { f32x4 halo = zero4; if (blk > 0) halo = *(const PG8_LAS f32x4*)(xb + (((((blk - 1) * 2 + 1) * 4 + wc) * 4 + fq) * 16 + (bj * 2 + n) * 4)); if (fr == 0) up = halo; }
;                         if (m == 3) { f32x4 halo = zero4; if (blk < 3) halo = *(const PG8_LAS f32x4*)(xb + (((((blk + 1) * 2 + 0) * 4 + wc) * 4 + fq) * 16 + (bj * 2 + n) * 4)); if (fr == 15) dn = halo; }
;                         if (edge) { if (!upok) up = zero4; if (!dnok) dn = zero4; }
;                         res[bj] = bb[bj] + w0[bj] * up + w1[bj] * cur + w2[bj] * dn; }
;                     if (store_ok) {
;                         float o[4];
; #pragma unroll
;                         for (int j = 0; j < 4; ++j) { const float gg = res[1][j]; o[j] = gg * __builtin_amdgcn_rcpf(1.f + __expf(-gg)) * res[0][j]; }
;                         u32x2 w; w.x = cvt_pk_bf16(o[0], o[1]); w.y = cvt_pk_bf16(o[2], o[3]);
;                         *(u32x2*)(ACT + (size_t)(seqrow + t) * 2816 + ch0 + 4 * n) = w; } } }
	v_cndmask_b32_e64 v196, v196, v200, s[4:5]
	v_cndmask_b32_e64 v197, v197, v201, s[4:5]
	v_pk_fma_f32 v[202:203], v[108:109], v[176:177], v[120:121]
	v_pk_fma_f32 v[80:81], v[80:81], v[112:113], v[202:203]
	v_pk_fma_f32 v[80:81], v[116:117], v[196:197], v[80:81]
	ds_read_b64 v[176:177], v244 offset:768
	ds_read_b64 v[196:197], v243 offset:784
	ds_read_b64 v[200:201], v246 offset:32
	ds_write_b64 v243, v[100:101]
	ds_write_b64 v243, v[92:93] offset:256
	ds_write_b64 v243, v[84:85] offset:512
	ds_write_b64 v243, v[76:77] offset:768
	s_waitcnt lgkmcnt(11)
	v_cndmask_b32_e64 v170, v170, v198, s[6:7]
	v_cndmask_b32_e64 v171, v171, v199, s[6:7]
	v_pk_fma_f32 v[202:203], v[122:123], v[170:171], v[134:135]
	v_pk_fma_f32 v[98:99], v[98:99], v[126:127], v[202:203]
	v_pk_fma_f32 v[98:99], v[130:131], v[178:179], v[98:99]
	ds_read_b64 v[170:171], v244
	ds_read_b64 v[178:179], v243 offset:16
	ds_read_b64 v[198:199], v238 offset:3112
	s_waitcnt lgkmcnt(12)
	v_pk_fma_f32 v[202:203], v[122:123], v[172:173], v[134:135]
	v_pk_fma_f32 v[90:91], v[90:91], v[126:127], v[202:203]
	v_pk_fma_f32 v[90:91], v[130:131], v[180:181], v[90:91]
	ds_read_b64 v[172:173], v244 offset:256
	ds_read_b64 v[180:181], v243 offset:272
	s_waitcnt lgkmcnt(12)
	v_pk_fma_f32 v[202:203], v[122:123], v[174:175], v[134:135]
	v_pk_fma_f32 v[82:83], v[82:83], v[126:127], v[202:203]
	v_pk_fma_f32 v[82:83], v[130:131], v[194:195], v[82:83]
	ds_read_b64 v[174:175], v244 offset:512
	ds_read_b64 v[194:195], v243 offset:528
	s_waitcnt lgkmcnt(11)
	v_cndmask_b32_e64 v196, v196, v200, s[4:5]
	v_cndmask_b32_e64 v197, v197, v201, s[4:5]
	v_pk_fma_f32 v[202:203], v[122:123], v[176:177], v[134:135]
	v_pk_fma_f32 v[74:75], v[74:75], v[126:127], v[202:203]
	v_pk_fma_f32 v[74:75], v[130:131], v[196:197], v[74:75]
	ds_read_b64 v[176:177], v244 offset:768
	ds_read_b64 v[196:197], v243 offset:784
	ds_read_b64 v[200:201], v246 offset:40
	ds_write_b64 v243, v[70:71]
	ds_write_b64 v243, v[62:63] offset:256
	ds_write_b64 v243, v[54:55] offset:512
	ds_write_b64 v243, v[46:47] offset:768
	s_waitcnt lgkmcnt(11)
	v_cndmask_b32_e64 v170, v170, v198, s[6:7]
	v_cndmask_b32_e64 v171, v171, v199, s[6:7]
	v_pk_fma_f32 v[202:203], v[124:125], v[170:171], v[136:137]
	v_pk_fma_f32 v[100:101], v[100:101], v[128:129], v[202:203]
	v_pk_fma_f32 v[100:101], v[132:133], v[178:179], v[100:101]
	ds_read_b64 v[170:171], v244
	ds_read_b64 v[178:179], v243 offset:16
	ds_read_b64 v[198:199], v245 offset:16
	s_waitcnt lgkmcnt(12)
	v_pk_fma_f32 v[202:203], v[124:125], v[172:173], v[136:137]
	v_pk_fma_f32 v[92:93], v[92:93], v[128:129], v[202:203]
	v_pk_fma_f32 v[92:93], v[132:133], v[180:181], v[92:93]
	ds_read_b64 v[172:173], v244 offset:256
	ds_read_b64 v[180:181], v243 offset:272
	s_waitcnt lgkmcnt(12)
	v_pk_fma_f32 v[202:203], v[124:125], v[174:175], v[136:137]
	v_pk_fma_f32 v[84:85], v[84:85], v[128:129], v[202:203]
	v_pk_fma_f32 v[84:85], v[132:133], v[194:195], v[84:85]
	ds_read_b64 v[174:175], v244 offset:512
	ds_read_b64 v[194:195], v243 offset:528
	s_waitcnt lgkmcnt(11)
	v_cndmask_b32_e64 v196, v196, v200, s[4:5]
	v_cndmask_b32_e64 v197, v197, v201, s[4:5]
	v_pk_fma_f32 v[202:203], v[124:125], v[176:177], v[136:137]
	v_pk_fma_f32 v[76:77], v[76:77], v[128:129], v[202:203]
	v_pk_fma_f32 v[76:77], v[132:133], v[196:197], v[76:77]
	ds_read_b64 v[176:177], v244 offset:768
	ds_read_b64 v[196:197], v243 offset:784
	ds_read_b64 v[200:201], v238 offset:2064
	v_mul_f32_e32 v208, 0xbfb8aa3b, v98
	v_mul_f32_e32 v209, 0xbfb8aa3b, v99
	v_mul_f32_e32 v210, 0xbfb8aa3b, v100
	v_mul_f32_e32 v211, 0xbfb8aa3b, v101
	v_exp_f32_e32 v208, v208
	v_exp_f32_e32 v209, v209
	v_exp_f32_e32 v210, v210
	v_exp_f32_e32 v211, v211
	v_add_f32_e32 v208, 1.0, v208
	v_add_f32_e32 v209, 1.0, v209
	v_add_f32_e32 v210, 1.0, v210
	v_add_f32_e32 v211, 1.0, v211
	v_rcp_f32_e32 v208, v208
	v_rcp_f32_e32 v209, v209
	v_rcp_f32_e32 v210, v210
	v_rcp_f32_e32 v211, v211
	v_mul_f32_e32 v98, v98, v208
	v_mul_f32_e32 v99, v99, v209
	v_mul_f32_e32 v100, v100, v210
	v_mul_f32_e32 v101, v101, v211
	v_mul_f32_e32 v98, v102, v98
	v_mul_f32_e32 v99, v103, v99
	v_mul_f32_e32 v100, v104, v100
	v_mul_f32_e32 v101, v105, v101
	v_cvt_pk_bf16_f32 v212, v98, v99
	v_cvt_pk_bf16_f32 v213, v100, v101
	v_mad_u32_u24 v221, v234, s29, v247
	s_and_saveexec_b64 s[30:31], s[20:21]
	global_store_dwordx2 v221, v[212:213], s[10:11]
	s_mov_b64 exec, s[30:31]
	v_mul_f32_e32 v208, 0xbfb8aa3b, v90
	v_mul_f32_e32 v209, 0xbfb8aa3b, v91
	v_mul_f32_e32 v210, 0xbfb8aa3b, v92
	v_mul_f32_e32 v211, 0xbfb8aa3b, v93
	v_exp_f32_e32 v208, v208
	v_exp_f32_e32 v209, v209
	v_exp_f32_e32 v210, v210
	v_exp_f32_e32 v211, v211
	v_add_f32_e32 v208, 1.0, v208
	v_add_f32_e32 v209, 1.0, v209
	v_add_f32_e32 v210, 1.0, v210
	v_add_f32_e32 v211, 1.0, v211
	v_rcp_f32_e32 v208, v208
	v_rcp_f32_e32 v209, v209
	v_rcp_f32_e32 v210, v210
	v_rcp_f32_e32 v211, v211
	v_mul_f32_e32 v90, v90, v208
	v_mul_f32_e32 v91, v91, v209
	v_mul_f32_e32 v92, v92, v210
	v_mul_f32_e32 v93, v93, v211
	v_mul_f32_e32 v90, v94, v90
	v_mul_f32_e32 v91, v95, v91
	v_mul_f32_e32 v92, v96, v92
	v_mul_f32_e32 v93, v97, v93
	v_cvt_pk_bf16_f32 v218, v90, v91
	v_cvt_pk_bf16_f32 v219, v92, v93
	v_mad_u32_u24 v40, v235, s29, v247
	s_and_saveexec_b64 s[30:31], s[22:23]
	global_store_dwordx2 v40, v[218:219], s[10:11]
	s_mov_b64 exec, s[30:31]
	v_mul_f32_e32 v208, 0xbfb8aa3b, v82
	v_mul_f32_e32 v209, 0xbfb8aa3b, v83
	v_mul_f32_e32 v210, 0xbfb8aa3b, v84
	v_mul_f32_e32 v211, 0xbfb8aa3b, v85
	v_exp_f32_e32 v208, v208
	v_exp_f32_e32 v209, v209
	v_exp_f32_e32 v210, v210
	v_exp_f32_e32 v211, v211
	v_add_f32_e32 v208, 1.0, v208
	v_add_f32_e32 v209, 1.0, v209
	v_add_f32_e32 v210, 1.0, v210
; #define PG8_LAS __attribute__((address_space(3)))
; __device__ __forceinline__ unsigned cvt_pk_bf16(float lo, float hi) { unsigned r; asm volatile("v_cvt_pk_bf16_f32 %0, %1, %2" : "=v"(r) : "v"(lo), "v"(hi)); return r; }
;     __device__ __forceinline__ void operator()(const f32x4 (&acc)[2][2][4][2], const Unit& u, int wr, int wc, int fr, int fq) const {
;     ...
;                 for (int m = 0; m < 4; ++m) { const int r = 128 * ai + 64 * wr + 16 * m + fr, t = tstart + r;
;                     const bool upok = t >= 1, dnok = (t + 1) < T, store_ok = (r >= vlo) && (r < vhi) && (t < T);
;                     f32x4 res[2];
; #pragma unroll
;                     for (int bj = 0; bj < 2; ++bj) { const f32x4 cur = acc[ai][bj][m][n];
;                         f32x4 su = cur, sd = cur;
;                         if (m > 0) { if (fr == 15) su = acc[ai][bj][m > 0 ? m - 1 : 0][n]; }
;                         if (m < 3) { if (fr == 0) sd = acc[ai][bj][m < 3 ? m + 1 : 3][n]; }
;                         f32x4 up, dn;
;                         up[0] = dpp_ror1(su[0]); up[1] = dpp_ror1(su[1]); up[2] = dpp_ror1(su[2]); up[3] = dpp_ror1(su[3]);
;                         dn[0] = dpp_ror15(sd[0]); dn[1] = dpp_ror15(sd[1]); dn[2] = dpp_ror15(sd[2]); dn[3] = dpp_ror15(sd[3]);
;                         if (m == 0) { f32x4 halo = zero4; if (blk > 0) halo = *(const PG8_LAS f32x4*)(xb + (((((blk - 1) * 2 + 1) * 4 + wc) * 4 + fq) * 16 + (bj * 2 + n) * 4)); if (fr == 0) up = halo; }
;                         if (m == 3) { f32x4 halo = zero4; if (blk < 3) halo = *(const PG8_LAS f32x4*)(xb + (((((blk + 1) * 2 + 0) * 4 + wc) * 4 + fq) * 16 + (bj * 2 + n) * 4)); if (fr == 15) dn = halo; }
;                         if (edge) { if (!upok) up = zero4; if (!dnok) dn = zero4; }
;                         res[bj] = bb[bj] + w0[bj] * up + w1[bj] * cur + w2[bj] * dn; }
;                     if (store_ok) {
;                         float o[4];
; #pragma unroll
;                         for (int j = 0; j < 4; ++j) { const float gg = res[1][j]; o[j] = gg * __builtin_amdgcn_rcpf(1.f + __expf(-gg)) * res[0][j]; }
;                         u32x2 w; w.x = cvt_pk_bf16(o[0], o[1]); w.y = cvt_pk_bf16(o[2], o[3]);
;                         *(u32x2*)(ACT + (size_t)(seqrow + t) * 2816 + ch0 + 4 * n) = w; } } }
	v_add_f32_e32 v211, 1.0, v211
	v_rcp_f32_e32 v208, v208
	v_rcp_f32_e32 v209, v209
	v_rcp_f32_e32 v210, v210
	v_rcp_f32_e32 v211, v211
	v_mul_f32_e32 v82, v82, v208
	v_mul_f32_e32 v83, v83, v209
	v_mul_f32_e32 v84, v84, v210
	v_mul_f32_e32 v85, v85, v211
	v_mul_f32_e32 v82, v86, v82
	v_mul_f32_e32 v83, v87, v83
	v_mul_f32_e32 v84, v88, v84
	v_mul_f32_e32 v85, v89, v85
	v_cvt_pk_bf16_f32 v212, v82, v83
	v_cvt_pk_bf16_f32 v213, v84, v85
	v_mad_u32_u24 v221, v236, s29, v247
	s_and_saveexec_b64 s[30:31], s[24:25]
	global_store_dwordx2 v221, v[212:213], s[10:11]
	s_mov_b64 exec, s[30:31]
	v_mul_f32_e32 v208, 0xbfb8aa3b, v74
	v_mul_f32_e32 v209, 0xbfb8aa3b, v75
	v_mul_f32_e32 v210, 0xbfb8aa3b, v76
	v_mul_f32_e32 v211, 0xbfb8aa3b, v77
	v_exp_f32_e32 v208, v208
	v_exp_f32_e32 v209, v209
	v_exp_f32_e32 v210, v210
	v_exp_f32_e32 v211, v211
	v_add_f32_e32 v208, 1.0, v208
	v_add_f32_e32 v209, 1.0, v209
	v_add_f32_e32 v210, 1.0, v210
	v_add_f32_e32 v211, 1.0, v211
	v_rcp_f32_e32 v208, v208
	v_rcp_f32_e32 v209, v209
	v_rcp_f32_e32 v210, v210
	v_rcp_f32_e32 v211, v211
	v_mul_f32_e32 v74, v74, v208
	v_mul_f32_e32 v75, v75, v209
	v_mul_f32_e32 v76, v76, v210
	v_mul_f32_e32 v77, v77, v211
	v_mul_f32_e32 v74, v78, v74
	v_mul_f32_e32 v75, v79, v75
	v_mul_f32_e32 v76, v80, v76
	v_mul_f32_e32 v77, v81, v77
	v_cvt_pk_bf16_f32 v218, v74, v75
	v_cvt_pk_bf16_f32 v219, v76, v77
	v_mad_u32_u24 v40, v237, s29, v247
	s_and_saveexec_b64 s[30:31], s[26:27]
	global_store_dwordx2 v40, v[218:219], s[10:11]
	s_mov_b64 exec, s[30:31]
	s_waitcnt vmcnt(4)
	ds_write_b64 v243, v[72:73]
	ds_write_b64 v243, v[64:65] offset:256
	ds_write_b64 v243, v[56:57] offset:512
	ds_write_b64 v243, v[48:49] offset:768
	s_waitcnt lgkmcnt(11)
	v_cndmask_b32_e64 v170, v170, v198, s[6:7]
	v_cndmask_b32_e64 v171, v171, v199, s[6:7]
	v_pk_fma_f32 v[202:203], v[138:139], v[170:171], v[150:151]
	v_pk_fma_f32 v[70:71], v[70:71], v[142:143], v[202:203]
	v_pk_fma_f32 v[70:71], v[146:147], v[178:179], v[70:71]
	ds_read_b64 v[170:171], v244
	ds_read_b64 v[178:179], v243 offset:16
	ds_read_b64 v[198:199], v245 offset:24
	s_waitcnt lgkmcnt(12)
	v_pk_fma_f32 v[202:203], v[138:139], v[172:173], v[150:151]
	v_pk_fma_f32 v[62:63], v[62:63], v[142:143], v[202:203]
	v_pk_fma_f32 v[62:63], v[146:147], v[180:181], v[62:63]
	ds_read_b64 v[172:173], v244 offset:256
	ds_read_b64 v[180:181], v243 offset:272
	s_waitcnt lgkmcnt(12)
	v_pk_fma_f32 v[202:203], v[138:139], v[174:175], v[150:151]
	v_pk_fma_f32 v[54:55], v[54:55], v[142:143], v[202:203]
	v_pk_fma_f32 v[54:55], v[146:147], v[194:195], v[54:55]
	ds_read_b64 v[174:175], v244 offset:512
	ds_read_b64 v[194:195], v243 offset:528
	s_waitcnt lgkmcnt(11)
	v_cndmask_b32_e64 v196, v196, v200, s[4:5]
	v_cndmask_b32_e64 v197, v197, v201, s[4:5]
	v_pk_fma_f32 v[202:203], v[138:139], v[176:177], v[150:151]
	v_pk_fma_f32 v[46:47], v[46:47], v[142:143], v[202:203]
	v_pk_fma_f32 v[46:47], v[146:147], v[196:197], v[46:47]
	ds_read_b64 v[176:177], v244 offset:768
	ds_read_b64 v[196:197], v243 offset:784
	ds_read_b64 v[200:201], v238 offset:2072
	ds_write_b64 v243, v[66:67]
	ds_write_b64 v243, v[58:59] offset:256
	ds_write_b64 v243, v[50:51] offset:512
	ds_write_b64 v243, v[42:43] offset:768
	s_waitcnt lgkmcnt(11)
	v_cndmask_b32_e64 v170, v170, v198, s[6:7]
	v_cndmask_b32_e64 v171, v171, v199, s[6:7]
	v_pk_fma_f32 v[202:203], v[140:141], v[170:171], v[152:153]
	v_pk_fma_f32 v[72:73], v[72:73], v[144:145], v[202:203]
	v_pk_fma_f32 v[72:73], v[148:149], v[178:179], v[72:73]
	ds_read_b64 v[170:171], v244
	ds_read_b64 v[178:179], v243 offset:16
	ds_read_b64 v[198:199], v245 offset:48
	s_waitcnt lgkmcnt(12)
	v_pk_fma_f32 v[202:203], v[140:141], v[172:173], v[152:153]
	v_pk_fma_f32 v[64:65], v[64:65], v[144:145], v[202:203]
	v_pk_fma_f32 v[64:65], v[148:149], v[180:181], v[64:65]
	ds_read_b64 v[172:173], v244 offset:256
	ds_read_b64 v[180:181], v243 offset:272
	s_waitcnt lgkmcnt(12)
	v_pk_fma_f32 v[202:203], v[140:141], v[174:175], v[152:153]
	v_pk_fma_f32 v[56:57], v[56:57], v[144:145], v[202:203]
	v_pk_fma_f32 v[56:57], v[148:149], v[194:195], v[56:57]
	ds_read_b64 v[174:175], v244 offset:512
	ds_read_b64 v[194:195], v243 offset:528
	s_waitcnt lgkmcnt(11)
	v_cndmask_b32_e64 v196, v196, v200, s[4:5]
	v_cndmask_b32_e64 v197, v197, v201, s[4:5]
	v_pk_fma_f32 v[202:203], v[140:141], v[176:177], v[152:153]
	v_pk_fma_f32 v[48:49], v[48:49], v[144:145], v[202:203]
	v_pk_fma_f32 v[48:49], v[148:149], v[196:197], v[48:49]
	ds_read_b64 v[176:177], v244 offset:768
	ds_read_b64 v[196:197], v243 offset:784
	ds_read_b64 v[200:201], v238 offset:2096
	ds_write_b64 v243, v[68:69]
	ds_write_b64 v243, v[60:61] offset:256
	ds_write_b64 v243, v[52:53] offset:512
	ds_write_b64 v243, v[44:45] offset:768
	s_waitcnt lgkmcnt(11)
	v_cndmask_b32_e64 v170, v170, v198, s[6:7]
	v_cndmask_b32_e64 v171, v171, v199, s[6:7]
	v_pk_fma_f32 v[202:203], v[154:155], v[170:171], v[166:167]
	v_pk_fma_f32 v[66:67], v[66:67], v[158:159], v[202:203]
	v_pk_fma_f32 v[66:67], v[162:163], v[178:179], v[66:67]
	ds_read_b64 v[170:171], v244
	ds_read_b64 v[178:179], v243 offset:16
	ds_read_b64 v[198:199], v245 offset:56
	s_waitcnt lgkmcnt(12)
	v_pk_fma_f32 v[202:203], v[154:155], v[172:173], v[166:167]
	v_pk_fma_f32 v[58:59], v[58:59], v[158:159], v[202:203]
	v_pk_fma_f32 v[58:59], v[162:163], v[180:181], v[58:59]
	ds_read_b64 v[172:173], v244 offset:256
	ds_read_b64 v[180:181], v243 offset:272
	s_waitcnt lgkmcnt(12)
	v_pk_fma_f32 v[202:203], v[154:155], v[174:175], v[166:167]
	v_pk_fma_f32 v[50:51], v[50:51], v[158:159], v[202:203]
	v_pk_fma_f32 v[50:51], v[162:163], v[194:195], v[50:51]
	ds_read_b64 v[174:175], v244 offset:512
	ds_read_b64 v[194:195], v243 offset:528
	s_waitcnt lgkmcnt(11)
; #define PG8_LAS __attribute__((address_space(3)))
; __device__ __forceinline__ unsigned cvt_pk_bf16(float lo, float hi) { unsigned r; asm volatile("v_cvt_pk_bf16_f32 %0, %1, %2" : "=v"(r) : "v"(lo), "v"(hi)); return r; }
;     __device__ __forceinline__ void operator()(const f32x4 (&acc)[2][2][4][2], const Unit& u, int wr, int wc, int fr, int fq) const {
;     ...
;                 for (int m = 0; m < 4; ++m) { const int r = 128 * ai + 64 * wr + 16 * m + fr, t = tstart + r;
;                     const bool upok = t >= 1, dnok = (t + 1) < T, store_ok = (r >= vlo) && (r < vhi) && (t < T);
;                     f32x4 res[2];
; #pragma unroll
;                     for (int bj = 0; bj < 2; ++bj) { const f32x4 cur = acc[ai][bj][m][n];
;                         f32x4 su = cur, sd = cur;
;                         if (m > 0) { if (fr == 15) su = acc[ai][bj][m > 0 ? m - 1 : 0][n]; }
;                         if (m < 3) { if (fr == 0) sd = acc[ai][bj][m < 3 ? m + 1 : 3][n]; }
;                         f32x4 up, dn;
;                         up[0] = dpp_ror1(su[0]); up[1] = dpp_ror1(su[1]); up[2] = dpp_ror1(su[2]); up[3] = dpp_ror1(su[3]);
;                         dn[0] = dpp_ror15(sd[0]); dn[1] = dpp_ror15(sd[1]); dn[2] = dpp_ror15(sd[2]); dn[3] = dpp_ror15(sd[3]);
;                         if (m == 0) { f32x4 halo = zero4; if (blk > 0) halo = *(const PG8_LAS f32x4*)(xb + (((((blk - 1) * 2 + 1) * 4 + wc) * 4 + fq) * 16 + (bj * 2 + n) * 4)); if (fr == 0) up = halo; }
;                         if (m == 3) { f32x4 halo = zero4; if (blk < 3) halo = *(const PG8_LAS f32x4*)(xb + (((((blk + 1) * 2 + 0) * 4 + wc) * 4 + fq) * 16 + (bj * 2 + n) * 4)); if (fr == 15) dn = halo; }
;                         if (edge) { if (!upok) up = zero4; if (!dnok) dn = zero4; }
;                         res[bj] = bb[bj] + w0[bj] * up + w1[bj] * cur + w2[bj] * dn; }
;                     if (store_ok) {
;                         float o[4];
; #pragma unroll
;                         for (int j = 0; j < 4; ++j) { const float gg = res[1][j]; o[j] = gg * __builtin_amdgcn_rcpf(1.f + __expf(-gg)) * res[0][j]; }
;                         u32x2 w; w.x = cvt_pk_bf16(o[0], o[1]); w.y = cvt_pk_bf16(o[2], o[3]);
;                         *(u32x2*)(ACT + (size_t)(seqrow + t) * 2816 + ch0 + 4 * n) = w; } } }
	v_cndmask_b32_e64 v196, v196, v200, s[4:5]
	v_cndmask_b32_e64 v197, v197, v201, s[4:5]
	v_pk_fma_f32 v[202:203], v[154:155], v[176:177], v[166:167]
	v_pk_fma_f32 v[42:43], v[42:43], v[158:159], v[202:203]
	v_pk_fma_f32 v[42:43], v[162:163], v[196:197], v[42:43]
	ds_read_b64 v[176:177], v244 offset:768
	ds_read_b64 v[196:197], v243 offset:784
	ds_read_b64 v[200:201], v238 offset:2104
	ds_write_b64 v243, v[30:31]
	ds_write_b64 v243, v[22:23] offset:256
	ds_write_b64 v243, v[14:15] offset:512
	ds_write_b64 v243, v[6:7] offset:768
	s_waitcnt lgkmcnt(11)
	v_cndmask_b32_e64 v170, v170, v198, s[6:7]
	v_cndmask_b32_e64 v171, v171, v199, s[6:7]
	v_pk_fma_f32 v[202:203], v[156:157], v[170:171], v[168:169]
	v_pk_fma_f32 v[68:69], v[68:69], v[160:161], v[202:203]
	v_pk_fma_f32 v[68:69], v[164:165], v[178:179], v[68:69]
	ds_read_b64 v[170:171], v244
	ds_read_b64 v[178:179], v243 offset:16
	ds_read_b64 v[198:199], v238 offset:3088
	s_waitcnt lgkmcnt(12)
	v_pk_fma_f32 v[202:203], v[156:157], v[172:173], v[168:169]
	v_pk_fma_f32 v[60:61], v[60:61], v[160:161], v[202:203]
	v_pk_fma_f32 v[60:61], v[164:165], v[180:181], v[60:61]
	ds_read_b64 v[172:173], v244 offset:256
	ds_read_b64 v[180:181], v243 offset:272
	s_waitcnt lgkmcnt(12)
	v_pk_fma_f32 v[202:203], v[156:157], v[174:175], v[168:169]
	v_pk_fma_f32 v[52:53], v[52:53], v[160:161], v[202:203]
	v_pk_fma_f32 v[52:53], v[164:165], v[194:195], v[52:53]
	ds_read_b64 v[174:175], v244 offset:512
	ds_read_b64 v[194:195], v243 offset:528
	s_waitcnt lgkmcnt(11)
	v_cndmask_b32_e64 v196, v196, v200, s[4:5]
	v_cndmask_b32_e64 v197, v197, v201, s[4:5]
	v_pk_fma_f32 v[202:203], v[156:157], v[176:177], v[168:169]
	v_pk_fma_f32 v[44:45], v[44:45], v[160:161], v[202:203]
	v_pk_fma_f32 v[44:45], v[164:165], v[196:197], v[44:45]
	ds_read_b64 v[176:177], v244 offset:768
	ds_read_b64 v[196:197], v243 offset:784
	ds_read_b64 v[200:201], v246 offset:16
	v_mul_f32_e32 v208, 0xbfb8aa3b, v66
	v_mul_f32_e32 v209, 0xbfb8aa3b, v67
	v_mul_f32_e32 v210, 0xbfb8aa3b, v68
	v_mul_f32_e32 v211, 0xbfb8aa3b, v69
	v_exp_f32_e32 v208, v208
	v_exp_f32_e32 v209, v209
	v_exp_f32_e32 v210, v210
	v_exp_f32_e32 v211, v211
	v_add_f32_e32 v208, 1.0, v208
	v_add_f32_e32 v209, 1.0, v209
	v_add_f32_e32 v210, 1.0, v210
	v_add_f32_e32 v211, 1.0, v211
	v_rcp_f32_e32 v208, v208
	v_rcp_f32_e32 v209, v209
	v_rcp_f32_e32 v210, v210
	v_rcp_f32_e32 v211, v211
	v_mul_f32_e32 v66, v66, v208
	v_mul_f32_e32 v67, v67, v209
	v_mul_f32_e32 v68, v68, v210
	v_mul_f32_e32 v69, v69, v211
	v_mul_f32_e32 v66, v70, v66
	v_mul_f32_e32 v67, v71, v67
	v_mul_f32_e32 v68, v72, v68
	v_mul_f32_e32 v69, v73, v69
	v_cvt_pk_bf16_f32 v212, v66, v67
	v_cvt_pk_bf16_f32 v213, v68, v69
	v_mad_u32_u24 v221, v227, s29, v247
	s_and_saveexec_b64 s[30:31], s[12:13]
	global_store_dwordx2 v221, v[212:213], s[10:11] offset:8
	s_mov_b64 exec, s[30:31]
	v_mul_f32_e32 v208, 0xbfb8aa3b, v58
	v_mul_f32_e32 v209, 0xbfb8aa3b, v59
	v_mul_f32_e32 v210, 0xbfb8aa3b, v60
	v_mul_f32_e32 v211, 0xbfb8aa3b, v61
	v_exp_f32_e32 v208, v208
	v_exp_f32_e32 v209, v209
	v_exp_f32_e32 v210, v210
	v_exp_f32_e32 v211, v211
	v_add_f32_e32 v208, 1.0, v208
	v_add_f32_e32 v209, 1.0, v209
	v_add_f32_e32 v210, 1.0, v210
	v_add_f32_e32 v211, 1.0, v211
	v_rcp_f32_e32 v208, v208
	v_rcp_f32_e32 v209, v209
	v_rcp_f32_e32 v210, v210
	v_rcp_f32_e32 v211, v211
	v_mul_f32_e32 v58, v58, v208
	v_mul_f32_e32 v59, v59, v209
	v_mul_f32_e32 v60, v60, v210
	v_mul_f32_e32 v61, v61, v211
	v_mul_f32_e32 v58, v62, v58
	v_mul_f32_e32 v59, v63, v59
	v_mul_f32_e32 v60, v64, v60
	v_mul_f32_e32 v61, v65, v61
	v_cvt_pk_bf16_f32 v218, v58, v59
	v_cvt_pk_bf16_f32 v219, v60, v61
	v_mad_u32_u24 v40, v231, s29, v247
	s_and_saveexec_b64 s[30:31], s[14:15]
	global_store_dwordx2 v40, v[218:219], s[10:11] offset:8
	s_mov_b64 exec, s[30:31]
	v_mul_f32_e32 v208, 0xbfb8aa3b, v50
	v_mul_f32_e32 v209, 0xbfb8aa3b, v51
	v_mul_f32_e32 v210, 0xbfb8aa3b, v52
	v_mul_f32_e32 v211, 0xbfb8aa3b, v53
	v_exp_f32_e32 v208, v208
	v_exp_f32_e32 v209, v209
	v_exp_f32_e32 v210, v210
	v_exp_f32_e32 v211, v211
	v_add_f32_e32 v208, 1.0, v208
	v_add_f32_e32 v209, 1.0, v209
	v_add_f32_e32 v210, 1.0, v210
	v_add_f32_e32 v211, 1.0, v211
	v_rcp_f32_e32 v208, v208
	v_rcp_f32_e32 v209, v209
	v_rcp_f32_e32 v210, v210
	v_rcp_f32_e32 v211, v211
	v_mul_f32_e32 v50, v50, v208
	v_mul_f32_e32 v51, v51, v209
	v_mul_f32_e32 v52, v52, v210
	v_mul_f32_e32 v53, v53, v211
	v_mul_f32_e32 v50, v54, v50
	v_mul_f32_e32 v51, v55, v51
	v_mul_f32_e32 v52, v56, v52
	v_mul_f32_e32 v53, v57, v53
	v_cvt_pk_bf16_f32 v212, v50, v51
	v_cvt_pk_bf16_f32 v213, v52, v53
	v_mad_u32_u24 v221, v232, s29, v247
	s_and_saveexec_b64 s[30:31], s[16:17]
	global_store_dwordx2 v221, v[212:213], s[10:11] offset:8
	s_mov_b64 exec, s[30:31]
	v_mul_f32_e32 v208, 0xbfb8aa3b, v42
	v_mul_f32_e32 v209, 0xbfb8aa3b, v43
	v_mul_f32_e32 v210, 0xbfb8aa3b, v44
	v_mul_f32_e32 v211, 0xbfb8aa3b, v45
	v_exp_f32_e32 v208, v208
	v_exp_f32_e32 v209, v209
	v_exp_f32_e32 v210, v210
	v_exp_f32_e32 v211, v211
	v_add_f32_e32 v208, 1.0, v208
	v_add_f32_e32 v209, 1.0, v209
	v_add_f32_e32 v210, 1.0, v210
	v_add_f32_e32 v211, 1.0, v211
	v_rcp_f32_e32 v208, v208
	v_rcp_f32_e32 v209, v209
	v_rcp_f32_e32 v210, v210
	v_rcp_f32_e32 v211, v211
	v_mul_f32_e32 v42, v42, v208
	v_mul_f32_e32 v43, v43, v209
	v_mul_f32_e32 v44, v44, v210
	v_mul_f32_e32 v45, v45, v211
	v_mul_f32_e32 v42, v46, v42
	v_mul_f32_e32 v43, v47, v43
	v_mul_f32_e32 v44, v48, v44
	v_mul_f32_e32 v45, v49, v45
	v_cvt_pk_bf16_f32 v218, v42, v43
	v_cvt_pk_bf16_f32 v219, v44, v45
	v_mad_u32_u24 v40, v233, s29, v247
	s_and_saveexec_b64 s[30:31], s[18:19]
	global_store_dwordx2 v40, v[218:219], s[10:11] offset:8
	s_mov_b64 exec, s[30:31]
	ds_write_b64 v243, v[32:33]
	ds_write_b64 v243, v[24:25] offset:256
	ds_write_b64 v243, v[16:17] offset:512
	ds_write_b64 v243, v[8:9] offset:768
	s_waitcnt lgkmcnt(11)
; #define PG8_LAS __attribute__((address_space(3)))
; __device__ __forceinline__ float dpp_ror1(float v) { return __builtin_bit_cast(float, __builtin_amdgcn_update_dpp(0, __builtin_bit_cast(int, v), 0x121, 0xf, 0xf, false)); }
; __device__ __forceinline__ float dpp_ror15(float v) { return __builtin_bit_cast(float, __builtin_amdgcn_update_dpp(0, __builtin_bit_cast(int, v), 0x12F, 0xf, 0xf, false)); }
;     __device__ __forceinline__ void operator()(const f32x4 (&acc)[2][2][4][2], const Unit& u, int wr, int wc, int fr, int fq) const {
;     ...
;                 for (int m = 0; m < 4; ++m) { const int r = 128 * ai + 64 * wr + 16 * m + fr, t = tstart + r;
;                     const bool upok = t >= 1, dnok = (t + 1) < T, store_ok = (r >= vlo) && (r < vhi) && (t < T);
;                     f32x4 res[2];
; #pragma unroll
;                     for (int bj = 0; bj < 2; ++bj) { const f32x4 cur = acc[ai][bj][m][n];
;                         f32x4 su = cur, sd = cur;
;                         if (m > 0) { if (fr == 15) su = acc[ai][bj][m > 0 ? m - 1 : 0][n]; }
;                         if (m < 3) { if (fr == 0) sd = acc[ai][bj][m < 3 ? m + 1 : 3][n]; }
;                         f32x4 up, dn;
;                         up[0] = dpp_ror1(su[0]); up[1] = dpp_ror1(su[1]); up[2] = dpp_ror1(su[2]); up[3] = dpp_ror1(su[3]);
;                         dn[0] = dpp_ror15(sd[0]); dn[1] = dpp_ror15(sd[1]); dn[2] = dpp_ror15(sd[2]); dn[3] = dpp_ror15(sd[3]);
;                         if (m == 0) { f32x4 halo = zero4; if (blk > 0) halo = *(const PG8_LAS f32x4*)(xb + (((((blk - 1) * 2 + 1) * 4 + wc) * 4 + fq) * 16 + (bj * 2 + n) * 4)); if (fr == 0) up = halo; }
;                         if (m == 3) { f32x4 halo = zero4; if (blk < 3) halo = *(const PG8_LAS f32x4*)(xb + (((((blk + 1) * 2 + 0) * 4 + wc) * 4 + fq) * 16 + (bj * 2 + n) * 4)); if (fr == 15) dn = halo; }
;                         if (edge) { if (!upok) up = zero4; if (!dnok) dn = zero4; }
;                         res[bj] = bb[bj] + w0[bj] * up + w1[bj] * cur + w2[bj] * dn; }
	v_cndmask_b32_e64 v170, v170, v198, s[6:7]
	v_cndmask_b32_e64 v171, v171, v199, s[6:7]
	v_pk_fma_f32 v[202:203], v[138:139], v[170:171], v[150:151]
	v_pk_fma_f32 v[30:31], v[30:31], v[142:143], v[202:203]
	v_pk_fma_f32 v[30:31], v[146:147], v[178:179], v[30:31]
	ds_read_b64 v[170:171], v244
	ds_read_b64 v[178:179], v243 offset:16
	ds_read_b64 v[198:199], v238 offset:3096
	s_waitcnt lgkmcnt(12)
	v_pk_fma_f32 v[202:203], v[138:139], v[172:173], v[150:151]
	v_pk_fma_f32 v[22:23], v[22:23], v[142:143], v[202:203]
	v_pk_fma_f32 v[22:23], v[146:147], v[180:181], v[22:23]
	ds_read_b64 v[172:173], v244 offset:256
	ds_read_b64 v[180:181], v243 offset:272
	s_waitcnt lgkmcnt(12)
	v_pk_fma_f32 v[202:203], v[138:139], v[174:175], v[150:151]
	v_pk_fma_f32 v[14:15], v[14:15], v[142:143], v[202:203]
	v_pk_fma_f32 v[14:15], v[146:147], v[194:195], v[14:15]
	ds_read_b64 v[174:175], v244 offset:512
	ds_read_b64 v[194:195], v243 offset:528
	s_waitcnt lgkmcnt(11)
	v_cndmask_b32_e64 v196, v196, v200, s[4:5]
	v_cndmask_b32_e64 v197, v197, v201, s[4:5]
	v_pk_fma_f32 v[202:203], v[138:139], v[176:177], v[150:151]
	v_pk_fma_f32 v[6:7], v[6:7], v[142:143], v[202:203]
	v_pk_fma_f32 v[6:7], v[146:147], v[196:197], v[6:7]
	ds_read_b64 v[176:177], v244 offset:768
	ds_read_b64 v[196:197], v243 offset:784
	ds_read_b64 v[200:201], v246 offset:24
	ds_write_b64 v243, v[26:27]
	ds_write_b64 v243, v[18:19] offset:256
	ds_write_b64 v243, v[10:11] offset:512
	ds_write_b64 v243, v[2:3] offset:768
	s_waitcnt lgkmcnt(11)
	v_cndmask_b32_e64 v170, v170, v198, s[6:7]
	v_cndmask_b32_e64 v171, v171, v199, s[6:7]
	v_pk_fma_f32 v[202:203], v[140:141], v[170:171], v[152:153]
	v_pk_fma_f32 v[32:33], v[32:33], v[144:145], v[202:203]
	v_pk_fma_f32 v[32:33], v[148:149], v[178:179], v[32:33]
	ds_read_b64 v[170:171], v244
	ds_read_b64 v[178:179], v243 offset:16
	ds_read_b64 v[198:199], v238 offset:3120
	s_waitcnt lgkmcnt(12)
	v_pk_fma_f32 v[202:203], v[140:141], v[172:173], v[152:153]
	v_pk_fma_f32 v[24:25], v[24:25], v[144:145], v[202:203]
	v_pk_fma_f32 v[24:25], v[148:149], v[180:181], v[24:25]
	ds_read_b64 v[172:173], v244 offset:256
	ds_read_b64 v[180:181], v243 offset:272
	s_waitcnt lgkmcnt(12)
	v_pk_fma_f32 v[202:203], v[140:141], v[174:175], v[152:153]
	v_pk_fma_f32 v[16:17], v[16:17], v[144:145], v[202:203]
	v_pk_fma_f32 v[16:17], v[148:149], v[194:195], v[16:17]
	ds_read_b64 v[174:175], v244 offset:512
	ds_read_b64 v[194:195], v243 offset:528
	s_waitcnt lgkmcnt(11)
	v_cndmask_b32_e64 v196, v196, v200, s[4:5]
	v_cndmask_b32_e64 v197, v197, v201, s[4:5]
	v_pk_fma_f32 v[202:203], v[140:141], v[176:177], v[152:153]
	v_pk_fma_f32 v[8:9], v[8:9], v[144:145], v[202:203]
	v_pk_fma_f32 v[8:9], v[148:149], v[196:197], v[8:9]
	ds_read_b64 v[176:177], v244 offset:768
	ds_read_b64 v[196:197], v243 offset:784
	ds_read_b64 v[200:201], v246 offset:48
	ds_write_b64 v243, v[28:29]
	ds_write_b64 v243, v[20:21] offset:256
	ds_write_b64 v243, v[12:13] offset:512
	ds_write_b64 v243, v[4:5] offset:768
	s_waitcnt lgkmcnt(11)
	v_cndmask_b32_e64 v170, v170, v198, s[6:7]
	v_cndmask_b32_e64 v171, v171, v199, s[6:7]
	v_pk_fma_f32 v[202:203], v[154:155], v[170:171], v[166:167]
	v_pk_fma_f32 v[26:27], v[26:27], v[158:159], v[202:203]
	v_pk_fma_f32 v[26:27], v[162:163], v[178:179], v[26:27]
	ds_read_b64 v[170:171], v244
	ds_read_b64 v[178:179], v243 offset:16
	ds_read_b64 v[198:199], v238 offset:3128
	s_waitcnt lgkmcnt(12)
	v_pk_fma_f32 v[202:203], v[154:155], v[172:173], v[166:167]
	v_pk_fma_f32 v[18:19], v[18:19], v[158:159], v[202:203]
	v_pk_fma_f32 v[18:19], v[162:163], v[180:181], v[18:19]
	ds_read_b64 v[172:173], v244 offset:256
	ds_read_b64 v[180:181], v243 offset:272
	s_waitcnt lgkmcnt(12)
	v_pk_fma_f32 v[202:203], v[154:155], v[174:175], v[166:167]
	v_pk_fma_f32 v[10:11], v[10:11], v[158:159], v[202:203]
	v_pk_fma_f32 v[10:11], v[162:163], v[194:195], v[10:11]
	ds_read_b64 v[174:175], v244 offset:512
	ds_read_b64 v[194:195], v243 offset:528
	s_waitcnt lgkmcnt(11)
	v_cndmask_b32_e64 v196, v196, v200, s[4:5]
	v_cndmask_b32_e64 v197, v197, v201, s[4:5]
	v_pk_fma_f32 v[202:203], v[154:155], v[176:177], v[166:167]
	v_pk_fma_f32 v[2:3], v[2:3], v[158:159], v[202:203]
	v_pk_fma_f32 v[2:3], v[162:163], v[196:197], v[2:3]
	ds_read_b64 v[176:177], v244 offset:768
	ds_read_b64 v[196:197], v243 offset:784
	ds_read_b64 v[200:201], v246 offset:56
	s_waitcnt lgkmcnt(7)
	v_cndmask_b32_e64 v170, v170, v198, s[6:7]
	v_cndmask_b32_e64 v171, v171, v199, s[6:7]
	v_pk_fma_f32 v[202:203], v[156:157], v[170:171], v[168:169]
	v_pk_fma_f32 v[28:29], v[28:29], v[160:161], v[202:203]
	v_pk_fma_f32 v[28:29], v[164:165], v[178:179], v[28:29]
	s_waitcnt lgkmcnt(5)
	v_pk_fma_f32 v[202:203], v[156:157], v[172:173], v[168:169]
	v_pk_fma_f32 v[20:21], v[20:21], v[160:161], v[202:203]
	v_pk_fma_f32 v[20:21], v[164:165], v[180:181], v[20:21]
	s_waitcnt lgkmcnt(3)
	v_pk_fma_f32 v[202:203], v[156:157], v[174:175], v[168:169]
	v_pk_fma_f32 v[12:13], v[12:13], v[160:161], v[202:203]
	v_pk_fma_f32 v[12:13], v[164:165], v[194:195], v[12:13]
	s_waitcnt lgkmcnt(0)
; #define PG8_LAS __attribute__((address_space(3)))
; __device__ __forceinline__ unsigned cvt_pk_bf16(float lo, float hi) { unsigned r; asm volatile("v_cvt_pk_bf16_f32 %0, %1, %2" : "=v"(r) : "v"(lo), "v"(hi)); return r; }
;     __device__ __forceinline__ void operator()(const f32x4 (&acc)[2][2][4][2], const Unit& u, int wr, int wc, int fr, int fq) const {
;     ...
;                 for (int m = 0; m < 4; ++m) { const int r = 128 * ai + 64 * wr + 16 * m + fr, t = tstart + r;
;                     const bool upok = t >= 1, dnok = (t + 1) < T, store_ok = (r >= vlo) && (r < vhi) && (t < T);
;                     f32x4 res[2];
; #pragma unroll
;                     for (int bj = 0; bj < 2; ++bj) { const f32x4 cur = acc[ai][bj][m][n];
;                         f32x4 su = cur, sd = cur;
;                         if (m > 0) { if (fr == 15) su = acc[ai][bj][m > 0 ? m - 1 : 0][n]; }
;                         if (m < 3) { if (fr == 0) sd = acc[ai][bj][m < 3 ? m + 1 : 3][n]; }
;                         f32x4 up, dn;
;                         up[0] = dpp_ror1(su[0]); up[1] = dpp_ror1(su[1]); up[2] = dpp_ror1(su[2]); up[3] = dpp_ror1(su[3]);
;                         dn[0] = dpp_ror15(sd[0]); dn[1] = dpp_ror15(sd[1]); dn[2] = dpp_ror15(sd[2]); dn[3] = dpp_ror15(sd[3]);
;                         if (m == 0) { f32x4 halo = zero4; if (blk > 0) halo = *(const PG8_LAS f32x4*)(xb + (((((blk - 1) * 2 + 1) * 4 + wc) * 4 + fq) * 16 + (bj * 2 + n) * 4)); if (fr == 0) up = halo; }
;                         if (m == 3) { f32x4 halo = zero4; if (blk < 3) halo = *(const PG8_LAS f32x4*)(xb + (((((blk + 1) * 2 + 0) * 4 + wc) * 4 + fq) * 16 + (bj * 2 + n) * 4)); if (fr == 15) dn = halo; }
;                         if (edge) { if (!upok) up = zero4; if (!dnok) dn = zero4; }
;                         res[bj] = bb[bj] + w0[bj] * up + w1[bj] * cur + w2[bj] * dn; }
;                     if (store_ok) {
;                         float o[4];
; #pragma unroll
;                         for (int j = 0; j < 4; ++j) { const float gg = res[1][j]; o[j] = gg * __builtin_amdgcn_rcpf(1.f + __expf(-gg)) * res[0][j]; }
;                         u32x2 w; w.x = cvt_pk_bf16(o[0], o[1]); w.y = cvt_pk_bf16(o[2], o[3]);
;                         *(u32x2*)(ACT + (size_t)(seqrow + t) * 2816 + ch0 + 4 * n) = w; } } }
	v_cndmask_b32_e64 v196, v196, v200, s[4:5]
	v_cndmask_b32_e64 v197, v197, v201, s[4:5]
	v_pk_fma_f32 v[202:203], v[156:157], v[176:177], v[168:169]
	v_pk_fma_f32 v[4:5], v[4:5], v[160:161], v[202:203]
	v_pk_fma_f32 v[4:5], v[164:165], v[196:197], v[4:5]
	v_mul_f32_e32 v208, 0xbfb8aa3b, v26
	v_mul_f32_e32 v209, 0xbfb8aa3b, v27
	v_mul_f32_e32 v210, 0xbfb8aa3b, v28
	v_mul_f32_e32 v211, 0xbfb8aa3b, v29
	v_exp_f32_e32 v208, v208
	v_exp_f32_e32 v209, v209
	v_exp_f32_e32 v210, v210
	v_exp_f32_e32 v211, v211
	v_add_f32_e32 v208, 1.0, v208
	v_add_f32_e32 v209, 1.0, v209
	v_add_f32_e32 v210, 1.0, v210
	v_add_f32_e32 v211, 1.0, v211
	v_rcp_f32_e32 v208, v208
	v_rcp_f32_e32 v209, v209
	v_rcp_f32_e32 v210, v210
	v_rcp_f32_e32 v211, v211
	v_mul_f32_e32 v26, v26, v208
	v_mul_f32_e32 v27, v27, v209
	v_mul_f32_e32 v28, v28, v210
	v_mul_f32_e32 v29, v29, v211
	v_mul_f32_e32 v26, v30, v26
	v_mul_f32_e32 v27, v31, v27
	v_mul_f32_e32 v28, v32, v28
	v_mul_f32_e32 v29, v33, v29
	v_cvt_pk_bf16_f32 v212, v26, v27
	v_cvt_pk_bf16_f32 v213, v28, v29
	v_mad_u32_u24 v221, v234, s29, v247
	s_and_saveexec_b64 s[30:31], s[20:21]
	global_store_dwordx2 v221, v[212:213], s[10:11] offset:8
	s_mov_b64 exec, s[30:31]
	v_mul_f32_e32 v208, 0xbfb8aa3b, v18
	v_mul_f32_e32 v209, 0xbfb8aa3b, v19
	v_mul_f32_e32 v210, 0xbfb8aa3b, v20
	v_mul_f32_e32 v211, 0xbfb8aa3b, v21
	v_exp_f32_e32 v208, v208
	v_exp_f32_e32 v209, v209
	v_exp_f32_e32 v210, v210
	v_exp_f32_e32 v211, v211
	v_add_f32_e32 v208, 1.0, v208
	v_add_f32_e32 v209, 1.0, v209
	v_add_f32_e32 v210, 1.0, v210
	v_add_f32_e32 v211, 1.0, v211
	v_rcp_f32_e32 v208, v208
	v_rcp_f32_e32 v209, v209
	v_rcp_f32_e32 v210, v210
	v_rcp_f32_e32 v211, v211
	v_mul_f32_e32 v18, v18, v208
	v_mul_f32_e32 v19, v19, v209
	v_mul_f32_e32 v20, v20, v210
	v_mul_f32_e32 v21, v21, v211
	v_mul_f32_e32 v18, v22, v18
	v_mul_f32_e32 v19, v23, v19
	v_mul_f32_e32 v20, v24, v20
	v_mul_f32_e32 v21, v25, v21
	v_cvt_pk_bf16_f32 v218, v18, v19
	v_cvt_pk_bf16_f32 v219, v20, v21
	v_mad_u32_u24 v40, v235, s29, v247
	s_and_saveexec_b64 s[30:31], s[22:23]
	global_store_dwordx2 v40, v[218:219], s[10:11] offset:8
	s_mov_b64 exec, s[30:31]
	v_mul_f32_e32 v208, 0xbfb8aa3b, v10
	v_mul_f32_e32 v209, 0xbfb8aa3b, v11
	v_mul_f32_e32 v210, 0xbfb8aa3b, v12
	v_mul_f32_e32 v211, 0xbfb8aa3b, v13
	v_exp_f32_e32 v208, v208
	v_exp_f32_e32 v209, v209
	v_exp_f32_e32 v210, v210
	v_exp_f32_e32 v211, v211
	v_add_f32_e32 v208, 1.0, v208
	v_add_f32_e32 v209, 1.0, v209
	v_add_f32_e32 v210, 1.0, v210
	v_add_f32_e32 v211, 1.0, v211
	v_rcp_f32_e32 v208, v208
	v_rcp_f32_e32 v209, v209
	v_rcp_f32_e32 v210, v210
	v_rcp_f32_e32 v211, v211
	v_mul_f32_e32 v10, v10, v208
	v_mul_f32_e32 v11, v11, v209
	v_mul_f32_e32 v12, v12, v210
	v_mul_f32_e32 v13, v13, v211
	v_mul_f32_e32 v10, v14, v10
	v_mul_f32_e32 v11, v15, v11
	v_mul_f32_e32 v12, v16, v12
	v_mul_f32_e32 v13, v17, v13
	v_cvt_pk_bf16_f32 v212, v10, v11
	v_cvt_pk_bf16_f32 v213, v12, v13
	v_mad_u32_u24 v221, v236, s29, v247
	s_and_saveexec_b64 s[30:31], s[24:25]
	global_store_dwordx2 v221, v[212:213], s[10:11] offset:8
	s_mov_b64 exec, s[30:31]
	v_mul_f32_e32 v208, 0xbfb8aa3b, v2
	v_mul_f32_e32 v209, 0xbfb8aa3b, v3
	v_mul_f32_e32 v210, 0xbfb8aa3b, v4
	v_mul_f32_e32 v211, 0xbfb8aa3b, v5
	v_exp_f32_e32 v208, v208
	v_exp_f32_e32 v209, v209
	v_exp_f32_e32 v210, v210
	v_exp_f32_e32 v211, v211
	v_add_f32_e32 v208, 1.0, v208
	v_add_f32_e32 v209, 1.0, v209
	v_add_f32_e32 v210, 1.0, v210
	v_add_f32_e32 v211, 1.0, v211
	v_rcp_f32_e32 v208, v208
	v_rcp_f32_e32 v209, v209
	v_rcp_f32_e32 v210, v210
	v_rcp_f32_e32 v211, v211
	v_mul_f32_e32 v2, v2, v208
	v_mul_f32_e32 v3, v3, v209
	v_mul_f32_e32 v4, v4, v210
	v_mul_f32_e32 v5, v5, v211
	v_mul_f32_e32 v2, v6, v2
	v_mul_f32_e32 v3, v7, v3
	v_mul_f32_e32 v4, v8, v4
	v_mul_f32_e32 v5, v9, v5
	v_cvt_pk_bf16_f32 v218, v2, v3
	v_cvt_pk_bf16_f32 v219, v4, v5
	v_mad_u32_u24 v40, v237, s29, v247
	s_and_saveexec_b64 s[30:31], s[26:27]
	global_store_dwordx2 v40, v[218:219], s[10:11] offset:8
	s_mov_b64 exec, s[30:31]
	s_branch .Lec_done
.Lec_edge:
	v_cmp_le_i32_e64 s[12:13], s54, v227
	v_cmp_gt_i32_e32 vcc, s55, v227
	s_and_b64 s[12:13], s[12:13], vcc
	v_add_u32_e32 v220, s48, v227
	v_cmp_gt_i32_e32 vcc, s93, v220
	s_and_b64 s[12:13], s[12:13], vcc
	v_cmp_le_i32_e64 s[14:15], s54, v231
	v_cmp_gt_i32_e32 vcc, s55, v231
	s_and_b64 s[14:15], s[14:15], vcc
	v_add_u32_e32 v220, s48, v231
	v_cmp_gt_i32_e32 vcc, s93, v220
	s_and_b64 s[14:15], s[14:15], vcc
	v_cmp_le_i32_e64 s[16:17], s54, v232
	v_cmp_gt_i32_e32 vcc, s55, v232
	s_and_b64 s[16:17], s[16:17], vcc
	v_add_u32_e32 v220, s48, v232
	v_cmp_gt_i32_e32 vcc, s93, v220
	s_and_b64 s[16:17], s[16:17], vcc
	v_cmp_le_i32_e64 s[18:19], s54, v233
	v_cmp_gt_i32_e32 vcc, s55, v233
	s_and_b64 s[18:19], s[18:19], vcc
	v_add_u32_e32 v220, s48, v233
	v_cmp_gt_i32_e32 vcc, s93, v220
	s_and_b64 s[18:19], s[18:19], vcc
	v_cmp_le_i32_e64 s[20:21], s54, v234
	v_cmp_gt_i32_e32 vcc, s55, v234
	s_and_b64 s[20:21], s[20:21], vcc
	v_add_u32_e32 v220, s48, v234
	v_cmp_gt_i32_e32 vcc, s93, v220
	s_and_b64 s[20:21], s[20:21], vcc
	v_cmp_le_i32_e64 s[22:23], s54, v235
	v_cmp_gt_i32_e32 vcc, s55, v235
	s_and_b64 s[22:23], s[22:23], vcc
	v_add_u32_e32 v220, s48, v235
	v_cmp_gt_i32_e32 vcc, s93, v220
	s_and_b64 s[22:23], s[22:23], vcc
	v_cmp_le_i32_e64 s[24:25], s54, v236
	v_cmp_gt_i32_e32 vcc, s55, v236
	s_and_b64 s[24:25], s[24:25], vcc
	v_add_u32_e32 v220, s48, v236
	v_cmp_gt_i32_e32 vcc, s93, v220
	s_and_b64 s[24:25], s[24:25], vcc
	v_cmp_le_i32_e64 s[26:27], s54, v237
	v_cmp_gt_i32_e32 vcc, s55, v237
	s_and_b64 s[26:27], s[26:27], vcc
	v_add_u32_e32 v220, s48, v237
	v_cmp_gt_i32_e32 vcc, s93, v220
	s_and_b64 s[26:27], s[26:27], vcc
	ds_write_b64 v243, v[166:167]
	ds_write_b64 v243, v[158:159] offset:256
	ds_write_b64 v243, v[150:151] offset:512
	ds_write_b64 v243, v[142:143] offset:768
	ds_read_b64 v[170:171], v244
	ds_read_b64 v[178:179], v243 offset:16
	ds_read_b64 v[198:199], v245
	ds_read_b64 v[172:173], v244 offset:256
	ds_read_b64 v[180:181], v243 offset:272
	ds_read_b64 v[174:175], v244 offset:512
	ds_read_b64 v[194:195], v243 offset:528
	ds_read_b64 v[176:177], v244 offset:768
	ds_read_b64 v[196:197], v243 offset:784
	ds_read_b64 v[200:201], v238 offset:2048
	s_waitcnt vmcnt(0)
; #define PG8_LAS __attribute__((address_space(3)))
; __device__ __forceinline__ float dpp_ror1(float v) { return __builtin_bit_cast(float, __builtin_amdgcn_update_dpp(0, __builtin_bit_cast(int, v), 0x121, 0xf, 0xf, false)); }
; __device__ __forceinline__ float dpp_ror15(float v) { return __builtin_bit_cast(float, __builtin_amdgcn_update_dpp(0, __builtin_bit_cast(int, v), 0x12F, 0xf, 0xf, false)); }
;     __device__ __forceinline__ void operator()(const f32x4 (&acc)[2][2][4][2], const Unit& u, int wr, int wc, int fr, int fq) const {
;     ...
;                 for (int m = 0; m < 4; ++m) { const int r = 128 * ai + 64 * wr + 16 * m + fr, t = tstart + r;
;                     const bool upok = t >= 1, dnok = (t + 1) < T, store_ok = (r >= vlo) && (r < vhi) && (t < T);
;                     f32x4 res[2];
; #pragma unroll
;                     for (int bj = 0; bj < 2; ++bj) { const f32x4 cur = acc[ai][bj][m][n];
;                         f32x4 su = cur, sd = cur;
;                         if (m > 0) { if (fr == 15) su = acc[ai][bj][m > 0 ? m - 1 : 0][n]; }
;                         if (m < 3) { if (fr == 0) sd = acc[ai][bj][m < 3 ? m + 1 : 3][n]; }
;                         f32x4 up, dn;
;                         up[0] = dpp_ror1(su[0]); up[1] = dpp_ror1(su[1]); up[2] = dpp_ror1(su[2]); up[3] = dpp_ror1(su[3]);
;                         dn[0] = dpp_ror15(sd[0]); dn[1] = dpp_ror15(sd[1]); dn[2] = dpp_ror15(sd[2]); dn[3] = dpp_ror15(sd[3]);
;                         if (m == 0) { f32x4 halo = zero4; if (blk > 0) halo = *(const PG8_LAS f32x4*)(xb + (((((blk - 1) * 2 + 1) * 4 + wc) * 4 + fq) * 16 + (bj * 2 + n) * 4)); if (fr == 0) up = halo; }
;                         if (m == 3) { f32x4 halo = zero4; if (blk < 3) halo = *(const PG8_LAS f32x4*)(xb + (((((blk + 1) * 2 + 0) * 4 + wc) * 4 + fq) * 16 + (bj * 2 + n) * 4)); if (fr == 15) dn = halo; }
;                         if (edge) { if (!upok) up = zero4; if (!dnok) dn = zero4; }
;                         res[bj] = bb[bj] + w0[bj] * up + w1[bj] * cur + w2[bj] * dn; }
	ds_write_b64 v243, v[168:169]
	ds_write_b64 v243, v[160:161] offset:256
	ds_write_b64 v243, v[152:153] offset:512
	ds_write_b64 v243, v[144:145] offset:768
	s_waitcnt lgkmcnt(11)
	v_cndmask_b32_e64 v170, v170, v198, s[6:7]
	v_cndmask_b32_e64 v171, v171, v199, s[6:7]
	v_add_u32_e32 v220, s48, v227
	v_cmp_lt_i32_e32 vcc, 0, v220
	s_nop 1
	v_cndmask_b32_e32 v170, 0, v170, vcc
	v_cndmask_b32_e32 v171, 0, v171, vcc
	v_cmp_gt_i32_e32 vcc, s28, v220
	s_nop 1
	v_cndmask_b32_e32 v178, 0, v178, vcc
	v_cndmask_b32_e32 v179, 0, v179, vcc
	v_pk_fma_f32 v[202:203], v[106:107], v[170:171], v[118:119]
	v_pk_fma_f32 v[166:167], v[166:167], v[110:111], v[202:203]
	v_pk_fma_f32 v[166:167], v[114:115], v[178:179], v[166:167]
	ds_read_b64 v[170:171], v244
	ds_read_b64 v[178:179], v243 offset:16
	ds_read_b64 v[198:199], v245 offset:8
	s_waitcnt lgkmcnt(12)
	v_add_u32_e32 v220, s48, v231
	v_cmp_lt_i32_e32 vcc, 0, v220
	s_nop 1
	v_cndmask_b32_e32 v172, 0, v172, vcc
	v_cndmask_b32_e32 v173, 0, v173, vcc
	v_cmp_gt_i32_e32 vcc, s28, v220
	s_nop 1
	v_cndmask_b32_e32 v180, 0, v180, vcc
	v_cndmask_b32_e32 v181, 0, v181, vcc
	v_pk_fma_f32 v[202:203], v[106:107], v[172:173], v[118:119]
	v_pk_fma_f32 v[158:159], v[158:159], v[110:111], v[202:203]
	v_pk_fma_f32 v[158:159], v[114:115], v[180:181], v[158:159]
	ds_read_b64 v[172:173], v244 offset:256
	ds_read_b64 v[180:181], v243 offset:272
	s_waitcnt lgkmcnt(12)
	v_add_u32_e32 v220, s48, v232
	v_cmp_lt_i32_e32 vcc, 0, v220
	s_nop 1
	v_cndmask_b32_e32 v174, 0, v174, vcc
	v_cndmask_b32_e32 v175, 0, v175, vcc
	v_cmp_gt_i32_e32 vcc, s28, v220
	s_nop 1
	v_cndmask_b32_e32 v194, 0, v194, vcc
	v_cndmask_b32_e32 v195, 0, v195, vcc
	v_pk_fma_f32 v[202:203], v[106:107], v[174:175], v[118:119]
	v_pk_fma_f32 v[150:151], v[150:151], v[110:111], v[202:203]
	v_pk_fma_f32 v[150:151], v[114:115], v[194:195], v[150:151]
	ds_read_b64 v[174:175], v244 offset:512
	ds_read_b64 v[194:195], v243 offset:528
	s_waitcnt lgkmcnt(11)
	v_cndmask_b32_e64 v196, v196, v200, s[4:5]
	v_cndmask_b32_e64 v197, v197, v201, s[4:5]
	v_add_u32_e32 v220, s48, v233
	v_cmp_lt_i32_e32 vcc, 0, v220
	s_nop 1
	v_cndmask_b32_e32 v176, 0, v176, vcc
	v_cndmask_b32_e32 v177, 0, v177, vcc
	v_cmp_gt_i32_e32 vcc, s28, v220
	s_nop 1
	v_cndmask_b32_e32 v196, 0, v196, vcc
	v_cndmask_b32_e32 v197, 0, v197, vcc
	v_pk_fma_f32 v[202:203], v[106:107], v[176:177], v[118:119]
	v_pk_fma_f32 v[142:143], v[142:143], v[110:111], v[202:203]
	v_pk_fma_f32 v[142:143], v[114:115], v[196:197], v[142:143]
	ds_read_b64 v[176:177], v244 offset:768
	ds_read_b64 v[196:197], v243 offset:784
	ds_read_b64 v[200:201], v238 offset:2056
	ds_write_b64 v243, v[162:163]
	ds_write_b64 v243, v[154:155] offset:256
	ds_write_b64 v243, v[146:147] offset:512
	ds_write_b64 v243, v[138:139] offset:768
	s_waitcnt lgkmcnt(11)
	v_cndmask_b32_e64 v170, v170, v198, s[6:7]
	v_cndmask_b32_e64 v171, v171, v199, s[6:7]
	v_add_u32_e32 v220, s48, v227
	v_cmp_lt_i32_e32 vcc, 0, v220
	s_nop 1
	v_cndmask_b32_e32 v170, 0, v170, vcc
	v_cndmask_b32_e32 v171, 0, v171, vcc
	v_cmp_gt_i32_e32 vcc, s28, v220
	s_nop 1
	v_cndmask_b32_e32 v178, 0, v178, vcc
	v_cndmask_b32_e32 v179, 0, v179, vcc
	v_pk_fma_f32 v[202:203], v[108:109], v[170:171], v[120:121]
	v_pk_fma_f32 v[168:169], v[168:169], v[112:113], v[202:203]
	v_pk_fma_f32 v[168:169], v[116:117], v[178:179], v[168:169]
	ds_read_b64 v[170:171], v244
	ds_read_b64 v[178:179], v243 offset:16
	ds_read_b64 v[198:199], v245 offset:32
	s_waitcnt lgkmcnt(12)
	v_add_u32_e32 v220, s48, v231
	v_cmp_lt_i32_e32 vcc, 0, v220
	s_nop 1
	v_cndmask_b32_e32 v172, 0, v172, vcc
	v_cndmask_b32_e32 v173, 0, v173, vcc
	v_cmp_gt_i32_e32 vcc, s28, v220
	s_nop 1
	v_cndmask_b32_e32 v180, 0, v180, vcc
	v_cndmask_b32_e32 v181, 0, v181, vcc
	v_pk_fma_f32 v[202:203], v[108:109], v[172:173], v[120:121]
	v_pk_fma_f32 v[160:161], v[160:161], v[112:113], v[202:203]
	v_pk_fma_f32 v[160:161], v[116:117], v[180:181], v[160:161]
	ds_read_b64 v[172:173], v244 offset:256
	ds_read_b64 v[180:181], v243 offset:272
	s_waitcnt lgkmcnt(12)
	v_add_u32_e32 v220, s48, v232
	v_cmp_lt_i32_e32 vcc, 0, v220
	s_nop 1
	v_cndmask_b32_e32 v174, 0, v174, vcc
	v_cndmask_b32_e32 v175, 0, v175, vcc
	v_cmp_gt_i32_e32 vcc, s28, v220
	s_nop 1
	v_cndmask_b32_e32 v194, 0, v194, vcc
	v_cndmask_b32_e32 v195, 0, v195, vcc
	v_pk_fma_f32 v[202:203], v[108:109], v[174:175], v[120:121]
	v_pk_fma_f32 v[152:153], v[152:153], v[112:113], v[202:203]
	v_pk_fma_f32 v[152:153], v[116:117], v[194:195], v[152:153]
	ds_read_b64 v[174:175], v244 offset:512
	ds_read_b64 v[194:195], v243 offset:528
	s_waitcnt lgkmcnt(11)
	v_cndmask_b32_e64 v196, v196, v200, s[4:5]
	v_cndmask_b32_e64 v197, v197, v201, s[4:5]
	v_add_u32_e32 v220, s48, v233
	v_cmp_lt_i32_e32 vcc, 0, v220
	s_nop 1
	v_cndmask_b32_e32 v176, 0, v176, vcc
	v_cndmask_b32_e32 v177, 0, v177, vcc
	v_cmp_gt_i32_e32 vcc, s28, v220
	s_nop 1
	v_cndmask_b32_e32 v196, 0, v196, vcc
	v_cndmask_b32_e32 v197, 0, v197, vcc
	v_pk_fma_f32 v[202:203], v[108:109], v[176:177], v[120:121]
	v_pk_fma_f32 v[144:145], v[144:145], v[112:113], v[202:203]
	v_pk_fma_f32 v[144:145], v[116:117], v[196:197], v[144:145]
	ds_read_b64 v[176:177], v244 offset:768
	ds_read_b64 v[196:197], v243 offset:784
	ds_read_b64 v[200:201], v238 offset:2080
	ds_write_b64 v243, v[164:165]
	ds_write_b64 v243, v[156:157] offset:256
	ds_write_b64 v243, v[148:149] offset:512
	ds_write_b64 v243, v[140:141] offset:768
	s_waitcnt lgkmcnt(11)
; #define PG8_LAS __attribute__((address_space(3)))
; __device__ __forceinline__ float dpp_ror1(float v) { return __builtin_bit_cast(float, __builtin_amdgcn_update_dpp(0, __builtin_bit_cast(int, v), 0x121, 0xf, 0xf, false)); }
; __device__ __forceinline__ float dpp_ror15(float v) { return __builtin_bit_cast(float, __builtin_amdgcn_update_dpp(0, __builtin_bit_cast(int, v), 0x12F, 0xf, 0xf, false)); }
;     __device__ __forceinline__ void operator()(const f32x4 (&acc)[2][2][4][2], const Unit& u, int wr, int wc, int fr, int fq) const {
;     ...
;                 for (int m = 0; m < 4; ++m) { const int r = 128 * ai + 64 * wr + 16 * m + fr, t = tstart + r;
;                     const bool upok = t >= 1, dnok = (t + 1) < T, store_ok = (r >= vlo) && (r < vhi) && (t < T);
;                     f32x4 res[2];
; #pragma unroll
;                     for (int bj = 0; bj < 2; ++bj) { const f32x4 cur = acc[ai][bj][m][n];
;                         f32x4 su = cur, sd = cur;
;                         if (m > 0) { if (fr == 15) su = acc[ai][bj][m > 0 ? m - 1 : 0][n]; }
;                         if (m < 3) { if (fr == 0) sd = acc[ai][bj][m < 3 ? m + 1 : 3][n]; }
;                         f32x4 up, dn;
;                         up[0] = dpp_ror1(su[0]); up[1] = dpp_ror1(su[1]); up[2] = dpp_ror1(su[2]); up[3] = dpp_ror1(su[3]);
;                         dn[0] = dpp_ror15(sd[0]); dn[1] = dpp_ror15(sd[1]); dn[2] = dpp_ror15(sd[2]); dn[3] = dpp_ror15(sd[3]);
;                         if (m == 0) { f32x4 halo = zero4; if (blk > 0) halo = *(const PG8_LAS f32x4*)(xb + (((((blk - 1) * 2 + 1) * 4 + wc) * 4 + fq) * 16 + (bj * 2 + n) * 4)); if (fr == 0) up = halo; }
;                         if (m == 3) { f32x4 halo = zero4; if (blk < 3) halo = *(const PG8_LAS f32x4*)(xb + (((((blk + 1) * 2 + 0) * 4 + wc) * 4 + fq) * 16 + (bj * 2 + n) * 4)); if (fr == 15) dn = halo; }
;                         if (edge) { if (!upok) up = zero4; if (!dnok) dn = zero4; }
;                         res[bj] = bb[bj] + w0[bj] * up + w1[bj] * cur + w2[bj] * dn; }
	v_cndmask_b32_e64 v170, v170, v198, s[6:7]
	v_cndmask_b32_e64 v171, v171, v199, s[6:7]
	v_add_u32_e32 v220, s48, v227
	v_cmp_lt_i32_e32 vcc, 0, v220
	s_nop 1
	v_cndmask_b32_e32 v170, 0, v170, vcc
	v_cndmask_b32_e32 v171, 0, v171, vcc
	v_cmp_gt_i32_e32 vcc, s28, v220
	s_nop 1
	v_cndmask_b32_e32 v178, 0, v178, vcc
	v_cndmask_b32_e32 v179, 0, v179, vcc
	v_pk_fma_f32 v[202:203], v[122:123], v[170:171], v[134:135]
	v_pk_fma_f32 v[162:163], v[162:163], v[126:127], v[202:203]
	v_pk_fma_f32 v[162:163], v[130:131], v[178:179], v[162:163]
	ds_read_b64 v[170:171], v244
	ds_read_b64 v[178:179], v243 offset:16
	ds_read_b64 v[198:199], v245 offset:40
	s_waitcnt lgkmcnt(12)
	v_add_u32_e32 v220, s48, v231
	v_cmp_lt_i32_e32 vcc, 0, v220
	s_nop 1
	v_cndmask_b32_e32 v172, 0, v172, vcc
	v_cndmask_b32_e32 v173, 0, v173, vcc
	v_cmp_gt_i32_e32 vcc, s28, v220
	s_nop 1
	v_cndmask_b32_e32 v180, 0, v180, vcc
	v_cndmask_b32_e32 v181, 0, v181, vcc
	v_pk_fma_f32 v[202:203], v[122:123], v[172:173], v[134:135]
	v_pk_fma_f32 v[154:155], v[154:155], v[126:127], v[202:203]
	v_pk_fma_f32 v[154:155], v[130:131], v[180:181], v[154:155]
	ds_read_b64 v[172:173], v244 offset:256
	ds_read_b64 v[180:181], v243 offset:272
	s_waitcnt lgkmcnt(12)
	v_add_u32_e32 v220, s48, v232
	v_cmp_lt_i32_e32 vcc, 0, v220
	s_nop 1
	v_cndmask_b32_e32 v174, 0, v174, vcc
	v_cndmask_b32_e32 v175, 0, v175, vcc
	v_cmp_gt_i32_e32 vcc, s28, v220
	s_nop 1
	v_cndmask_b32_e32 v194, 0, v194, vcc
	v_cndmask_b32_e32 v195, 0, v195, vcc
	v_pk_fma_f32 v[202:203], v[122:123], v[174:175], v[134:135]
	v_pk_fma_f32 v[146:147], v[146:147], v[126:127], v[202:203]
	v_pk_fma_f32 v[146:147], v[130:131], v[194:195], v[146:147]
	ds_read_b64 v[174:175], v244 offset:512
	ds_read_b64 v[194:195], v243 offset:528
	s_waitcnt lgkmcnt(11)
	v_cndmask_b32_e64 v196, v196, v200, s[4:5]
	v_cndmask_b32_e64 v197, v197, v201, s[4:5]
	v_add_u32_e32 v220, s48, v233
	v_cmp_lt_i32_e32 vcc, 0, v220
	s_nop 1
	v_cndmask_b32_e32 v176, 0, v176, vcc
	v_cndmask_b32_e32 v177, 0, v177, vcc
	v_cmp_gt_i32_e32 vcc, s28, v220
	s_nop 1
	v_cndmask_b32_e32 v196, 0, v196, vcc
	v_cndmask_b32_e32 v197, 0, v197, vcc
	v_pk_fma_f32 v[202:203], v[122:123], v[176:177], v[134:135]
	v_pk_fma_f32 v[138:139], v[138:139], v[126:127], v[202:203]
	v_pk_fma_f32 v[138:139], v[130:131], v[196:197], v[138:139]
	ds_read_b64 v[176:177], v244 offset:768
	ds_read_b64 v[196:197], v243 offset:784
	ds_read_b64 v[200:201], v238 offset:2088
	ds_write_b64 v243, v[102:103]
	ds_write_b64 v243, v[94:95] offset:256
	ds_write_b64 v243, v[86:87] offset:512
	ds_write_b64 v243, v[78:79] offset:768
	s_waitcnt lgkmcnt(11)
	v_cndmask_b32_e64 v170, v170, v198, s[6:7]
	v_cndmask_b32_e64 v171, v171, v199, s[6:7]
	v_add_u32_e32 v220, s48, v227
	v_cmp_lt_i32_e32 vcc, 0, v220
	s_nop 1
	v_cndmask_b32_e32 v170, 0, v170, vcc
	v_cndmask_b32_e32 v171, 0, v171, vcc
	v_cmp_gt_i32_e32 vcc, s28, v220
	s_nop 1
	v_cndmask_b32_e32 v178, 0, v178, vcc
	v_cndmask_b32_e32 v179, 0, v179, vcc
	v_pk_fma_f32 v[202:203], v[124:125], v[170:171], v[136:137]
	v_pk_fma_f32 v[164:165], v[164:165], v[128:129], v[202:203]
	v_pk_fma_f32 v[164:165], v[132:133], v[178:179], v[164:165]
	ds_read_b64 v[170:171], v244
	ds_read_b64 v[178:179], v243 offset:16
	ds_read_b64 v[198:199], v238 offset:3072
	s_waitcnt lgkmcnt(12)
	v_add_u32_e32 v220, s48, v231
	v_cmp_lt_i32_e32 vcc, 0, v220
	s_nop 1
	v_cndmask_b32_e32 v172, 0, v172, vcc
	v_cndmask_b32_e32 v173, 0, v173, vcc
	v_cmp_gt_i32_e32 vcc, s28, v220
	s_nop 1
	v_cndmask_b32_e32 v180, 0, v180, vcc
	v_cndmask_b32_e32 v181, 0, v181, vcc
	v_pk_fma_f32 v[202:203], v[124:125], v[172:173], v[136:137]
	v_pk_fma_f32 v[156:157], v[156:157], v[128:129], v[202:203]
	v_pk_fma_f32 v[156:157], v[132:133], v[180:181], v[156:157]
	ds_read_b64 v[172:173], v244 offset:256
	ds_read_b64 v[180:181], v243 offset:272
	s_waitcnt lgkmcnt(12)
	v_add_u32_e32 v220, s48, v232
	v_cmp_lt_i32_e32 vcc, 0, v220
	s_nop 1
	v_cndmask_b32_e32 v174, 0, v174, vcc
	v_cndmask_b32_e32 v175, 0, v175, vcc
	v_cmp_gt_i32_e32 vcc, s28, v220
	s_nop 1
	v_cndmask_b32_e32 v194, 0, v194, vcc
	v_cndmask_b32_e32 v195, 0, v195, vcc
	v_pk_fma_f32 v[202:203], v[124:125], v[174:175], v[136:137]
	v_pk_fma_f32 v[148:149], v[148:149], v[128:129], v[202:203]
	v_pk_fma_f32 v[148:149], v[132:133], v[194:195], v[148:149]
	ds_read_b64 v[174:175], v244 offset:512
	ds_read_b64 v[194:195], v243 offset:528
	s_waitcnt lgkmcnt(11)
; #define PG8_LAS __attribute__((address_space(3)))
;     __device__ __forceinline__ void operator()(const f32x4 (&acc)[2][2][4][2], const Unit& u, int wr, int wc, int fr, int fq) const {
;     ...
;         for (int n = 0; n < 2; ++n) {
;             if (n == 1) {
; #pragma unroll
;                 for (int bj = 0; bj < 2; ++bj) { const int col = bj * 2816 + ch0 + 4;
;                     w0[bj] = *(const f32x4*)(cw + col); w1[bj] = *(const f32x4*)(cw + 5632 + col); w2[bj] = *(const f32x4*)(cw + 11264 + col); bb[bj] = *(const f32x4*)(cb + col); } }
; #pragma unroll
;             for (int ai = 0; ai < 2; ++ai) { const int blk = ai * 2 + wr;
; #pragma unroll
;                 for (int m = 0; m < 4; ++m) { const int r = 128 * ai + 64 * wr + 16 * m + fr, t = tstart + r;
;                     const bool upok = t >= 1, dnok = (t + 1) < T, store_ok = (r >= vlo) && (r < vhi) && (t < T);
;                     f32x4 res[2];
; #pragma unroll
;                     for (int bj = 0; bj < 2; ++bj) { const f32x4 cur = acc[ai][bj][m][n];
;                         f32x4 su = cur, sd = cur;
;                         if (m > 0) { if (fr == 15) su = acc[ai][bj][m > 0 ? m - 1 : 0][n]; }
;                         if (m < 3) { if (fr == 0) sd = acc[ai][bj][m < 3 ? m + 1 : 3][n]; }
;                         f32x4 up, dn;
;                         up[0] = dpp_ror1(su[0]); up[1] = dpp_ror1(su[1]); up[2] = dpp_ror1(su[2]); up[3] = dpp_ror1(su[3]);
;                         dn[0] = dpp_ror15(sd[0]); dn[1] = dpp_ror15(sd[1]); dn[2] = dpp_ror15(sd[2]); dn[3] = dpp_ror15(sd[3]);
;                         if (m == 0) { f32x4 halo = zero4; if (blk > 0) halo = *(const PG8_LAS f32x4*)(xb + (((((blk - 1) * 2 + 1) * 4 + wc) * 4 + fq) * 16 + (bj * 2 + n) * 4)); if (fr == 0) up = halo; }
;                         if (m == 3) { f32x4 halo = zero4; if (blk < 3) halo = *(const PG8_LAS f32x4*)(xb + (((((blk + 1) * 2 + 0) * 4 + wc) * 4 + fq) * 16 + (bj * 2 + n) * 4)); if (fr == 15) dn = halo; }
;                         if (edge) { if (!upok) up = zero4; if (!dnok) dn = zero4; }
;                         res[bj] = bb[bj] + w0[bj] * up + w1[bj] * cur + w2[bj] * dn; }
;                     if (store_ok) {
;                         float o[4];
; #pragma unroll
;                         for (int j = 0; j < 4; ++j) { const float gg = res[1][j]; o[j] = gg * __builtin_amdgcn_rcpf(1.f + __expf(-gg)) * res[0][j]; }
	v_cndmask_b32_e64 v196, v196, v200, s[4:5]
	v_cndmask_b32_e64 v197, v197, v201, s[4:5]
	v_add_u32_e32 v220, s48, v233
	v_cmp_lt_i32_e32 vcc, 0, v220
	s_nop 1
	v_cndmask_b32_e32 v176, 0, v176, vcc
	v_cndmask_b32_e32 v177, 0, v177, vcc
	v_cmp_gt_i32_e32 vcc, s28, v220
	s_nop 1
	v_cndmask_b32_e32 v196, 0, v196, vcc
	v_cndmask_b32_e32 v197, 0, v197, vcc
	v_pk_fma_f32 v[202:203], v[124:125], v[176:177], v[136:137]
	v_pk_fma_f32 v[140:141], v[140:141], v[128:129], v[202:203]
	v_pk_fma_f32 v[140:141], v[132:133], v[196:197], v[140:141]
	ds_read_b64 v[176:177], v244 offset:768
	ds_read_b64 v[196:197], v243 offset:784
	ds_read_b64 v[200:201], v246
	v_mul_f32_e32 v208, 0xbfb8aa3b, v162
	v_mul_f32_e32 v209, 0xbfb8aa3b, v163
	v_mul_f32_e32 v210, 0xbfb8aa3b, v164
	v_mul_f32_e32 v211, 0xbfb8aa3b, v165
	v_exp_f32_e32 v208, v208
	v_exp_f32_e32 v209, v209
	v_exp_f32_e32 v210, v210
	v_exp_f32_e32 v211, v211
	v_add_f32_e32 v208, 1.0, v208
	v_add_f32_e32 v209, 1.0, v209
	v_add_f32_e32 v210, 1.0, v210
	v_add_f32_e32 v211, 1.0, v211
	v_rcp_f32_e32 v208, v208
	v_rcp_f32_e32 v209, v209
	v_rcp_f32_e32 v210, v210
	v_rcp_f32_e32 v211, v211
	v_mul_f32_e32 v162, v162, v208
	v_mul_f32_e32 v163, v163, v209
	v_mul_f32_e32 v164, v164, v210
	v_mul_f32_e32 v165, v165, v211
	v_mul_f32_e32 v162, v166, v162
	v_mul_f32_e32 v163, v167, v163
	v_mul_f32_e32 v164, v168, v164
	v_mul_f32_e32 v165, v169, v165
	v_cvt_pk_bf16_f32 v212, v162, v163
	v_cvt_pk_bf16_f32 v213, v164, v165
	v_mad_u32_u24 v221, v227, s29, v247
	s_and_saveexec_b64 s[30:31], s[12:13]
	global_store_dwordx2 v221, v[212:213], s[10:11]
	s_mov_b64 exec, s[30:31]
	v_mul_f32_e32 v208, 0xbfb8aa3b, v154
	v_mul_f32_e32 v209, 0xbfb8aa3b, v155
	v_mul_f32_e32 v210, 0xbfb8aa3b, v156
	v_mul_f32_e32 v211, 0xbfb8aa3b, v157
	v_exp_f32_e32 v208, v208
	v_exp_f32_e32 v209, v209
	v_exp_f32_e32 v210, v210
	v_exp_f32_e32 v211, v211
	v_add_f32_e32 v208, 1.0, v208
	v_add_f32_e32 v209, 1.0, v209
	v_add_f32_e32 v210, 1.0, v210
	v_add_f32_e32 v211, 1.0, v211
	v_rcp_f32_e32 v208, v208
	v_rcp_f32_e32 v209, v209
	v_rcp_f32_e32 v210, v210
	v_rcp_f32_e32 v211, v211
	v_mul_f32_e32 v154, v154, v208
	v_mul_f32_e32 v155, v155, v209
	v_mul_f32_e32 v156, v156, v210
	v_mul_f32_e32 v157, v157, v211
	v_mul_f32_e32 v154, v158, v154
	v_mul_f32_e32 v155, v159, v155
	v_mul_f32_e32 v156, v160, v156
	v_mul_f32_e32 v157, v161, v157
	v_cvt_pk_bf16_f32 v218, v154, v155
	v_cvt_pk_bf16_f32 v219, v156, v157
	v_mad_u32_u24 v40, v231, s29, v247
	s_and_saveexec_b64 s[30:31], s[14:15]
	global_store_dwordx2 v40, v[218:219], s[10:11]
	s_mov_b64 exec, s[30:31]
	v_mul_f32_e32 v208, 0xbfb8aa3b, v146
	v_mul_f32_e32 v209, 0xbfb8aa3b, v147
	v_mul_f32_e32 v210, 0xbfb8aa3b, v148
	v_mul_f32_e32 v211, 0xbfb8aa3b, v149
	v_exp_f32_e32 v208, v208
	v_exp_f32_e32 v209, v209
	v_exp_f32_e32 v210, v210
	v_exp_f32_e32 v211, v211
	v_add_f32_e32 v208, 1.0, v208
	v_add_f32_e32 v209, 1.0, v209
	v_add_f32_e32 v210, 1.0, v210
	v_add_f32_e32 v211, 1.0, v211
	v_rcp_f32_e32 v208, v208
	v_rcp_f32_e32 v209, v209
	v_rcp_f32_e32 v210, v210
	v_rcp_f32_e32 v211, v211
	v_mul_f32_e32 v146, v146, v208
	v_mul_f32_e32 v147, v147, v209
	v_mul_f32_e32 v148, v148, v210
	v_mul_f32_e32 v149, v149, v211
	v_mul_f32_e32 v146, v150, v146
	v_mul_f32_e32 v147, v151, v147
	v_mul_f32_e32 v148, v152, v148
	v_mul_f32_e32 v149, v153, v149
	v_cvt_pk_bf16_f32 v212, v146, v147
	v_cvt_pk_bf16_f32 v213, v148, v149
	v_mad_u32_u24 v221, v232, s29, v247
	s_and_saveexec_b64 s[30:31], s[16:17]
	global_store_dwordx2 v221, v[212:213], s[10:11]
	s_mov_b64 exec, s[30:31]
	v_mul_f32_e32 v208, 0xbfb8aa3b, v138
	v_mul_f32_e32 v209, 0xbfb8aa3b, v139
	v_mul_f32_e32 v210, 0xbfb8aa3b, v140
	v_mul_f32_e32 v211, 0xbfb8aa3b, v141
	v_exp_f32_e32 v208, v208
	v_exp_f32_e32 v209, v209
	v_exp_f32_e32 v210, v210
	v_exp_f32_e32 v211, v211
	v_add_f32_e32 v208, 1.0, v208
	v_add_f32_e32 v209, 1.0, v209
	v_add_f32_e32 v210, 1.0, v210
	v_add_f32_e32 v211, 1.0, v211
	v_rcp_f32_e32 v208, v208
	v_rcp_f32_e32 v209, v209
	v_rcp_f32_e32 v210, v210
	v_rcp_f32_e32 v211, v211
	v_mul_f32_e32 v138, v138, v208
	v_mul_f32_e32 v139, v139, v209
	v_mul_f32_e32 v140, v140, v210
	v_mul_f32_e32 v141, v141, v211
	v_mul_f32_e32 v138, v142, v138
	v_mul_f32_e32 v139, v143, v139
	v_mul_f32_e32 v140, v144, v140
	v_mul_f32_e32 v141, v145, v141
	v_cvt_pk_bf16_f32 v218, v138, v139
	v_cvt_pk_bf16_f32 v219, v140, v141
	v_mad_u32_u24 v40, v233, s29, v247
	s_and_saveexec_b64 s[30:31], s[18:19]
	global_store_dwordx2 v40, v[218:219], s[10:11]
	s_mov_b64 exec, s[30:31]
	global_load_dwordx4 v[138:141], v248, s[62:63] offset:16
	global_load_dwordx4 v[142:145], v248, s[66:67] offset:16
	global_load_dwordx4 v[146:149], v248, s[68:69] offset:16
	global_load_dwordx4 v[150:153], v248, s[64:65] offset:16
	global_load_dwordx4 v[154:157], v249, s[62:63] offset:16
	global_load_dwordx4 v[158:161], v249, s[66:67] offset:16
	global_load_dwordx4 v[162:165], v249, s[68:69] offset:16
	global_load_dwordx4 v[166:169], v249, s[64:65] offset:16
	ds_write_b64 v243, v[104:105]
	ds_write_b64 v243, v[96:97] offset:256
	ds_write_b64 v243, v[88:89] offset:512
	ds_write_b64 v243, v[80:81] offset:768
	s_waitcnt lgkmcnt(11)
	v_cndmask_b32_e64 v170, v170, v198, s[6:7]
	v_cndmask_b32_e64 v171, v171, v199, s[6:7]
	v_add_u32_e32 v220, s48, v234
	v_cmp_lt_i32_e32 vcc, 0, v220
	s_nop 1
	v_cndmask_b32_e32 v170, 0, v170, vcc
	v_cndmask_b32_e32 v171, 0, v171, vcc
	v_cmp_gt_i32_e32 vcc, s28, v220
	s_nop 1
	v_cndmask_b32_e32 v178, 0, v178, vcc
	v_cndmask_b32_e32 v179, 0, v179, vcc
	v_pk_fma_f32 v[202:203], v[106:107], v[170:171], v[118:119]
	v_pk_fma_f32 v[102:103], v[102:103], v[110:111], v[202:203]
	v_pk_fma_f32 v[102:103], v[114:115], v[178:179], v[102:103]
	ds_read_b64 v[170:171], v244
	ds_read_b64 v[178:179], v243 offset:16
	ds_read_b64 v[198:199], v238 offset:3080
	s_waitcnt lgkmcnt(12)
; #define PG8_LAS __attribute__((address_space(3)))
; __device__ __forceinline__ float dpp_ror1(float v) { return __builtin_bit_cast(float, __builtin_amdgcn_update_dpp(0, __builtin_bit_cast(int, v), 0x121, 0xf, 0xf, false)); }
; __device__ __forceinline__ float dpp_ror15(float v) { return __builtin_bit_cast(float, __builtin_amdgcn_update_dpp(0, __builtin_bit_cast(int, v), 0x12F, 0xf, 0xf, false)); }
;     __device__ __forceinline__ void operator()(const f32x4 (&acc)[2][2][4][2], const Unit& u, int wr, int wc, int fr, int fq) const {
;     ...
;                 for (int m = 0; m < 4; ++m) { const int r = 128 * ai + 64 * wr + 16 * m + fr, t = tstart + r;
;                     const bool upok = t >= 1, dnok = (t + 1) < T, store_ok = (r >= vlo) && (r < vhi) && (t < T);
;                     f32x4 res[2];
; #pragma unroll
;                     for (int bj = 0; bj < 2; ++bj) { const f32x4 cur = acc[ai][bj][m][n];
;                         f32x4 su = cur, sd = cur;
;                         if (m > 0) { if (fr == 15) su = acc[ai][bj][m > 0 ? m - 1 : 0][n]; }
;                         if (m < 3) { if (fr == 0) sd = acc[ai][bj][m < 3 ? m + 1 : 3][n]; }
;                         f32x4 up, dn;
;                         up[0] = dpp_ror1(su[0]); up[1] = dpp_ror1(su[1]); up[2] = dpp_ror1(su[2]); up[3] = dpp_ror1(su[3]);
;                         dn[0] = dpp_ror15(sd[0]); dn[1] = dpp_ror15(sd[1]); dn[2] = dpp_ror15(sd[2]); dn[3] = dpp_ror15(sd[3]);
;                         if (m == 0) { f32x4 halo = zero4; if (blk > 0) halo = *(const PG8_LAS f32x4*)(xb + (((((blk - 1) * 2 + 1) * 4 + wc) * 4 + fq) * 16 + (bj * 2 + n) * 4)); if (fr == 0) up = halo; }
;                         if (m == 3) { f32x4 halo = zero4; if (blk < 3) halo = *(const PG8_LAS f32x4*)(xb + (((((blk + 1) * 2 + 0) * 4 + wc) * 4 + fq) * 16 + (bj * 2 + n) * 4)); if (fr == 15) dn = halo; }
;                         if (edge) { if (!upok) up = zero4; if (!dnok) dn = zero4; }
;                         res[bj] = bb[bj] + w0[bj] * up + w1[bj] * cur + w2[bj] * dn; }
	v_add_u32_e32 v220, s48, v235
	v_cmp_lt_i32_e32 vcc, 0, v220
	s_nop 1
	v_cndmask_b32_e32 v172, 0, v172, vcc
	v_cndmask_b32_e32 v173, 0, v173, vcc
	v_cmp_gt_i32_e32 vcc, s28, v220
	s_nop 1
	v_cndmask_b32_e32 v180, 0, v180, vcc
	v_cndmask_b32_e32 v181, 0, v181, vcc
	v_pk_fma_f32 v[202:203], v[106:107], v[172:173], v[118:119]
	v_pk_fma_f32 v[94:95], v[94:95], v[110:111], v[202:203]
	v_pk_fma_f32 v[94:95], v[114:115], v[180:181], v[94:95]
	ds_read_b64 v[172:173], v244 offset:256
	ds_read_b64 v[180:181], v243 offset:272
	s_waitcnt lgkmcnt(12)
	v_add_u32_e32 v220, s48, v236
	v_cmp_lt_i32_e32 vcc, 0, v220
	s_nop 1
	v_cndmask_b32_e32 v174, 0, v174, vcc
	v_cndmask_b32_e32 v175, 0, v175, vcc
	v_cmp_gt_i32_e32 vcc, s28, v220
	s_nop 1
	v_cndmask_b32_e32 v194, 0, v194, vcc
	v_cndmask_b32_e32 v195, 0, v195, vcc
	v_pk_fma_f32 v[202:203], v[106:107], v[174:175], v[118:119]
	v_pk_fma_f32 v[86:87], v[86:87], v[110:111], v[202:203]
	v_pk_fma_f32 v[86:87], v[114:115], v[194:195], v[86:87]
	ds_read_b64 v[174:175], v244 offset:512
	ds_read_b64 v[194:195], v243 offset:528
	s_waitcnt lgkmcnt(11)
	v_cndmask_b32_e64 v196, v196, v200, s[4:5]
	v_cndmask_b32_e64 v197, v197, v201, s[4:5]
	v_add_u32_e32 v220, s48, v237
	v_cmp_lt_i32_e32 vcc, 0, v220
	s_nop 1
	v_cndmask_b32_e32 v176, 0, v176, vcc
	v_cndmask_b32_e32 v177, 0, v177, vcc
	v_cmp_gt_i32_e32 vcc, s28, v220
	s_nop 1
	v_cndmask_b32_e32 v196, 0, v196, vcc
	v_cndmask_b32_e32 v197, 0, v197, vcc
	v_pk_fma_f32 v[202:203], v[106:107], v[176:177], v[118:119]
	v_pk_fma_f32 v[78:79], v[78:79], v[110:111], v[202:203]
	v_pk_fma_f32 v[78:79], v[114:115], v[196:197], v[78:79]
	ds_read_b64 v[176:177], v244 offset:768
	ds_read_b64 v[196:197], v243 offset:784
	ds_read_b64 v[200:201], v246 offset:8
	ds_write_b64 v243, v[98:99]
	ds_write_b64 v243, v[90:91] offset:256
	ds_write_b64 v243, v[82:83] offset:512
	ds_write_b64 v243, v[74:75] offset:768
	s_waitcnt lgkmcnt(11)
	v_cndmask_b32_e64 v170, v170, v198, s[6:7]
	v_cndmask_b32_e64 v171, v171, v199, s[6:7]
	v_add_u32_e32 v220, s48, v234
	v_cmp_lt_i32_e32 vcc, 0, v220
	s_nop 1
	v_cndmask_b32_e32 v170, 0, v170, vcc
	v_cndmask_b32_e32 v171, 0, v171, vcc
	v_cmp_gt_i32_e32 vcc, s28, v220
	s_nop 1
	v_cndmask_b32_e32 v178, 0, v178, vcc
	v_cndmask_b32_e32 v179, 0, v179, vcc
	v_pk_fma_f32 v[202:203], v[108:109], v[170:171], v[120:121]
	v_pk_fma_f32 v[104:105], v[104:105], v[112:113], v[202:203]
	v_pk_fma_f32 v[104:105], v[116:117], v[178:179], v[104:105]
	ds_read_b64 v[170:171], v244
	ds_read_b64 v[178:179], v243 offset:16
	ds_read_b64 v[198:199], v238 offset:3104
	s_waitcnt lgkmcnt(12)
	v_add_u32_e32 v220, s48, v235
	v_cmp_lt_i32_e32 vcc, 0, v220
	s_nop 1
	v_cndmask_b32_e32 v172, 0, v172, vcc
	v_cndmask_b32_e32 v173, 0, v173, vcc
	v_cmp_gt_i32_e32 vcc, s28, v220
	s_nop 1
	v_cndmask_b32_e32 v180, 0, v180, vcc
	v_cndmask_b32_e32 v181, 0, v181, vcc
	v_pk_fma_f32 v[202:203], v[108:109], v[172:173], v[120:121]
	v_pk_fma_f32 v[96:97], v[96:97], v[112:113], v[202:203]
	v_pk_fma_f32 v[96:97], v[116:117], v[180:181], v[96:97]
	ds_read_b64 v[172:173], v244 offset:256
	ds_read_b64 v[180:181], v243 offset:272
	s_waitcnt lgkmcnt(12)
	v_add_u32_e32 v220, s48, v236
	v_cmp_lt_i32_e32 vcc, 0, v220
	s_nop 1
	v_cndmask_b32_e32 v174, 0, v174, vcc
	v_cndmask_b32_e32 v175, 0, v175, vcc
	v_cmp_gt_i32_e32 vcc, s28, v220
	s_nop 1
	v_cndmask_b32_e32 v194, 0, v194, vcc
	v_cndmask_b32_e32 v195, 0, v195, vcc
	v_pk_fma_f32 v[202:203], v[108:109], v[174:175], v[120:121]
	v_pk_fma_f32 v[88:89], v[88:89], v[112:113], v[202:203]
	v_pk_fma_f32 v[88:89], v[116:117], v[194:195], v[88:89]
	ds_read_b64 v[174:175], v244 offset:512
	ds_read_b64 v[194:195], v243 offset:528
	s_waitcnt lgkmcnt(11)
	v_cndmask_b32_e64 v196, v196, v200, s[4:5]
	v_cndmask_b32_e64 v197, v197, v201, s[4:5]
	v_add_u32_e32 v220, s48, v237
	v_cmp_lt_i32_e32 vcc, 0, v220
	s_nop 1
	v_cndmask_b32_e32 v176, 0, v176, vcc
	v_cndmask_b32_e32 v177, 0, v177, vcc
	v_cmp_gt_i32_e32 vcc, s28, v220
	s_nop 1
	v_cndmask_b32_e32 v196, 0, v196, vcc
	v_cndmask_b32_e32 v197, 0, v197, vcc
	v_pk_fma_f32 v[202:203], v[108:109], v[176:177], v[120:121]
	v_pk_fma_f32 v[80:81], v[80:81], v[112:113], v[202:203]
	v_pk_fma_f32 v[80:81], v[116:117], v[196:197], v[80:81]
	ds_read_b64 v[176:177], v244 offset:768
	ds_read_b64 v[196:197], v243 offset:784
	ds_read_b64 v[200:201], v246 offset:32
	ds_write_b64 v243, v[100:101]
	ds_write_b64 v243, v[92:93] offset:256
	ds_write_b64 v243, v[84:85] offset:512
	ds_write_b64 v243, v[76:77] offset:768
	s_waitcnt lgkmcnt(11)
	v_cndmask_b32_e64 v170, v170, v198, s[6:7]
	v_cndmask_b32_e64 v171, v171, v199, s[6:7]
	v_add_u32_e32 v220, s48, v234
	v_cmp_lt_i32_e32 vcc, 0, v220
	s_nop 1
	v_cndmask_b32_e32 v170, 0, v170, vcc
	v_cndmask_b32_e32 v171, 0, v171, vcc
	v_cmp_gt_i32_e32 vcc, s28, v220
	s_nop 1
	v_cndmask_b32_e32 v178, 0, v178, vcc
	v_cndmask_b32_e32 v179, 0, v179, vcc
	v_pk_fma_f32 v[202:203], v[122:123], v[170:171], v[134:135]
	v_pk_fma_f32 v[98:99], v[98:99], v[126:127], v[202:203]
	v_pk_fma_f32 v[98:99], v[130:131], v[178:179], v[98:99]
	ds_read_b64 v[170:171], v244
	ds_read_b64 v[178:179], v243 offset:16
	ds_read_b64 v[198:199], v238 offset:3112
	s_waitcnt lgkmcnt(12)
	v_add_u32_e32 v220, s48, v235
	v_cmp_lt_i32_e32 vcc, 0, v220
	s_nop 1
	v_cndmask_b32_e32 v172, 0, v172, vcc
	v_cndmask_b32_e32 v173, 0, v173, vcc
	v_cmp_gt_i32_e32 vcc, s28, v220
	s_nop 1
	v_cndmask_b32_e32 v180, 0, v180, vcc
	v_cndmask_b32_e32 v181, 0, v181, vcc
	v_pk_fma_f32 v[202:203], v[122:123], v[172:173], v[134:135]
	v_pk_fma_f32 v[90:91], v[90:91], v[126:127], v[202:203]
	v_pk_fma_f32 v[90:91], v[130:131], v[180:181], v[90:91]
	ds_read_b64 v[172:173], v244 offset:256
	ds_read_b64 v[180:181], v243 offset:272
	s_waitcnt lgkmcnt(12)
; #define PG8_LAS __attribute__((address_space(3)))
; __device__ __forceinline__ unsigned cvt_pk_bf16(float lo, float hi) { unsigned r; asm volatile("v_cvt_pk_bf16_f32 %0, %1, %2" : "=v"(r) : "v"(lo), "v"(hi)); return r; }
;     __device__ __forceinline__ void operator()(const f32x4 (&acc)[2][2][4][2], const Unit& u, int wr, int wc, int fr, int fq) const {
;     ...
;                 for (int m = 0; m < 4; ++m) { const int r = 128 * ai + 64 * wr + 16 * m + fr, t = tstart + r;
;                     const bool upok = t >= 1, dnok = (t + 1) < T, store_ok = (r >= vlo) && (r < vhi) && (t < T);
;                     f32x4 res[2];
; #pragma unroll
;                     for (int bj = 0; bj < 2; ++bj) { const f32x4 cur = acc[ai][bj][m][n];
;                         f32x4 su = cur, sd = cur;
;                         if (m > 0) { if (fr == 15) su = acc[ai][bj][m > 0 ? m - 1 : 0][n]; }
;                         if (m < 3) { if (fr == 0) sd = acc[ai][bj][m < 3 ? m + 1 : 3][n]; }
;                         f32x4 up, dn;
;                         up[0] = dpp_ror1(su[0]); up[1] = dpp_ror1(su[1]); up[2] = dpp_ror1(su[2]); up[3] = dpp_ror1(su[3]);
;                         dn[0] = dpp_ror15(sd[0]); dn[1] = dpp_ror15(sd[1]); dn[2] = dpp_ror15(sd[2]); dn[3] = dpp_ror15(sd[3]);
;                         if (m == 0) { f32x4 halo = zero4; if (blk > 0) halo = *(const PG8_LAS f32x4*)(xb + (((((blk - 1) * 2 + 1) * 4 + wc) * 4 + fq) * 16 + (bj * 2 + n) * 4)); if (fr == 0) up = halo; }
;                         if (m == 3) { f32x4 halo = zero4; if (blk < 3) halo = *(const PG8_LAS f32x4*)(xb + (((((blk + 1) * 2 + 0) * 4 + wc) * 4 + fq) * 16 + (bj * 2 + n) * 4)); if (fr == 15) dn = halo; }
;                         if (edge) { if (!upok) up = zero4; if (!dnok) dn = zero4; }
;                         res[bj] = bb[bj] + w0[bj] * up + w1[bj] * cur + w2[bj] * dn; }
;                     if (store_ok) {
;                         float o[4];
; #pragma unroll
;                         for (int j = 0; j < 4; ++j) { const float gg = res[1][j]; o[j] = gg * __builtin_amdgcn_rcpf(1.f + __expf(-gg)) * res[0][j]; }
;                         u32x2 w; w.x = cvt_pk_bf16(o[0], o[1]); w.y = cvt_pk_bf16(o[2], o[3]);
;                         *(u32x2*)(ACT + (size_t)(seqrow + t) * 2816 + ch0 + 4 * n) = w; } } }
	v_add_u32_e32 v220, s48, v236
	v_cmp_lt_i32_e32 vcc, 0, v220
	s_nop 1
	v_cndmask_b32_e32 v174, 0, v174, vcc
	v_cndmask_b32_e32 v175, 0, v175, vcc
	v_cmp_gt_i32_e32 vcc, s28, v220
	s_nop 1
	v_cndmask_b32_e32 v194, 0, v194, vcc
	v_cndmask_b32_e32 v195, 0, v195, vcc
	v_pk_fma_f32 v[202:203], v[122:123], v[174:175], v[134:135]
	v_pk_fma_f32 v[82:83], v[82:83], v[126:127], v[202:203]
	v_pk_fma_f32 v[82:83], v[130:131], v[194:195], v[82:83]
	ds_read_b64 v[174:175], v244 offset:512
	ds_read_b64 v[194:195], v243 offset:528
	s_waitcnt lgkmcnt(11)
	v_cndmask_b32_e64 v196, v196, v200, s[4:5]
	v_cndmask_b32_e64 v197, v197, v201, s[4:5]
	v_add_u32_e32 v220, s48, v237
	v_cmp_lt_i32_e32 vcc, 0, v220
	s_nop 1
	v_cndmask_b32_e32 v176, 0, v176, vcc
	v_cndmask_b32_e32 v177, 0, v177, vcc
	v_cmp_gt_i32_e32 vcc, s28, v220
	s_nop 1
	v_cndmask_b32_e32 v196, 0, v196, vcc
	v_cndmask_b32_e32 v197, 0, v197, vcc
	v_pk_fma_f32 v[202:203], v[122:123], v[176:177], v[134:135]
	v_pk_fma_f32 v[74:75], v[74:75], v[126:127], v[202:203]
	v_pk_fma_f32 v[74:75], v[130:131], v[196:197], v[74:75]
	ds_read_b64 v[176:177], v244 offset:768
	ds_read_b64 v[196:197], v243 offset:784
	ds_read_b64 v[200:201], v246 offset:40
	ds_write_b64 v243, v[70:71]
	ds_write_b64 v243, v[62:63] offset:256
	ds_write_b64 v243, v[54:55] offset:512
	ds_write_b64 v243, v[46:47] offset:768
	s_waitcnt lgkmcnt(11)
	v_cndmask_b32_e64 v170, v170, v198, s[6:7]
	v_cndmask_b32_e64 v171, v171, v199, s[6:7]
	v_add_u32_e32 v220, s48, v234
	v_cmp_lt_i32_e32 vcc, 0, v220
	s_nop 1
	v_cndmask_b32_e32 v170, 0, v170, vcc
	v_cndmask_b32_e32 v171, 0, v171, vcc
	v_cmp_gt_i32_e32 vcc, s28, v220
	s_nop 1
	v_cndmask_b32_e32 v178, 0, v178, vcc
	v_cndmask_b32_e32 v179, 0, v179, vcc
	v_pk_fma_f32 v[202:203], v[124:125], v[170:171], v[136:137]
	v_pk_fma_f32 v[100:101], v[100:101], v[128:129], v[202:203]
	v_pk_fma_f32 v[100:101], v[132:133], v[178:179], v[100:101]
	ds_read_b64 v[170:171], v244
	ds_read_b64 v[178:179], v243 offset:16
	ds_read_b64 v[198:199], v245 offset:16
	s_waitcnt lgkmcnt(12)
	v_add_u32_e32 v220, s48, v235
	v_cmp_lt_i32_e32 vcc, 0, v220
	s_nop 1
	v_cndmask_b32_e32 v172, 0, v172, vcc
	v_cndmask_b32_e32 v173, 0, v173, vcc
	v_cmp_gt_i32_e32 vcc, s28, v220
	s_nop 1
	v_cndmask_b32_e32 v180, 0, v180, vcc
	v_cndmask_b32_e32 v181, 0, v181, vcc
	v_pk_fma_f32 v[202:203], v[124:125], v[172:173], v[136:137]
	v_pk_fma_f32 v[92:93], v[92:93], v[128:129], v[202:203]
	v_pk_fma_f32 v[92:93], v[132:133], v[180:181], v[92:93]
	ds_read_b64 v[172:173], v244 offset:256
	ds_read_b64 v[180:181], v243 offset:272
	s_waitcnt lgkmcnt(12)
	v_add_u32_e32 v220, s48, v236
	v_cmp_lt_i32_e32 vcc, 0, v220
	s_nop 1
	v_cndmask_b32_e32 v174, 0, v174, vcc
	v_cndmask_b32_e32 v175, 0, v175, vcc
	v_cmp_gt_i32_e32 vcc, s28, v220
	s_nop 1
	v_cndmask_b32_e32 v194, 0, v194, vcc
	v_cndmask_b32_e32 v195, 0, v195, vcc
	v_pk_fma_f32 v[202:203], v[124:125], v[174:175], v[136:137]
	v_pk_fma_f32 v[84:85], v[84:85], v[128:129], v[202:203]
	v_pk_fma_f32 v[84:85], v[132:133], v[194:195], v[84:85]
	ds_read_b64 v[174:175], v244 offset:512
	ds_read_b64 v[194:195], v243 offset:528
	s_waitcnt lgkmcnt(11)
	v_cndmask_b32_e64 v196, v196, v200, s[4:5]
	v_cndmask_b32_e64 v197, v197, v201, s[4:5]
	v_add_u32_e32 v220, s48, v237
	v_cmp_lt_i32_e32 vcc, 0, v220
	s_nop 1
	v_cndmask_b32_e32 v176, 0, v176, vcc
	v_cndmask_b32_e32 v177, 0, v177, vcc
	v_cmp_gt_i32_e32 vcc, s28, v220
	s_nop 1
	v_cndmask_b32_e32 v196, 0, v196, vcc
	v_cndmask_b32_e32 v197, 0, v197, vcc
	v_pk_fma_f32 v[202:203], v[124:125], v[176:177], v[136:137]
	v_pk_fma_f32 v[76:77], v[76:77], v[128:129], v[202:203]
	v_pk_fma_f32 v[76:77], v[132:133], v[196:197], v[76:77]
	ds_read_b64 v[176:177], v244 offset:768
	ds_read_b64 v[196:197], v243 offset:784
	ds_read_b64 v[200:201], v238 offset:2064
	v_mul_f32_e32 v208, 0xbfb8aa3b, v98
	v_mul_f32_e32 v209, 0xbfb8aa3b, v99
	v_mul_f32_e32 v210, 0xbfb8aa3b, v100
	v_mul_f32_e32 v211, 0xbfb8aa3b, v101
	v_exp_f32_e32 v208, v208
	v_exp_f32_e32 v209, v209
	v_exp_f32_e32 v210, v210
	v_exp_f32_e32 v211, v211
	v_add_f32_e32 v208, 1.0, v208
	v_add_f32_e32 v209, 1.0, v209
	v_add_f32_e32 v210, 1.0, v210
	v_add_f32_e32 v211, 1.0, v211
	v_rcp_f32_e32 v208, v208
	v_rcp_f32_e32 v209, v209
	v_rcp_f32_e32 v210, v210
	v_rcp_f32_e32 v211, v211
	v_mul_f32_e32 v98, v98, v208
	v_mul_f32_e32 v99, v99, v209
	v_mul_f32_e32 v100, v100, v210
	v_mul_f32_e32 v101, v101, v211
	v_mul_f32_e32 v98, v102, v98
	v_mul_f32_e32 v99, v103, v99
	v_mul_f32_e32 v100, v104, v100
	v_mul_f32_e32 v101, v105, v101
	v_cvt_pk_bf16_f32 v212, v98, v99
	v_cvt_pk_bf16_f32 v213, v100, v101
	v_mad_u32_u24 v221, v234, s29, v247
	s_and_saveexec_b64 s[30:31], s[20:21]
	global_store_dwordx2 v221, v[212:213], s[10:11]
	s_mov_b64 exec, s[30:31]
	v_mul_f32_e32 v208, 0xbfb8aa3b, v90
	v_mul_f32_e32 v209, 0xbfb8aa3b, v91
	v_mul_f32_e32 v210, 0xbfb8aa3b, v92
	v_mul_f32_e32 v211, 0xbfb8aa3b, v93
	v_exp_f32_e32 v208, v208
	v_exp_f32_e32 v209, v209
	v_exp_f32_e32 v210, v210
	v_exp_f32_e32 v211, v211
	v_add_f32_e32 v208, 1.0, v208
	v_add_f32_e32 v209, 1.0, v209
	v_add_f32_e32 v210, 1.0, v210
	v_add_f32_e32 v211, 1.0, v211
	v_rcp_f32_e32 v208, v208
	v_rcp_f32_e32 v209, v209
	v_rcp_f32_e32 v210, v210
	v_rcp_f32_e32 v211, v211
	v_mul_f32_e32 v90, v90, v208
	v_mul_f32_e32 v91, v91, v209
	v_mul_f32_e32 v92, v92, v210
	v_mul_f32_e32 v93, v93, v211
	v_mul_f32_e32 v90, v94, v90
	v_mul_f32_e32 v91, v95, v91
	v_mul_f32_e32 v92, v96, v92
	v_mul_f32_e32 v93, v97, v93
	v_cvt_pk_bf16_f32 v218, v90, v91
	v_cvt_pk_bf16_f32 v219, v92, v93
	v_mad_u32_u24 v40, v235, s29, v247
	s_and_saveexec_b64 s[30:31], s[22:23]
	global_store_dwordx2 v40, v[218:219], s[10:11]
; #define PG8_LAS __attribute__((address_space(3)))
; __device__ __forceinline__ unsigned cvt_pk_bf16(float lo, float hi) { unsigned r; asm volatile("v_cvt_pk_bf16_f32 %0, %1, %2" : "=v"(r) : "v"(lo), "v"(hi)); return r; }
;     __device__ __forceinline__ void operator()(const f32x4 (&acc)[2][2][4][2], const Unit& u, int wr, int wc, int fr, int fq) const {
;     ...
;                 for (int m = 0; m < 4; ++m) { const int r = 128 * ai + 64 * wr + 16 * m + fr, t = tstart + r;
;                     const bool upok = t >= 1, dnok = (t + 1) < T, store_ok = (r >= vlo) && (r < vhi) && (t < T);
;                     f32x4 res[2];
; #pragma unroll
;                     for (int bj = 0; bj < 2; ++bj) { const f32x4 cur = acc[ai][bj][m][n];
;                         f32x4 su = cur, sd = cur;
;                         if (m > 0) { if (fr == 15) su = acc[ai][bj][m > 0 ? m - 1 : 0][n]; }
;                         if (m < 3) { if (fr == 0) sd = acc[ai][bj][m < 3 ? m + 1 : 3][n]; }
;                         f32x4 up, dn;
;                         up[0] = dpp_ror1(su[0]); up[1] = dpp_ror1(su[1]); up[2] = dpp_ror1(su[2]); up[3] = dpp_ror1(su[3]);
;                         dn[0] = dpp_ror15(sd[0]); dn[1] = dpp_ror15(sd[1]); dn[2] = dpp_ror15(sd[2]); dn[3] = dpp_ror15(sd[3]);
;                         if (m == 0) { f32x4 halo = zero4; if (blk > 0) halo = *(const PG8_LAS f32x4*)(xb + (((((blk - 1) * 2 + 1) * 4 + wc) * 4 + fq) * 16 + (bj * 2 + n) * 4)); if (fr == 0) up = halo; }
;                         if (m == 3) { f32x4 halo = zero4; if (blk < 3) halo = *(const PG8_LAS f32x4*)(xb + (((((blk + 1) * 2 + 0) * 4 + wc) * 4 + fq) * 16 + (bj * 2 + n) * 4)); if (fr == 15) dn = halo; }
;                         if (edge) { if (!upok) up = zero4; if (!dnok) dn = zero4; }
;                         res[bj] = bb[bj] + w0[bj] * up + w1[bj] * cur + w2[bj] * dn; }
;                     if (store_ok) {
;                         float o[4];
; #pragma unroll
;                         for (int j = 0; j < 4; ++j) { const float gg = res[1][j]; o[j] = gg * __builtin_amdgcn_rcpf(1.f + __expf(-gg)) * res[0][j]; }
;                         u32x2 w; w.x = cvt_pk_bf16(o[0], o[1]); w.y = cvt_pk_bf16(o[2], o[3]);
;                         *(u32x2*)(ACT + (size_t)(seqrow + t) * 2816 + ch0 + 4 * n) = w; } } }
	s_mov_b64 exec, s[30:31]
	v_mul_f32_e32 v208, 0xbfb8aa3b, v82
	v_mul_f32_e32 v209, 0xbfb8aa3b, v83
	v_mul_f32_e32 v210, 0xbfb8aa3b, v84
	v_mul_f32_e32 v211, 0xbfb8aa3b, v85
	v_exp_f32_e32 v208, v208
	v_exp_f32_e32 v209, v209
	v_exp_f32_e32 v210, v210
	v_exp_f32_e32 v211, v211
	v_add_f32_e32 v208, 1.0, v208
	v_add_f32_e32 v209, 1.0, v209
	v_add_f32_e32 v210, 1.0, v210
	v_add_f32_e32 v211, 1.0, v211
	v_rcp_f32_e32 v208, v208
	v_rcp_f32_e32 v209, v209
	v_rcp_f32_e32 v210, v210
	v_rcp_f32_e32 v211, v211
	v_mul_f32_e32 v82, v82, v208
	v_mul_f32_e32 v83, v83, v209
	v_mul_f32_e32 v84, v84, v210
	v_mul_f32_e32 v85, v85, v211
	v_mul_f32_e32 v82, v86, v82
	v_mul_f32_e32 v83, v87, v83
	v_mul_f32_e32 v84, v88, v84
	v_mul_f32_e32 v85, v89, v85
	v_cvt_pk_bf16_f32 v212, v82, v83
	v_cvt_pk_bf16_f32 v213, v84, v85
	v_mad_u32_u24 v221, v236, s29, v247
	s_and_saveexec_b64 s[30:31], s[24:25]
	global_store_dwordx2 v221, v[212:213], s[10:11]
	s_mov_b64 exec, s[30:31]
	v_mul_f32_e32 v208, 0xbfb8aa3b, v74
	v_mul_f32_e32 v209, 0xbfb8aa3b, v75
	v_mul_f32_e32 v210, 0xbfb8aa3b, v76
	v_mul_f32_e32 v211, 0xbfb8aa3b, v77
	v_exp_f32_e32 v208, v208
	v_exp_f32_e32 v209, v209
	v_exp_f32_e32 v210, v210
	v_exp_f32_e32 v211, v211
	v_add_f32_e32 v208, 1.0, v208
	v_add_f32_e32 v209, 1.0, v209
	v_add_f32_e32 v210, 1.0, v210
	v_add_f32_e32 v211, 1.0, v211
	v_rcp_f32_e32 v208, v208
	v_rcp_f32_e32 v209, v209
	v_rcp_f32_e32 v210, v210
	v_rcp_f32_e32 v211, v211
	v_mul_f32_e32 v74, v74, v208
	v_mul_f32_e32 v75, v75, v209
	v_mul_f32_e32 v76, v76, v210
	v_mul_f32_e32 v77, v77, v211
	v_mul_f32_e32 v74, v78, v74
	v_mul_f32_e32 v75, v79, v75
	v_mul_f32_e32 v76, v80, v76
	v_mul_f32_e32 v77, v81, v77
	v_cvt_pk_bf16_f32 v218, v74, v75
	v_cvt_pk_bf16_f32 v219, v76, v77
	v_mad_u32_u24 v40, v237, s29, v247
	s_and_saveexec_b64 s[30:31], s[26:27]
	global_store_dwordx2 v40, v[218:219], s[10:11]
	s_mov_b64 exec, s[30:31]
	s_waitcnt vmcnt(4)
	ds_write_b64 v243, v[72:73]
	ds_write_b64 v243, v[64:65] offset:256
	ds_write_b64 v243, v[56:57] offset:512
	ds_write_b64 v243, v[48:49] offset:768
	s_waitcnt lgkmcnt(11)
	v_cndmask_b32_e64 v170, v170, v198, s[6:7]
	v_cndmask_b32_e64 v171, v171, v199, s[6:7]
	v_add_u32_e32 v220, s48, v227
	v_cmp_lt_i32_e32 vcc, 0, v220
	s_nop 1
	v_cndmask_b32_e32 v170, 0, v170, vcc
	v_cndmask_b32_e32 v171, 0, v171, vcc
	v_cmp_gt_i32_e32 vcc, s28, v220
	s_nop 1
	v_cndmask_b32_e32 v178, 0, v178, vcc
	v_cndmask_b32_e32 v179, 0, v179, vcc
	v_pk_fma_f32 v[202:203], v[138:139], v[170:171], v[150:151]
	v_pk_fma_f32 v[70:71], v[70:71], v[142:143], v[202:203]
	v_pk_fma_f32 v[70:71], v[146:147], v[178:179], v[70:71]
	ds_read_b64 v[170:171], v244
	ds_read_b64 v[178:179], v243 offset:16
	ds_read_b64 v[198:199], v245 offset:24
	s_waitcnt lgkmcnt(12)
	v_add_u32_e32 v220, s48, v231
	v_cmp_lt_i32_e32 vcc, 0, v220
	s_nop 1
	v_cndmask_b32_e32 v172, 0, v172, vcc
	v_cndmask_b32_e32 v173, 0, v173, vcc
	v_cmp_gt_i32_e32 vcc, s28, v220
	s_nop 1
	v_cndmask_b32_e32 v180, 0, v180, vcc
	v_cndmask_b32_e32 v181, 0, v181, vcc
	v_pk_fma_f32 v[202:203], v[138:139], v[172:173], v[150:151]
	v_pk_fma_f32 v[62:63], v[62:63], v[142:143], v[202:203]
	v_pk_fma_f32 v[62:63], v[146:147], v[180:181], v[62:63]
	ds_read_b64 v[172:173], v244 offset:256
	ds_read_b64 v[180:181], v243 offset:272
	s_waitcnt lgkmcnt(12)
	v_add_u32_e32 v220, s48, v232
	v_cmp_lt_i32_e32 vcc, 0, v220
	s_nop 1
	v_cndmask_b32_e32 v174, 0, v174, vcc
	v_cndmask_b32_e32 v175, 0, v175, vcc
	v_cmp_gt_i32_e32 vcc, s28, v220
	s_nop 1
	v_cndmask_b32_e32 v194, 0, v194, vcc
	v_cndmask_b32_e32 v195, 0, v195, vcc
	v_pk_fma_f32 v[202:203], v[138:139], v[174:175], v[150:151]
	v_pk_fma_f32 v[54:55], v[54:55], v[142:143], v[202:203]
	v_pk_fma_f32 v[54:55], v[146:147], v[194:195], v[54:55]
	ds_read_b64 v[174:175], v244 offset:512
	ds_read_b64 v[194:195], v243 offset:528
	s_waitcnt lgkmcnt(11)
	v_cndmask_b32_e64 v196, v196, v200, s[4:5]
	v_cndmask_b32_e64 v197, v197, v201, s[4:5]
	v_add_u32_e32 v220, s48, v233
	v_cmp_lt_i32_e32 vcc, 0, v220
	s_nop 1
	v_cndmask_b32_e32 v176, 0, v176, vcc
	v_cndmask_b32_e32 v177, 0, v177, vcc
	v_cmp_gt_i32_e32 vcc, s28, v220
	s_nop 1
	v_cndmask_b32_e32 v196, 0, v196, vcc
	v_cndmask_b32_e32 v197, 0, v197, vcc
	v_pk_fma_f32 v[202:203], v[138:139], v[176:177], v[150:151]
	v_pk_fma_f32 v[46:47], v[46:47], v[142:143], v[202:203]
	v_pk_fma_f32 v[46:47], v[146:147], v[196:197], v[46:47]
	ds_read_b64 v[176:177], v244 offset:768
	ds_read_b64 v[196:197], v243 offset:784
	ds_read_b64 v[200:201], v238 offset:2072
	ds_write_b64 v243, v[66:67]
	ds_write_b64 v243, v[58:59] offset:256
	ds_write_b64 v243, v[50:51] offset:512
	ds_write_b64 v243, v[42:43] offset:768
	s_waitcnt lgkmcnt(11)
	v_cndmask_b32_e64 v170, v170, v198, s[6:7]
	v_cndmask_b32_e64 v171, v171, v199, s[6:7]
	v_add_u32_e32 v220, s48, v227
	v_cmp_lt_i32_e32 vcc, 0, v220
	s_nop 1
	v_cndmask_b32_e32 v170, 0, v170, vcc
	v_cndmask_b32_e32 v171, 0, v171, vcc
	v_cmp_gt_i32_e32 vcc, s28, v220
	s_nop 1
	v_cndmask_b32_e32 v178, 0, v178, vcc
	v_cndmask_b32_e32 v179, 0, v179, vcc
	v_pk_fma_f32 v[202:203], v[140:141], v[170:171], v[152:153]
	v_pk_fma_f32 v[72:73], v[72:73], v[144:145], v[202:203]
	v_pk_fma_f32 v[72:73], v[148:149], v[178:179], v[72:73]
	ds_read_b64 v[170:171], v244
	ds_read_b64 v[178:179], v243 offset:16
	ds_read_b64 v[198:199], v245 offset:48
	s_waitcnt lgkmcnt(12)
	v_add_u32_e32 v220, s48, v231
	v_cmp_lt_i32_e32 vcc, 0, v220
	s_nop 1
	v_cndmask_b32_e32 v172, 0, v172, vcc
	v_cndmask_b32_e32 v173, 0, v173, vcc
	v_cmp_gt_i32_e32 vcc, s28, v220
	s_nop 1
	v_cndmask_b32_e32 v180, 0, v180, vcc
	v_cndmask_b32_e32 v181, 0, v181, vcc
	v_pk_fma_f32 v[202:203], v[140:141], v[172:173], v[152:153]
	v_pk_fma_f32 v[64:65], v[64:65], v[144:145], v[202:203]
	v_pk_fma_f32 v[64:65], v[148:149], v[180:181], v[64:65]
	ds_read_b64 v[172:173], v244 offset:256
	ds_read_b64 v[180:181], v243 offset:272
	s_waitcnt lgkmcnt(12)
; #define PG8_LAS __attribute__((address_space(3)))
; __device__ __forceinline__ float dpp_ror1(float v) { return __builtin_bit_cast(float, __builtin_amdgcn_update_dpp(0, __builtin_bit_cast(int, v), 0x121, 0xf, 0xf, false)); }
; __device__ __forceinline__ float dpp_ror15(float v) { return __builtin_bit_cast(float, __builtin_amdgcn_update_dpp(0, __builtin_bit_cast(int, v), 0x12F, 0xf, 0xf, false)); }
;     __device__ __forceinline__ void operator()(const f32x4 (&acc)[2][2][4][2], const Unit& u, int wr, int wc, int fr, int fq) const {
;     ...
;                 for (int m = 0; m < 4; ++m) { const int r = 128 * ai + 64 * wr + 16 * m + fr, t = tstart + r;
;                     const bool upok = t >= 1, dnok = (t + 1) < T, store_ok = (r >= vlo) && (r < vhi) && (t < T);
;                     f32x4 res[2];
; #pragma unroll
;                     for (int bj = 0; bj < 2; ++bj) { const f32x4 cur = acc[ai][bj][m][n];
;                         f32x4 su = cur, sd = cur;
;                         if (m > 0) { if (fr == 15) su = acc[ai][bj][m > 0 ? m - 1 : 0][n]; }
;                         if (m < 3) { if (fr == 0) sd = acc[ai][bj][m < 3 ? m + 1 : 3][n]; }
;                         f32x4 up, dn;
;                         up[0] = dpp_ror1(su[0]); up[1] = dpp_ror1(su[1]); up[2] = dpp_ror1(su[2]); up[3] = dpp_ror1(su[3]);
;                         dn[0] = dpp_ror15(sd[0]); dn[1] = dpp_ror15(sd[1]); dn[2] = dpp_ror15(sd[2]); dn[3] = dpp_ror15(sd[3]);
;                         if (m == 0) { f32x4 halo = zero4; if (blk > 0) halo = *(const PG8_LAS f32x4*)(xb + (((((blk - 1) * 2 + 1) * 4 + wc) * 4 + fq) * 16 + (bj * 2 + n) * 4)); if (fr == 0) up = halo; }
;                         if (m == 3) { f32x4 halo = zero4; if (blk < 3) halo = *(const PG8_LAS f32x4*)(xb + (((((blk + 1) * 2 + 0) * 4 + wc) * 4 + fq) * 16 + (bj * 2 + n) * 4)); if (fr == 15) dn = halo; }
;                         if (edge) { if (!upok) up = zero4; if (!dnok) dn = zero4; }
;                         res[bj] = bb[bj] + w0[bj] * up + w1[bj] * cur + w2[bj] * dn; }
	v_add_u32_e32 v220, s48, v232
	v_cmp_lt_i32_e32 vcc, 0, v220
	s_nop 1
	v_cndmask_b32_e32 v174, 0, v174, vcc
	v_cndmask_b32_e32 v175, 0, v175, vcc
	v_cmp_gt_i32_e32 vcc, s28, v220
	s_nop 1
	v_cndmask_b32_e32 v194, 0, v194, vcc
	v_cndmask_b32_e32 v195, 0, v195, vcc
	v_pk_fma_f32 v[202:203], v[140:141], v[174:175], v[152:153]
	v_pk_fma_f32 v[56:57], v[56:57], v[144:145], v[202:203]
	v_pk_fma_f32 v[56:57], v[148:149], v[194:195], v[56:57]
	ds_read_b64 v[174:175], v244 offset:512
	ds_read_b64 v[194:195], v243 offset:528
	s_waitcnt lgkmcnt(11)
	v_cndmask_b32_e64 v196, v196, v200, s[4:5]
	v_cndmask_b32_e64 v197, v197, v201, s[4:5]
	v_add_u32_e32 v220, s48, v233
	v_cmp_lt_i32_e32 vcc, 0, v220
	s_nop 1
	v_cndmask_b32_e32 v176, 0, v176, vcc
	v_cndmask_b32_e32 v177, 0, v177, vcc
	v_cmp_gt_i32_e32 vcc, s28, v220
	s_nop 1
	v_cndmask_b32_e32 v196, 0, v196, vcc
	v_cndmask_b32_e32 v197, 0, v197, vcc
	v_pk_fma_f32 v[202:203], v[140:141], v[176:177], v[152:153]
	v_pk_fma_f32 v[48:49], v[48:49], v[144:145], v[202:203]
	v_pk_fma_f32 v[48:49], v[148:149], v[196:197], v[48:49]
	ds_read_b64 v[176:177], v244 offset:768
	ds_read_b64 v[196:197], v243 offset:784
	ds_read_b64 v[200:201], v238 offset:2096
	ds_write_b64 v243, v[68:69]
	ds_write_b64 v243, v[60:61] offset:256
	ds_write_b64 v243, v[52:53] offset:512
	ds_write_b64 v243, v[44:45] offset:768
	s_waitcnt lgkmcnt(11)
	v_cndmask_b32_e64 v170, v170, v198, s[6:7]
	v_cndmask_b32_e64 v171, v171, v199, s[6:7]
	v_add_u32_e32 v220, s48, v227
	v_cmp_lt_i32_e32 vcc, 0, v220
	s_nop 1
	v_cndmask_b32_e32 v170, 0, v170, vcc
	v_cndmask_b32_e32 v171, 0, v171, vcc
	v_cmp_gt_i32_e32 vcc, s28, v220
	s_nop 1
	v_cndmask_b32_e32 v178, 0, v178, vcc
	v_cndmask_b32_e32 v179, 0, v179, vcc
	v_pk_fma_f32 v[202:203], v[154:155], v[170:171], v[166:167]
	v_pk_fma_f32 v[66:67], v[66:67], v[158:159], v[202:203]
	v_pk_fma_f32 v[66:67], v[162:163], v[178:179], v[66:67]
	ds_read_b64 v[170:171], v244
	ds_read_b64 v[178:179], v243 offset:16
	ds_read_b64 v[198:199], v245 offset:56
	s_waitcnt lgkmcnt(12)
	v_add_u32_e32 v220, s48, v231
	v_cmp_lt_i32_e32 vcc, 0, v220
	s_nop 1
	v_cndmask_b32_e32 v172, 0, v172, vcc
	v_cndmask_b32_e32 v173, 0, v173, vcc
	v_cmp_gt_i32_e32 vcc, s28, v220
	s_nop 1
	v_cndmask_b32_e32 v180, 0, v180, vcc
	v_cndmask_b32_e32 v181, 0, v181, vcc
	v_pk_fma_f32 v[202:203], v[154:155], v[172:173], v[166:167]
	v_pk_fma_f32 v[58:59], v[58:59], v[158:159], v[202:203]
	v_pk_fma_f32 v[58:59], v[162:163], v[180:181], v[58:59]
	ds_read_b64 v[172:173], v244 offset:256
	ds_read_b64 v[180:181], v243 offset:272
	s_waitcnt lgkmcnt(12)
	v_add_u32_e32 v220, s48, v232
	v_cmp_lt_i32_e32 vcc, 0, v220
	s_nop 1
	v_cndmask_b32_e32 v174, 0, v174, vcc
	v_cndmask_b32_e32 v175, 0, v175, vcc
	v_cmp_gt_i32_e32 vcc, s28, v220
	s_nop 1
	v_cndmask_b32_e32 v194, 0, v194, vcc
	v_cndmask_b32_e32 v195, 0, v195, vcc
	v_pk_fma_f32 v[202:203], v[154:155], v[174:175], v[166:167]
	v_pk_fma_f32 v[50:51], v[50:51], v[158:159], v[202:203]
	v_pk_fma_f32 v[50:51], v[162:163], v[194:195], v[50:51]
	ds_read_b64 v[174:175], v244 offset:512
	ds_read_b64 v[194:195], v243 offset:528
	s_waitcnt lgkmcnt(11)
	v_cndmask_b32_e64 v196, v196, v200, s[4:5]
	v_cndmask_b32_e64 v197, v197, v201, s[4:5]
	v_add_u32_e32 v220, s48, v233
	v_cmp_lt_i32_e32 vcc, 0, v220
	s_nop 1
	v_cndmask_b32_e32 v176, 0, v176, vcc
	v_cndmask_b32_e32 v177, 0, v177, vcc
	v_cmp_gt_i32_e32 vcc, s28, v220
	s_nop 1
	v_cndmask_b32_e32 v196, 0, v196, vcc
	v_cndmask_b32_e32 v197, 0, v197, vcc
	v_pk_fma_f32 v[202:203], v[154:155], v[176:177], v[166:167]
	v_pk_fma_f32 v[42:43], v[42:43], v[158:159], v[202:203]
	v_pk_fma_f32 v[42:43], v[162:163], v[196:197], v[42:43]
	ds_read_b64 v[176:177], v244 offset:768
	ds_read_b64 v[196:197], v243 offset:784
	ds_read_b64 v[200:201], v238 offset:2104
	ds_write_b64 v243, v[30:31]
	ds_write_b64 v243, v[22:23] offset:256
	ds_write_b64 v243, v[14:15] offset:512
	ds_write_b64 v243, v[6:7] offset:768
	s_waitcnt lgkmcnt(11)
	v_cndmask_b32_e64 v170, v170, v198, s[6:7]
	v_cndmask_b32_e64 v171, v171, v199, s[6:7]
	v_add_u32_e32 v220, s48, v227
	v_cmp_lt_i32_e32 vcc, 0, v220
	s_nop 1
	v_cndmask_b32_e32 v170, 0, v170, vcc
	v_cndmask_b32_e32 v171, 0, v171, vcc
	v_cmp_gt_i32_e32 vcc, s28, v220
	s_nop 1
	v_cndmask_b32_e32 v178, 0, v178, vcc
	v_cndmask_b32_e32 v179, 0, v179, vcc
	v_pk_fma_f32 v[202:203], v[156:157], v[170:171], v[168:169]
	v_pk_fma_f32 v[68:69], v[68:69], v[160:161], v[202:203]
	v_pk_fma_f32 v[68:69], v[164:165], v[178:179], v[68:69]
	ds_read_b64 v[170:171], v244
	ds_read_b64 v[178:179], v243 offset:16
	ds_read_b64 v[198:199], v238 offset:3088
	s_waitcnt lgkmcnt(12)
	v_add_u32_e32 v220, s48, v231
	v_cmp_lt_i32_e32 vcc, 0, v220
	s_nop 1
	v_cndmask_b32_e32 v172, 0, v172, vcc
	v_cndmask_b32_e32 v173, 0, v173, vcc
	v_cmp_gt_i32_e32 vcc, s28, v220
	s_nop 1
	v_cndmask_b32_e32 v180, 0, v180, vcc
	v_cndmask_b32_e32 v181, 0, v181, vcc
	v_pk_fma_f32 v[202:203], v[156:157], v[172:173], v[168:169]
	v_pk_fma_f32 v[60:61], v[60:61], v[160:161], v[202:203]
	v_pk_fma_f32 v[60:61], v[164:165], v[180:181], v[60:61]
	ds_read_b64 v[172:173], v244 offset:256
	ds_read_b64 v[180:181], v243 offset:272
	s_waitcnt lgkmcnt(12)
	v_add_u32_e32 v220, s48, v232
	v_cmp_lt_i32_e32 vcc, 0, v220
	s_nop 1
	v_cndmask_b32_e32 v174, 0, v174, vcc
	v_cndmask_b32_e32 v175, 0, v175, vcc
	v_cmp_gt_i32_e32 vcc, s28, v220
	s_nop 1
	v_cndmask_b32_e32 v194, 0, v194, vcc
	v_cndmask_b32_e32 v195, 0, v195, vcc
	v_pk_fma_f32 v[202:203], v[156:157], v[174:175], v[168:169]
	v_pk_fma_f32 v[52:53], v[52:53], v[160:161], v[202:203]
	v_pk_fma_f32 v[52:53], v[164:165], v[194:195], v[52:53]
	ds_read_b64 v[174:175], v244 offset:512
	ds_read_b64 v[194:195], v243 offset:528
	s_waitcnt lgkmcnt(11)
; #define PG8_LAS __attribute__((address_space(3)))
; __device__ __forceinline__ unsigned cvt_pk_bf16(float lo, float hi) { unsigned r; asm volatile("v_cvt_pk_bf16_f32 %0, %1, %2" : "=v"(r) : "v"(lo), "v"(hi)); return r; }
;     __device__ __forceinline__ void operator()(const f32x4 (&acc)[2][2][4][2], const Unit& u, int wr, int wc, int fr, int fq) const {
;     ...
;                 for (int m = 0; m < 4; ++m) { const int r = 128 * ai + 64 * wr + 16 * m + fr, t = tstart + r;
;                     const bool upok = t >= 1, dnok = (t + 1) < T, store_ok = (r >= vlo) && (r < vhi) && (t < T);
;                     f32x4 res[2];
; #pragma unroll
;                     for (int bj = 0; bj < 2; ++bj) { const f32x4 cur = acc[ai][bj][m][n];
;                         f32x4 su = cur, sd = cur;
;                         if (m > 0) { if (fr == 15) su = acc[ai][bj][m > 0 ? m - 1 : 0][n]; }
;                         if (m < 3) { if (fr == 0) sd = acc[ai][bj][m < 3 ? m + 1 : 3][n]; }
;                         f32x4 up, dn;
;                         up[0] = dpp_ror1(su[0]); up[1] = dpp_ror1(su[1]); up[2] = dpp_ror1(su[2]); up[3] = dpp_ror1(su[3]);
;                         dn[0] = dpp_ror15(sd[0]); dn[1] = dpp_ror15(sd[1]); dn[2] = dpp_ror15(sd[2]); dn[3] = dpp_ror15(sd[3]);
;                         if (m == 0) { f32x4 halo = zero4; if (blk > 0) halo = *(const PG8_LAS f32x4*)(xb + (((((blk - 1) * 2 + 1) * 4 + wc) * 4 + fq) * 16 + (bj * 2 + n) * 4)); if (fr == 0) up = halo; }
;                         if (m == 3) { f32x4 halo = zero4; if (blk < 3) halo = *(const PG8_LAS f32x4*)(xb + (((((blk + 1) * 2 + 0) * 4 + wc) * 4 + fq) * 16 + (bj * 2 + n) * 4)); if (fr == 15) dn = halo; }
;                         if (edge) { if (!upok) up = zero4; if (!dnok) dn = zero4; }
;                         res[bj] = bb[bj] + w0[bj] * up + w1[bj] * cur + w2[bj] * dn; }
;                     if (store_ok) {
;                         float o[4];
; #pragma unroll
;                         for (int j = 0; j < 4; ++j) { const float gg = res[1][j]; o[j] = gg * __builtin_amdgcn_rcpf(1.f + __expf(-gg)) * res[0][j]; }
;                         u32x2 w; w.x = cvt_pk_bf16(o[0], o[1]); w.y = cvt_pk_bf16(o[2], o[3]);
;                         *(u32x2*)(ACT + (size_t)(seqrow + t) * 2816 + ch0 + 4 * n) = w; } } }
	v_cndmask_b32_e64 v196, v196, v200, s[4:5]
	v_cndmask_b32_e64 v197, v197, v201, s[4:5]
	v_add_u32_e32 v220, s48, v233
	v_cmp_lt_i32_e32 vcc, 0, v220
	s_nop 1
	v_cndmask_b32_e32 v176, 0, v176, vcc
	v_cndmask_b32_e32 v177, 0, v177, vcc
	v_cmp_gt_i32_e32 vcc, s28, v220
	s_nop 1
	v_cndmask_b32_e32 v196, 0, v196, vcc
	v_cndmask_b32_e32 v197, 0, v197, vcc
	v_pk_fma_f32 v[202:203], v[156:157], v[176:177], v[168:169]
	v_pk_fma_f32 v[44:45], v[44:45], v[160:161], v[202:203]
	v_pk_fma_f32 v[44:45], v[164:165], v[196:197], v[44:45]
	ds_read_b64 v[176:177], v244 offset:768
	ds_read_b64 v[196:197], v243 offset:784
	ds_read_b64 v[200:201], v246 offset:16
	v_mul_f32_e32 v208, 0xbfb8aa3b, v66
	v_mul_f32_e32 v209, 0xbfb8aa3b, v67
	v_mul_f32_e32 v210, 0xbfb8aa3b, v68
	v_mul_f32_e32 v211, 0xbfb8aa3b, v69
	v_exp_f32_e32 v208, v208
	v_exp_f32_e32 v209, v209
	v_exp_f32_e32 v210, v210
	v_exp_f32_e32 v211, v211
	v_add_f32_e32 v208, 1.0, v208
	v_add_f32_e32 v209, 1.0, v209
	v_add_f32_e32 v210, 1.0, v210
	v_add_f32_e32 v211, 1.0, v211
	v_rcp_f32_e32 v208, v208
	v_rcp_f32_e32 v209, v209
	v_rcp_f32_e32 v210, v210
	v_rcp_f32_e32 v211, v211
	v_mul_f32_e32 v66, v66, v208
	v_mul_f32_e32 v67, v67, v209
	v_mul_f32_e32 v68, v68, v210
	v_mul_f32_e32 v69, v69, v211
	v_mul_f32_e32 v66, v70, v66
	v_mul_f32_e32 v67, v71, v67
	v_mul_f32_e32 v68, v72, v68
	v_mul_f32_e32 v69, v73, v69
	v_cvt_pk_bf16_f32 v212, v66, v67
	v_cvt_pk_bf16_f32 v213, v68, v69
	v_mad_u32_u24 v221, v227, s29, v247
	s_and_saveexec_b64 s[30:31], s[12:13]
	global_store_dwordx2 v221, v[212:213], s[10:11] offset:8
	s_mov_b64 exec, s[30:31]
	v_mul_f32_e32 v208, 0xbfb8aa3b, v58
	v_mul_f32_e32 v209, 0xbfb8aa3b, v59
	v_mul_f32_e32 v210, 0xbfb8aa3b, v60
	v_mul_f32_e32 v211, 0xbfb8aa3b, v61
	v_exp_f32_e32 v208, v208
	v_exp_f32_e32 v209, v209
	v_exp_f32_e32 v210, v210
	v_exp_f32_e32 v211, v211
	v_add_f32_e32 v208, 1.0, v208
	v_add_f32_e32 v209, 1.0, v209
	v_add_f32_e32 v210, 1.0, v210
	v_add_f32_e32 v211, 1.0, v211
	v_rcp_f32_e32 v208, v208
	v_rcp_f32_e32 v209, v209
	v_rcp_f32_e32 v210, v210
	v_rcp_f32_e32 v211, v211
	v_mul_f32_e32 v58, v58, v208
	v_mul_f32_e32 v59, v59, v209
	v_mul_f32_e32 v60, v60, v210
	v_mul_f32_e32 v61, v61, v211
	v_mul_f32_e32 v58, v62, v58
	v_mul_f32_e32 v59, v63, v59
	v_mul_f32_e32 v60, v64, v60
	v_mul_f32_e32 v61, v65, v61
	v_cvt_pk_bf16_f32 v218, v58, v59
	v_cvt_pk_bf16_f32 v219, v60, v61
	v_mad_u32_u24 v40, v231, s29, v247
	s_and_saveexec_b64 s[30:31], s[14:15]
	global_store_dwordx2 v40, v[218:219], s[10:11] offset:8
	s_mov_b64 exec, s[30:31]
	v_mul_f32_e32 v208, 0xbfb8aa3b, v50
	v_mul_f32_e32 v209, 0xbfb8aa3b, v51
	v_mul_f32_e32 v210, 0xbfb8aa3b, v52
	v_mul_f32_e32 v211, 0xbfb8aa3b, v53
	v_exp_f32_e32 v208, v208
	v_exp_f32_e32 v209, v209
	v_exp_f32_e32 v210, v210
	v_exp_f32_e32 v211, v211
	v_add_f32_e32 v208, 1.0, v208
	v_add_f32_e32 v209, 1.0, v209
	v_add_f32_e32 v210, 1.0, v210
	v_add_f32_e32 v211, 1.0, v211
	v_rcp_f32_e32 v208, v208
	v_rcp_f32_e32 v209, v209
	v_rcp_f32_e32 v210, v210
	v_rcp_f32_e32 v211, v211
	v_mul_f32_e32 v50, v50, v208
	v_mul_f32_e32 v51, v51, v209
	v_mul_f32_e32 v52, v52, v210
	v_mul_f32_e32 v53, v53, v211
	v_mul_f32_e32 v50, v54, v50
	v_mul_f32_e32 v51, v55, v51
	v_mul_f32_e32 v52, v56, v52
	v_mul_f32_e32 v53, v57, v53
	v_cvt_pk_bf16_f32 v212, v50, v51
	v_cvt_pk_bf16_f32 v213, v52, v53
	v_mad_u32_u24 v221, v232, s29, v247
	s_and_saveexec_b64 s[30:31], s[16:17]
	global_store_dwordx2 v221, v[212:213], s[10:11] offset:8
	s_mov_b64 exec, s[30:31]
	v_mul_f32_e32 v208, 0xbfb8aa3b, v42
	v_mul_f32_e32 v209, 0xbfb8aa3b, v43
	v_mul_f32_e32 v210, 0xbfb8aa3b, v44
	v_mul_f32_e32 v211, 0xbfb8aa3b, v45
	v_exp_f32_e32 v208, v208
	v_exp_f32_e32 v209, v209
	v_exp_f32_e32 v210, v210
	v_exp_f32_e32 v211, v211
	v_add_f32_e32 v208, 1.0, v208
	v_add_f32_e32 v209, 1.0, v209
	v_add_f32_e32 v210, 1.0, v210
	v_add_f32_e32 v211, 1.0, v211
	v_rcp_f32_e32 v208, v208
	v_rcp_f32_e32 v209, v209
	v_rcp_f32_e32 v210, v210
	v_rcp_f32_e32 v211, v211
	v_mul_f32_e32 v42, v42, v208
	v_mul_f32_e32 v43, v43, v209
	v_mul_f32_e32 v44, v44, v210
	v_mul_f32_e32 v45, v45, v211
	v_mul_f32_e32 v42, v46, v42
	v_mul_f32_e32 v43, v47, v43
	v_mul_f32_e32 v44, v48, v44
	v_mul_f32_e32 v45, v49, v45
	v_cvt_pk_bf16_f32 v218, v42, v43
	v_cvt_pk_bf16_f32 v219, v44, v45
	v_mad_u32_u24 v40, v233, s29, v247
	s_and_saveexec_b64 s[30:31], s[18:19]
	global_store_dwordx2 v40, v[218:219], s[10:11] offset:8
	s_mov_b64 exec, s[30:31]
	ds_write_b64 v243, v[32:33]
	ds_write_b64 v243, v[24:25] offset:256
	ds_write_b64 v243, v[16:17] offset:512
	ds_write_b64 v243, v[8:9] offset:768
	s_waitcnt lgkmcnt(11)
	v_cndmask_b32_e64 v170, v170, v198, s[6:7]
	v_cndmask_b32_e64 v171, v171, v199, s[6:7]
	v_add_u32_e32 v220, s48, v234
	v_cmp_lt_i32_e32 vcc, 0, v220
	s_nop 1
	v_cndmask_b32_e32 v170, 0, v170, vcc
	v_cndmask_b32_e32 v171, 0, v171, vcc
	v_cmp_gt_i32_e32 vcc, s28, v220
	s_nop 1
	v_cndmask_b32_e32 v178, 0, v178, vcc
	v_cndmask_b32_e32 v179, 0, v179, vcc
	v_pk_fma_f32 v[202:203], v[138:139], v[170:171], v[150:151]
	v_pk_fma_f32 v[30:31], v[30:31], v[142:143], v[202:203]
	v_pk_fma_f32 v[30:31], v[146:147], v[178:179], v[30:31]
	ds_read_b64 v[170:171], v244
	ds_read_b64 v[178:179], v243 offset:16
	ds_read_b64 v[198:199], v238 offset:3096
	s_waitcnt lgkmcnt(12)
	v_add_u32_e32 v220, s48, v235
	v_cmp_lt_i32_e32 vcc, 0, v220
	s_nop 1
	v_cndmask_b32_e32 v172, 0, v172, vcc
	v_cndmask_b32_e32 v173, 0, v173, vcc
	v_cmp_gt_i32_e32 vcc, s28, v220
	s_nop 1
	v_cndmask_b32_e32 v180, 0, v180, vcc
	v_cndmask_b32_e32 v181, 0, v181, vcc
	v_pk_fma_f32 v[202:203], v[138:139], v[172:173], v[150:151]
	v_pk_fma_f32 v[22:23], v[22:23], v[142:143], v[202:203]
	v_pk_fma_f32 v[22:23], v[146:147], v[180:181], v[22:23]
	ds_read_b64 v[172:173], v244 offset:256
	ds_read_b64 v[180:181], v243 offset:272
	s_waitcnt lgkmcnt(12)
; #define PG8_LAS __attribute__((address_space(3)))
; __device__ __forceinline__ float dpp_ror1(float v) { return __builtin_bit_cast(float, __builtin_amdgcn_update_dpp(0, __builtin_bit_cast(int, v), 0x121, 0xf, 0xf, false)); }
; __device__ __forceinline__ float dpp_ror15(float v) { return __builtin_bit_cast(float, __builtin_amdgcn_update_dpp(0, __builtin_bit_cast(int, v), 0x12F, 0xf, 0xf, false)); }
;     __device__ __forceinline__ void operator()(const f32x4 (&acc)[2][2][4][2], const Unit& u, int wr, int wc, int fr, int fq) const {
;     ...
;                 for (int m = 0; m < 4; ++m) { const int r = 128 * ai + 64 * wr + 16 * m + fr, t = tstart + r;
;                     const bool upok = t >= 1, dnok = (t + 1) < T, store_ok = (r >= vlo) && (r < vhi) && (t < T);
;                     f32x4 res[2];
; #pragma unroll
;                     for (int bj = 0; bj < 2; ++bj) { const f32x4 cur = acc[ai][bj][m][n];
;                         f32x4 su = cur, sd = cur;
;                         if (m > 0) { if (fr == 15) su = acc[ai][bj][m > 0 ? m - 1 : 0][n]; }
;                         if (m < 3) { if (fr == 0) sd = acc[ai][bj][m < 3 ? m + 1 : 3][n]; }
;                         f32x4 up, dn;
;                         up[0] = dpp_ror1(su[0]); up[1] = dpp_ror1(su[1]); up[2] = dpp_ror1(su[2]); up[3] = dpp_ror1(su[3]);
;                         dn[0] = dpp_ror15(sd[0]); dn[1] = dpp_ror15(sd[1]); dn[2] = dpp_ror15(sd[2]); dn[3] = dpp_ror15(sd[3]);
;                         if (m == 0) { f32x4 halo = zero4; if (blk > 0) halo = *(const PG8_LAS f32x4*)(xb + (((((blk - 1) * 2 + 1) * 4 + wc) * 4 + fq) * 16 + (bj * 2 + n) * 4)); if (fr == 0) up = halo; }
;                         if (m == 3) { f32x4 halo = zero4; if (blk < 3) halo = *(const PG8_LAS f32x4*)(xb + (((((blk + 1) * 2 + 0) * 4 + wc) * 4 + fq) * 16 + (bj * 2 + n) * 4)); if (fr == 15) dn = halo; }
;                         if (edge) { if (!upok) up = zero4; if (!dnok) dn = zero4; }
;                         res[bj] = bb[bj] + w0[bj] * up + w1[bj] * cur + w2[bj] * dn; }
	v_add_u32_e32 v220, s48, v236
	v_cmp_lt_i32_e32 vcc, 0, v220
	s_nop 1
	v_cndmask_b32_e32 v174, 0, v174, vcc
	v_cndmask_b32_e32 v175, 0, v175, vcc
	v_cmp_gt_i32_e32 vcc, s28, v220
	s_nop 1
	v_cndmask_b32_e32 v194, 0, v194, vcc
	v_cndmask_b32_e32 v195, 0, v195, vcc
	v_pk_fma_f32 v[202:203], v[138:139], v[174:175], v[150:151]
	v_pk_fma_f32 v[14:15], v[14:15], v[142:143], v[202:203]
	v_pk_fma_f32 v[14:15], v[146:147], v[194:195], v[14:15]
	ds_read_b64 v[174:175], v244 offset:512
	ds_read_b64 v[194:195], v243 offset:528
	s_waitcnt lgkmcnt(11)
	v_cndmask_b32_e64 v196, v196, v200, s[4:5]
	v_cndmask_b32_e64 v197, v197, v201, s[4:5]
	v_add_u32_e32 v220, s48, v237
	v_cmp_lt_i32_e32 vcc, 0, v220
	s_nop 1
	v_cndmask_b32_e32 v176, 0, v176, vcc
	v_cndmask_b32_e32 v177, 0, v177, vcc
	v_cmp_gt_i32_e32 vcc, s28, v220
	s_nop 1
	v_cndmask_b32_e32 v196, 0, v196, vcc
	v_cndmask_b32_e32 v197, 0, v197, vcc
	v_pk_fma_f32 v[202:203], v[138:139], v[176:177], v[150:151]
	v_pk_fma_f32 v[6:7], v[6:7], v[142:143], v[202:203]
	v_pk_fma_f32 v[6:7], v[146:147], v[196:197], v[6:7]
	ds_read_b64 v[176:177], v244 offset:768
	ds_read_b64 v[196:197], v243 offset:784
	ds_read_b64 v[200:201], v246 offset:24
	ds_write_b64 v243, v[26:27]
	ds_write_b64 v243, v[18:19] offset:256
	ds_write_b64 v243, v[10:11] offset:512
	ds_write_b64 v243, v[2:3] offset:768
	s_waitcnt lgkmcnt(11)
	v_cndmask_b32_e64 v170, v170, v198, s[6:7]
	v_cndmask_b32_e64 v171, v171, v199, s[6:7]
	v_add_u32_e32 v220, s48, v234
	v_cmp_lt_i32_e32 vcc, 0, v220
	s_nop 1
	v_cndmask_b32_e32 v170, 0, v170, vcc
	v_cndmask_b32_e32 v171, 0, v171, vcc
	v_cmp_gt_i32_e32 vcc, s28, v220
	s_nop 1
	v_cndmask_b32_e32 v178, 0, v178, vcc
	v_cndmask_b32_e32 v179, 0, v179, vcc
	v_pk_fma_f32 v[202:203], v[140:141], v[170:171], v[152:153]
	v_pk_fma_f32 v[32:33], v[32:33], v[144:145], v[202:203]
	v_pk_fma_f32 v[32:33], v[148:149], v[178:179], v[32:33]
	ds_read_b64 v[170:171], v244
	ds_read_b64 v[178:179], v243 offset:16
	ds_read_b64 v[198:199], v238 offset:3120
	s_waitcnt lgkmcnt(12)
	v_add_u32_e32 v220, s48, v235
	v_cmp_lt_i32_e32 vcc, 0, v220
	s_nop 1
	v_cndmask_b32_e32 v172, 0, v172, vcc
	v_cndmask_b32_e32 v173, 0, v173, vcc
	v_cmp_gt_i32_e32 vcc, s28, v220
	s_nop 1
	v_cndmask_b32_e32 v180, 0, v180, vcc
	v_cndmask_b32_e32 v181, 0, v181, vcc
	v_pk_fma_f32 v[202:203], v[140:141], v[172:173], v[152:153]
	v_pk_fma_f32 v[24:25], v[24:25], v[144:145], v[202:203]
	v_pk_fma_f32 v[24:25], v[148:149], v[180:181], v[24:25]
	ds_read_b64 v[172:173], v244 offset:256
	ds_read_b64 v[180:181], v243 offset:272
	s_waitcnt lgkmcnt(12)
	v_add_u32_e32 v220, s48, v236
	v_cmp_lt_i32_e32 vcc, 0, v220
	s_nop 1
	v_cndmask_b32_e32 v174, 0, v174, vcc
	v_cndmask_b32_e32 v175, 0, v175, vcc
	v_cmp_gt_i32_e32 vcc, s28, v220
	s_nop 1
	v_cndmask_b32_e32 v194, 0, v194, vcc
	v_cndmask_b32_e32 v195, 0, v195, vcc
	v_pk_fma_f32 v[202:203], v[140:141], v[174:175], v[152:153]
	v_pk_fma_f32 v[16:17], v[16:17], v[144:145], v[202:203]
	v_pk_fma_f32 v[16:17], v[148:149], v[194:195], v[16:17]
	ds_read_b64 v[174:175], v244 offset:512
	ds_read_b64 v[194:195], v243 offset:528
	s_waitcnt lgkmcnt(11)
	v_cndmask_b32_e64 v196, v196, v200, s[4:5]
	v_cndmask_b32_e64 v197, v197, v201, s[4:5]
	v_add_u32_e32 v220, s48, v237
	v_cmp_lt_i32_e32 vcc, 0, v220
	s_nop 1
	v_cndmask_b32_e32 v176, 0, v176, vcc
	v_cndmask_b32_e32 v177, 0, v177, vcc
	v_cmp_gt_i32_e32 vcc, s28, v220
	s_nop 1
	v_cndmask_b32_e32 v196, 0, v196, vcc
	v_cndmask_b32_e32 v197, 0, v197, vcc
	v_pk_fma_f32 v[202:203], v[140:141], v[176:177], v[152:153]
	v_pk_fma_f32 v[8:9], v[8:9], v[144:145], v[202:203]
	v_pk_fma_f32 v[8:9], v[148:149], v[196:197], v[8:9]
	ds_read_b64 v[176:177], v244 offset:768
	ds_read_b64 v[196:197], v243 offset:784
	ds_read_b64 v[200:201], v246 offset:48
	ds_write_b64 v243, v[28:29]
	ds_write_b64 v243, v[20:21] offset:256
	ds_write_b64 v243, v[12:13] offset:512
	ds_write_b64 v243, v[4:5] offset:768
	s_waitcnt lgkmcnt(11)
	v_cndmask_b32_e64 v170, v170, v198, s[6:7]
	v_cndmask_b32_e64 v171, v171, v199, s[6:7]
	v_add_u32_e32 v220, s48, v234
	v_cmp_lt_i32_e32 vcc, 0, v220
	s_nop 1
	v_cndmask_b32_e32 v170, 0, v170, vcc
	v_cndmask_b32_e32 v171, 0, v171, vcc
	v_cmp_gt_i32_e32 vcc, s28, v220
	s_nop 1
	v_cndmask_b32_e32 v178, 0, v178, vcc
	v_cndmask_b32_e32 v179, 0, v179, vcc
	v_pk_fma_f32 v[202:203], v[154:155], v[170:171], v[166:167]
	v_pk_fma_f32 v[26:27], v[26:27], v[158:159], v[202:203]
	v_pk_fma_f32 v[26:27], v[162:163], v[178:179], v[26:27]
	ds_read_b64 v[170:171], v244
	ds_read_b64 v[178:179], v243 offset:16
	ds_read_b64 v[198:199], v238 offset:3128
	s_waitcnt lgkmcnt(12)
	v_add_u32_e32 v220, s48, v235
	v_cmp_lt_i32_e32 vcc, 0, v220
	s_nop 1
	v_cndmask_b32_e32 v172, 0, v172, vcc
	v_cndmask_b32_e32 v173, 0, v173, vcc
	v_cmp_gt_i32_e32 vcc, s28, v220
	s_nop 1
	v_cndmask_b32_e32 v180, 0, v180, vcc
	v_cndmask_b32_e32 v181, 0, v181, vcc
	v_pk_fma_f32 v[202:203], v[154:155], v[172:173], v[166:167]
	v_pk_fma_f32 v[18:19], v[18:19], v[158:159], v[202:203]
	v_pk_fma_f32 v[18:19], v[162:163], v[180:181], v[18:19]
	ds_read_b64 v[172:173], v244 offset:256
	ds_read_b64 v[180:181], v243 offset:272
	s_waitcnt lgkmcnt(12)
	v_add_u32_e32 v220, s48, v236
	v_cmp_lt_i32_e32 vcc, 0, v220
	s_nop 1
	v_cndmask_b32_e32 v174, 0, v174, vcc
	v_cndmask_b32_e32 v175, 0, v175, vcc
	v_cmp_gt_i32_e32 vcc, s28, v220
	s_nop 1
	v_cndmask_b32_e32 v194, 0, v194, vcc
	v_cndmask_b32_e32 v195, 0, v195, vcc
	v_pk_fma_f32 v[202:203], v[154:155], v[174:175], v[166:167]
	v_pk_fma_f32 v[10:11], v[10:11], v[158:159], v[202:203]
	v_pk_fma_f32 v[10:11], v[162:163], v[194:195], v[10:11]
	ds_read_b64 v[174:175], v244 offset:512
	ds_read_b64 v[194:195], v243 offset:528
	s_waitcnt lgkmcnt(11)
; #define PG8_LAS __attribute__((address_space(3)))
; __device__ __forceinline__ unsigned cvt_pk_bf16(float lo, float hi) { unsigned r; asm volatile("v_cvt_pk_bf16_f32 %0, %1, %2" : "=v"(r) : "v"(lo), "v"(hi)); return r; }
; __device__ __forceinline__ float dpp_ror1(float v) { return __builtin_bit_cast(float, __builtin_amdgcn_update_dpp(0, __builtin_bit_cast(int, v), 0x121, 0xf, 0xf, false)); }
; __device__ __forceinline__ float dpp_ror15(float v) { return __builtin_bit_cast(float, __builtin_amdgcn_update_dpp(0, __builtin_bit_cast(int, v), 0x12F, 0xf, 0xf, false)); }
;     __device__ __forceinline__ void operator()(const f32x4 (&acc)[2][2][4][2], const Unit& u, int wr, int wc, int fr, int fq) const {
;     ...
;                     for (int bj = 0; bj < 2; ++bj) { const f32x4 cur = acc[ai][bj][m][n];
;                         f32x4 su = cur, sd = cur;
;                         if (m > 0) { if (fr == 15) su = acc[ai][bj][m > 0 ? m - 1 : 0][n]; }
;                         if (m < 3) { if (fr == 0) sd = acc[ai][bj][m < 3 ? m + 1 : 3][n]; }
;                         f32x4 up, dn;
;                         up[0] = dpp_ror1(su[0]); up[1] = dpp_ror1(su[1]); up[2] = dpp_ror1(su[2]); up[3] = dpp_ror1(su[3]);
;                         dn[0] = dpp_ror15(sd[0]); dn[1] = dpp_ror15(sd[1]); dn[2] = dpp_ror15(sd[2]); dn[3] = dpp_ror15(sd[3]);
;                         if (m == 0) { f32x4 halo = zero4; if (blk > 0) halo = *(const PG8_LAS f32x4*)(xb + (((((blk - 1) * 2 + 1) * 4 + wc) * 4 + fq) * 16 + (bj * 2 + n) * 4)); if (fr == 0) up = halo; }
;                         if (m == 3) { f32x4 halo = zero4; if (blk < 3) halo = *(const PG8_LAS f32x4*)(xb + (((((blk + 1) * 2 + 0) * 4 + wc) * 4 + fq) * 16 + (bj * 2 + n) * 4)); if (fr == 15) dn = halo; }
;                         if (edge) { if (!upok) up = zero4; if (!dnok) dn = zero4; }
;                         res[bj] = bb[bj] + w0[bj] * up + w1[bj] * cur + w2[bj] * dn; }
;                     if (store_ok) {
;                         float o[4];
; #pragma unroll
;                         for (int j = 0; j < 4; ++j) { const float gg = res[1][j]; o[j] = gg * __builtin_amdgcn_rcpf(1.f + __expf(-gg)) * res[0][j]; }
;                         u32x2 w; w.x = cvt_pk_bf16(o[0], o[1]); w.y = cvt_pk_bf16(o[2], o[3]);
;                         *(u32x2*)(ACT + (size_t)(seqrow + t) * 2816 + ch0 + 4 * n) = w; } } }
	v_cndmask_b32_e64 v196, v196, v200, s[4:5]
	v_cndmask_b32_e64 v197, v197, v201, s[4:5]
	v_add_u32_e32 v220, s48, v237
	v_cmp_lt_i32_e32 vcc, 0, v220
	s_nop 1
	v_cndmask_b32_e32 v176, 0, v176, vcc
	v_cndmask_b32_e32 v177, 0, v177, vcc
	v_cmp_gt_i32_e32 vcc, s28, v220
	s_nop 1
	v_cndmask_b32_e32 v196, 0, v196, vcc
	v_cndmask_b32_e32 v197, 0, v197, vcc
	v_pk_fma_f32 v[202:203], v[154:155], v[176:177], v[166:167]
	v_pk_fma_f32 v[2:3], v[2:3], v[158:159], v[202:203]
	v_pk_fma_f32 v[2:3], v[162:163], v[196:197], v[2:3]
	ds_read_b64 v[176:177], v244 offset:768
	ds_read_b64 v[196:197], v243 offset:784
	ds_read_b64 v[200:201], v246 offset:56
	s_waitcnt lgkmcnt(7)
	v_cndmask_b32_e64 v170, v170, v198, s[6:7]
	v_cndmask_b32_e64 v171, v171, v199, s[6:7]
	v_add_u32_e32 v220, s48, v234
	v_cmp_lt_i32_e32 vcc, 0, v220
	s_nop 1
	v_cndmask_b32_e32 v170, 0, v170, vcc
	v_cndmask_b32_e32 v171, 0, v171, vcc
	v_cmp_gt_i32_e32 vcc, s28, v220
	s_nop 1
	v_cndmask_b32_e32 v178, 0, v178, vcc
	v_cndmask_b32_e32 v179, 0, v179, vcc
	v_pk_fma_f32 v[202:203], v[156:157], v[170:171], v[168:169]
	v_pk_fma_f32 v[28:29], v[28:29], v[160:161], v[202:203]
	v_pk_fma_f32 v[28:29], v[164:165], v[178:179], v[28:29]
	s_waitcnt lgkmcnt(5)
	v_add_u32_e32 v220, s48, v235
	v_cmp_lt_i32_e32 vcc, 0, v220
	s_nop 1
	v_cndmask_b32_e32 v172, 0, v172, vcc
	v_cndmask_b32_e32 v173, 0, v173, vcc
	v_cmp_gt_i32_e32 vcc, s28, v220
	s_nop 1
	v_cndmask_b32_e32 v180, 0, v180, vcc
	v_cndmask_b32_e32 v181, 0, v181, vcc
	v_pk_fma_f32 v[202:203], v[156:157], v[172:173], v[168:169]
	v_pk_fma_f32 v[20:21], v[20:21], v[160:161], v[202:203]
	v_pk_fma_f32 v[20:21], v[164:165], v[180:181], v[20:21]
	s_waitcnt lgkmcnt(3)
	v_add_u32_e32 v220, s48, v236
	v_cmp_lt_i32_e32 vcc, 0, v220
	s_nop 1
	v_cndmask_b32_e32 v174, 0, v174, vcc
	v_cndmask_b32_e32 v175, 0, v175, vcc
	v_cmp_gt_i32_e32 vcc, s28, v220
	s_nop 1
	v_cndmask_b32_e32 v194, 0, v194, vcc
	v_cndmask_b32_e32 v195, 0, v195, vcc
	v_pk_fma_f32 v[202:203], v[156:157], v[174:175], v[168:169]
	v_pk_fma_f32 v[12:13], v[12:13], v[160:161], v[202:203]
	v_pk_fma_f32 v[12:13], v[164:165], v[194:195], v[12:13]
	s_waitcnt lgkmcnt(0)
	v_cndmask_b32_e64 v196, v196, v200, s[4:5]
	v_cndmask_b32_e64 v197, v197, v201, s[4:5]
	v_add_u32_e32 v220, s48, v237
	v_cmp_lt_i32_e32 vcc, 0, v220
	s_nop 1
	v_cndmask_b32_e32 v176, 0, v176, vcc
	v_cndmask_b32_e32 v177, 0, v177, vcc
	v_cmp_gt_i32_e32 vcc, s28, v220
	s_nop 1
	v_cndmask_b32_e32 v196, 0, v196, vcc
	v_cndmask_b32_e32 v197, 0, v197, vcc
	v_pk_fma_f32 v[202:203], v[156:157], v[176:177], v[168:169]
	v_pk_fma_f32 v[4:5], v[4:5], v[160:161], v[202:203]
	v_pk_fma_f32 v[4:5], v[164:165], v[196:197], v[4:5]
	v_mul_f32_e32 v208, 0xbfb8aa3b, v26
	v_mul_f32_e32 v209, 0xbfb8aa3b, v27
	v_mul_f32_e32 v210, 0xbfb8aa3b, v28
	v_mul_f32_e32 v211, 0xbfb8aa3b, v29
	v_exp_f32_e32 v208, v208
	v_exp_f32_e32 v209, v209
	v_exp_f32_e32 v210, v210
	v_exp_f32_e32 v211, v211
	v_add_f32_e32 v208, 1.0, v208
	v_add_f32_e32 v209, 1.0, v209
	v_add_f32_e32 v210, 1.0, v210
	v_add_f32_e32 v211, 1.0, v211
	v_rcp_f32_e32 v208, v208
	v_rcp_f32_e32 v209, v209
	v_rcp_f32_e32 v210, v210
	v_rcp_f32_e32 v211, v211
	v_mul_f32_e32 v26, v26, v208
	v_mul_f32_e32 v27, v27, v209
	v_mul_f32_e32 v28, v28, v210
	v_mul_f32_e32 v29, v29, v211
	v_mul_f32_e32 v26, v30, v26
	v_mul_f32_e32 v27, v31, v27
	v_mul_f32_e32 v28, v32, v28
	v_mul_f32_e32 v29, v33, v29
	v_cvt_pk_bf16_f32 v212, v26, v27
	v_cvt_pk_bf16_f32 v213, v28, v29
	v_mad_u32_u24 v221, v234, s29, v247
	s_and_saveexec_b64 s[30:31], s[20:21]
	global_store_dwordx2 v221, v[212:213], s[10:11] offset:8
	s_mov_b64 exec, s[30:31]
	v_mul_f32_e32 v208, 0xbfb8aa3b, v18
	v_mul_f32_e32 v209, 0xbfb8aa3b, v19
	v_mul_f32_e32 v210, 0xbfb8aa3b, v20
	v_mul_f32_e32 v211, 0xbfb8aa3b, v21
	v_exp_f32_e32 v208, v208
	v_exp_f32_e32 v209, v209
	v_exp_f32_e32 v210, v210
	v_exp_f32_e32 v211, v211
	v_add_f32_e32 v208, 1.0, v208
	v_add_f32_e32 v209, 1.0, v209
	v_add_f32_e32 v210, 1.0, v210
	v_add_f32_e32 v211, 1.0, v211
	v_rcp_f32_e32 v208, v208
	v_rcp_f32_e32 v209, v209
	v_rcp_f32_e32 v210, v210
	v_rcp_f32_e32 v211, v211
	v_mul_f32_e32 v18, v18, v208
	v_mul_f32_e32 v19, v19, v209
	v_mul_f32_e32 v20, v20, v210
	v_mul_f32_e32 v21, v21, v211
	v_mul_f32_e32 v18, v22, v18
	v_mul_f32_e32 v19, v23, v19
	v_mul_f32_e32 v20, v24, v20
	v_mul_f32_e32 v21, v25, v21
	v_cvt_pk_bf16_f32 v218, v18, v19
	v_cvt_pk_bf16_f32 v219, v20, v21
	v_mad_u32_u24 v40, v235, s29, v247
	s_and_saveexec_b64 s[30:31], s[22:23]
	global_store_dwordx2 v40, v[218:219], s[10:11] offset:8
	s_mov_b64 exec, s[30:31]
	v_mul_f32_e32 v208, 0xbfb8aa3b, v10
	v_mul_f32_e32 v209, 0xbfb8aa3b, v11
	v_mul_f32_e32 v210, 0xbfb8aa3b, v12
	v_mul_f32_e32 v211, 0xbfb8aa3b, v13
	v_exp_f32_e32 v208, v208
	v_exp_f32_e32 v209, v209
	v_exp_f32_e32 v210, v210
	v_exp_f32_e32 v211, v211
	v_add_f32_e32 v208, 1.0, v208
	v_add_f32_e32 v209, 1.0, v209
	v_add_f32_e32 v210, 1.0, v210
	v_add_f32_e32 v211, 1.0, v211
	v_rcp_f32_e32 v208, v208
	v_rcp_f32_e32 v209, v209
	v_rcp_f32_e32 v210, v210
	v_rcp_f32_e32 v211, v211
	v_mul_f32_e32 v10, v10, v208
	v_mul_f32_e32 v11, v11, v209
	v_mul_f32_e32 v12, v12, v210
	v_mul_f32_e32 v13, v13, v211
	v_mul_f32_e32 v10, v14, v10
	v_mul_f32_e32 v11, v15, v11
	v_mul_f32_e32 v12, v16, v12
	v_mul_f32_e32 v13, v17, v13
	v_cvt_pk_bf16_f32 v212, v10, v11
	v_cvt_pk_bf16_f32 v213, v12, v13
	v_mad_u32_u24 v221, v236, s29, v247
	s_and_saveexec_b64 s[30:31], s[24:25]
	global_store_dwordx2 v221, v[212:213], s[10:11] offset:8
	s_mov_b64 exec, s[30:31]
	v_mul_f32_e32 v208, 0xbfb8aa3b, v2
	v_mul_f32_e32 v209, 0xbfb8aa3b, v3
	v_mul_f32_e32 v210, 0xbfb8aa3b, v4
	v_mul_f32_e32 v211, 0xbfb8aa3b, v5
	v_exp_f32_e32 v208, v208
	v_exp_f32_e32 v209, v209
	v_exp_f32_e32 v210, v210
	v_exp_f32_e32 v211, v211
	v_add_f32_e32 v208, 1.0, v208
	v_add_f32_e32 v209, 1.0, v209
	v_add_f32_e32 v210, 1.0, v210
	v_add_f32_e32 v211, 1.0, v211
	v_rcp_f32_e32 v208, v208
	v_rcp_f32_e32 v209, v209
	v_rcp_f32_e32 v210, v210
	v_rcp_f32_e32 v211, v211
	v_mul_f32_e32 v2, v2, v208
	v_mul_f32_e32 v3, v3, v209
	v_mul_f32_e32 v4, v4, v210
	v_mul_f32_e32 v5, v5, v211
	v_mul_f32_e32 v2, v6, v2
	v_mul_f32_e32 v3, v7, v3
	v_mul_f32_e32 v4, v8, v4
	v_mul_f32_e32 v5, v9, v5
	v_cvt_pk_bf16_f32 v218, v2, v3
	v_cvt_pk_bf16_f32 v219, v4, v5
	v_mad_u32_u24 v40, v237, s29, v247
	s_and_saveexec_b64 s[30:31], s[26:27]
	global_store_dwordx2 v40, v[218:219], s[10:11] offset:8
	s_mov_b64 exec, s[30:31]
